# c1 with an 8-cycle safety pad (s_nop 1) before the early post-MMA barrier
# baseline (speedup 1.0000x reference)
; #define PG8_STAGE(bufoff, gbase, voff) do { _Pragma("unroll") for (int _i = 0; _i < 2; ++_i) \
;         __builtin_amdgcn_global_load_lds((const unsigned*)((const char*)(gbase) + (voff)[_i]), (LAS unsigned*)(lds + (bufoff) + ldsw + _i * 8192), 16, 0, 0); } while (0)
; #define PG8_LDA(dst, b, h) do { _Pragma("unroll") for (int m = 0; m < 4; ++m) _Pragma("unroll") for (int k = 0; k < 2; ++k) dst[m][k] = *(const LAS bf16x8*)(lds + PG8_SA(b, h) + aoff + m * 2048 + k * 1024); } while (0)
; #define PG8_LDB(dst, b, h) do { _Pragma("unroll") for (int n = 0; n < 2; ++n) _Pragma("unroll") for (int k = 0; k < 2; ++k) dst[n][k] = *(const LAS bf16x8*)(lds + PG8_SB(b, h) + boff + n * 2048 + k * 1024); } while (0)
; #define PG8_MMA(ai, bj, At, Bt) do { __builtin_amdgcn_s_setprio(1); _Pragma("unroll") for (int m = 0; m < 4; ++m) _Pragma("unroll") for (int n = 0; n < 2; ++n) _Pragma("unroll") for (int k = 0; k < 2; ++k) \
;         acc[ai][bj][m][n] = __builtin_amdgcn_mfma_f32_16x16x32_bf16(Bt[n][k], At[m][k], acc[ai][bj][m][n], 0, 0, 0); __builtin_amdgcn_s_setprio(0); } while (0)
; #define PG8_WAIT_V(n) asm volatile("s_waitcnt vmcnt(" #n ")" ::: "memory")
; #define PG8_WAIT_L(n) asm volatile("s_waitcnt lgkmcnt(" #n ")" ::: "memory")
; #define PG8_BAR __builtin_amdgcn_s_barrier()
; #define PG8_SCHED __builtin_amdgcn_sched_barrier(0)
; template <class Epi, bool ALIGN_EPI = true, bool SP2 = true>
; __device__ __forceinline__ void gemm_phase(LAS unsigned char* lds, const Gemm g, const StaticOrder& S, const Epi& E, unsigned long long& tacc, const int tmode) {
;     ...
;             const bool last = (t == nt - 2);
;             const char* a1 = cA + (size_t)(t + 1) * kstepA;
;             const char* a2 = last ? nA : cA + (size_t)(t + 2) * kstepA; const char* b2 = last ? nB : cB + (size_t)(t + 2) * kstepB;
;             const char* a3 = a2 + kstepA; const char* b3 = b2 + kstepB;
;             if constexpr (SP2) {
;             PG8_LDB(B0, 0, 0); PG8_LDB(B1, 0, 1); PG8_SCHED; PG8_LDA(At, 0, 0); PG8_STAGE(PG8_SA(1, 1), a1 + hstepA, voffA);
;             PG8_WAIT_V(8); PG8_WAIT_L(0); PG8_BAR; PG8_MMA(0, 0, At, B0); PG8_MMA(0, 1, At, B1); PG8_BAR; PG8_SCHED;
;             PG8_LDA(At, 0, 1); PG8_STAGE(PG8_SB(0, 0), b2, voffB); PG8_STAGE(PG8_SB(0, 1), b2 + hstepB, voffB); PG8_STAGE(PG8_SA(0, 0), a2, voffA);
.LBB0_133:
	s_add_u32 s0, s22, 0xfff84000
	s_addc_u32 s1, s23, -1
	s_cmp_eq_u32 s56, 28
	s_cselect_b32 s34, s50, s0
	s_cselect_b32 s35, s25, s1
	s_cselect_b32 s38, s51, s54
	s_cselect_b32 s39, s21, s55
	s_add_u32 s30, s34, 0x4000
	s_addc_u32 s31, s35, 0
	s_add_i32 s0, 0, 0x10000
	v_add_u32_e32 v141, s0, v139
	s_add_i32 s33, 0, 0x14000
	ds_read_b128 v[134:137], v141
	ds_read_b128 v[142:145], v141 offset:1024
	ds_read_b128 v[146:149], v141 offset:2048
	ds_read_b128 v[150:153], v141 offset:3072
	v_add_u32_e32 v141, s33, v139
	ds_read_b128 v[154:157], v141
	ds_read_b128 v[158:161], v141 offset:1024
	ds_read_b128 v[162:165], v141 offset:2048
	ds_read_b128 v[166:169], v141 offset:3072
	v_lshl_add_u64 v[190:191], s[22:23], 0, v[130:131]
	s_add_i32 m0, s10, 0xc000
	ds_read_b128 v[170:173], v140
	ds_read_b128 v[174:177], v140 offset:1024
	ds_read_b128 v[178:181], v140 offset:2048
	ds_read_b128 v[182:185], v140 offset:3072
	ds_read_b128 v[186:189], v140 offset:4096
	ds_read_b128 v[194:197], v140 offset:5120
	ds_read_b128 v[206:209], v140 offset:6144
	ds_read_b128 v[210:213], v140 offset:7168
	global_load_lds_dwordx4 v[190:191], off
	v_lshl_add_u64 v[190:191], s[22:23], 0, v[132:133]
	s_add_i32 m0, s10, 0xe000
	s_nop 0
	global_load_lds_dwordx4 v[190:191], off
	s_waitcnt vmcnt(8)
	s_waitcnt lgkmcnt(0)
	s_barrier
	s_setprio 1
	s_waitcnt lgkmcnt(0)
	v_mfma_f32_16x16x32_bf16 v[126:129], v[134:137], v[170:173], v[126:129]
	v_mfma_f32_16x16x32_bf16 v[122:125], v[146:149], v[170:173], v[122:125]
	v_mfma_f32_16x16x32_bf16 v[110:113], v[134:137], v[178:181], v[110:113]
	v_mfma_f32_16x16x32_bf16 v[106:109], v[146:149], v[178:181], v[106:109]
	v_mfma_f32_16x16x32_bf16 v[94:97], v[134:137], v[186:189], v[94:97]
	v_mfma_f32_16x16x32_bf16 v[90:93], v[146:149], v[186:189], v[90:93]
	v_mfma_f32_16x16x32_bf16 v[78:81], v[134:137], v[206:209], v[78:81]
	v_mfma_f32_16x16x32_bf16 v[74:77], v[146:149], v[206:209], v[74:77]
	v_mfma_f32_16x16x32_bf16 v[126:129], v[142:145], v[174:177], v[126:129]
	v_mfma_f32_16x16x32_bf16 v[122:125], v[150:153], v[174:177], v[122:125]
	v_mfma_f32_16x16x32_bf16 v[110:113], v[142:145], v[182:185], v[110:113]
	v_mfma_f32_16x16x32_bf16 v[106:109], v[150:153], v[182:185], v[106:109]
	v_mfma_f32_16x16x32_bf16 v[94:97], v[142:145], v[194:197], v[94:97]
	v_mfma_f32_16x16x32_bf16 v[90:93], v[150:153], v[194:197], v[90:93]
	v_mfma_f32_16x16x32_bf16 v[78:81], v[142:145], v[210:213], v[78:81]
	v_mfma_f32_16x16x32_bf16 v[74:77], v[150:153], v[210:213], v[74:77]
	s_setprio 0
	s_setprio 1
	v_mfma_f32_16x16x32_bf16 v[118:121], v[154:157], v[170:173], v[118:121]
	v_mfma_f32_16x16x32_bf16 v[114:117], v[162:165], v[170:173], v[114:117]
	v_mfma_f32_16x16x32_bf16 v[102:105], v[154:157], v[178:181], v[102:105]
	v_mfma_f32_16x16x32_bf16 v[98:101], v[162:165], v[178:181], v[98:101]
	v_mfma_f32_16x16x32_bf16 v[86:89], v[154:157], v[186:189], v[86:89]
	v_mfma_f32_16x16x32_bf16 v[82:85], v[162:165], v[186:189], v[82:85]
	v_mfma_f32_16x16x32_bf16 v[70:73], v[154:157], v[206:209], v[70:73]
	v_mfma_f32_16x16x32_bf16 v[66:69], v[162:165], v[206:209], v[66:69]
	v_mfma_f32_16x16x32_bf16 v[118:121], v[158:161], v[174:177], v[118:121]
	v_mfma_f32_16x16x32_bf16 v[114:117], v[166:169], v[174:177], v[114:117]
	v_mfma_f32_16x16x32_bf16 v[102:105], v[158:161], v[182:185], v[102:105]
	v_mfma_f32_16x16x32_bf16 v[98:101], v[166:169], v[182:185], v[98:101]
	v_mfma_f32_16x16x32_bf16 v[86:89], v[158:161], v[194:197], v[86:89]
	v_mfma_f32_16x16x32_bf16 v[82:85], v[166:169], v[194:197], v[82:85]
	v_mfma_f32_16x16x32_bf16 v[70:73], v[158:161], v[210:213], v[70:73]
	s_nop 1
	s_barrier
	v_mfma_f32_16x16x32_bf16 v[66:69], v[166:169], v[210:213], v[66:69]
	s_setprio 0
	s_add_i32 s0, s0, s2
	v_lshl_add_u64 v[190:191], s[38:39], 0, v[130:131]
	s_mov_b32 m0, s0
	ds_read_b128 v[170:173], v140 offset:16384
	ds_read_b128 v[174:177], v140 offset:17408
	ds_read_b128 v[178:181], v140 offset:18432
	ds_read_b128 v[182:185], v140 offset:19456
	ds_read_b128 v[186:189], v140 offset:20480
	ds_read_b128 v[194:197], v140 offset:21504
	ds_read_b128 v[206:209], v140 offset:22528
	ds_read_b128 v[210:213], v140 offset:23552
	global_load_lds_dwordx4 v[190:191], off
	s_add_i32 m0, s0, 0x2000
	s_add_u32 s0, s38, 0x80000
	v_lshl_add_u64 v[190:191], s[38:39], 0, v[132:133]
	s_addc_u32 s1, s39, 0
	s_add_i32 s33, s33, s2
	global_load_lds_dwordx4 v[190:191], off
	v_lshl_add_u64 v[190:191], s[0:1], 0, v[130:131]
	s_mov_b32 m0, s33
	s_nop 0
	global_load_lds_dwordx4 v[190:191], off
	v_lshl_add_u64 v[190:191], s[0:1], 0, v[132:133]
	s_add_i32 m0, s33, 0x2000
	s_nop 0
	global_load_lds_dwordx4 v[190:191], off
	v_lshl_add_u64 v[190:191], s[34:35], 0, v[130:131]
	s_mov_b32 m0, s10
	s_nop 0
	global_load_lds_dwordx4 v[190:191], off
	v_lshl_add_u64 v[190:191], s[34:35], 0, v[132:133]
	s_mov_b32 m0, s40
	s_nop 0
	global_load_lds_dwordx4 v[190:191], off
	s_waitcnt vmcnt(8)
	s_waitcnt lgkmcnt(0)
	s_barrier
; #define PG8_STAGE(bufoff, gbase, voff) do { _Pragma("unroll") for (int _i = 0; _i < 2; ++_i) \
;         __builtin_amdgcn_global_load_lds((const unsigned*)((const char*)(gbase) + (voff)[_i]), (LAS unsigned*)(lds + (bufoff) + ldsw + _i * 8192), 16, 0, 0); } while (0)
; #define PG8_LDA(dst, b, h) do { _Pragma("unroll") for (int m = 0; m < 4; ++m) _Pragma("unroll") for (int k = 0; k < 2; ++k) dst[m][k] = *(const LAS bf16x8*)(lds + PG8_SA(b, h) + aoff + m * 2048 + k * 1024); } while (0)
; #define PG8_LDB(dst, b, h) do { _Pragma("unroll") for (int n = 0; n < 2; ++n) _Pragma("unroll") for (int k = 0; k < 2; ++k) dst[n][k] = *(const LAS bf16x8*)(lds + PG8_SB(b, h) + boff + n * 2048 + k * 1024); } while (0)
; #define PG8_MMA(ai, bj, At, Bt) do { __builtin_amdgcn_s_setprio(1); _Pragma("unroll") for (int m = 0; m < 4; ++m) _Pragma("unroll") for (int n = 0; n < 2; ++n) _Pragma("unroll") for (int k = 0; k < 2; ++k) \
;         acc[ai][bj][m][n] = __builtin_amdgcn_mfma_f32_16x16x32_bf16(Bt[n][k], At[m][k], acc[ai][bj][m][n], 0, 0, 0); __builtin_amdgcn_s_setprio(0); } while (0)
; #define PG8_WAIT_V(n) asm volatile("s_waitcnt vmcnt(" #n ")" ::: "memory")
; #define PG8_WAIT_L(n) asm volatile("s_waitcnt lgkmcnt(" #n ")" ::: "memory")
; #define PG8_BAR __builtin_amdgcn_s_barrier()
; #define PG8_SCHED __builtin_amdgcn_sched_barrier(0)
; template <class Epi, bool ALIGN_EPI = true, bool SP2 = true>
; __device__ __forceinline__ void gemm_phase(LAS unsigned char* lds, const Gemm g, const StaticOrder& S, const Epi& E, unsigned long long& tacc, const int tmode) {
;     ...
;             PG8_WAIT_V(8); PG8_WAIT_L(0); PG8_BAR; PG8_MMA(1, 0, At, B0); PG8_MMA(1, 1, At, B1); PG8_BAR; PG8_SCHED;
;             PG8_LDB(B0, 1, 0); PG8_LDB(B1, 1, 1); PG8_SCHED; PG8_LDA(At, 1, 0); PG8_STAGE(PG8_SA(0, 1), a2 + hstepA, voffA);
;             PG8_WAIT_V(8); PG8_WAIT_L(0); PG8_BAR; PG8_MMA(0, 0, At, B0); PG8_MMA(0, 1, At, B1); PG8_BAR; PG8_SCHED;
	s_setprio 1
	s_waitcnt lgkmcnt(0)
	v_mfma_f32_16x16x32_bf16 v[62:65], v[134:137], v[170:173], v[62:65]
	v_mfma_f32_16x16x32_bf16 v[58:61], v[146:149], v[170:173], v[58:61]
	v_mfma_f32_16x16x32_bf16 v[46:49], v[134:137], v[178:181], v[46:49]
	v_mfma_f32_16x16x32_bf16 v[42:45], v[146:149], v[178:181], v[42:45]
	v_mfma_f32_16x16x32_bf16 v[30:33], v[134:137], v[186:189], v[30:33]
	v_mfma_f32_16x16x32_bf16 v[26:29], v[146:149], v[186:189], v[26:29]
	v_mfma_f32_16x16x32_bf16 v[14:17], v[134:137], v[206:209], v[14:17]
	v_mfma_f32_16x16x32_bf16 v[10:13], v[146:149], v[206:209], v[10:13]
	v_mfma_f32_16x16x32_bf16 v[62:65], v[142:145], v[174:177], v[62:65]
	v_mfma_f32_16x16x32_bf16 v[58:61], v[150:153], v[174:177], v[58:61]
	v_mfma_f32_16x16x32_bf16 v[46:49], v[142:145], v[182:185], v[46:49]
	v_mfma_f32_16x16x32_bf16 v[42:45], v[150:153], v[182:185], v[42:45]
	v_mfma_f32_16x16x32_bf16 v[30:33], v[142:145], v[194:197], v[30:33]
	v_mfma_f32_16x16x32_bf16 v[26:29], v[150:153], v[194:197], v[26:29]
	v_mfma_f32_16x16x32_bf16 v[14:17], v[142:145], v[210:213], v[14:17]
	v_mfma_f32_16x16x32_bf16 v[10:13], v[150:153], v[210:213], v[10:13]
	s_setprio 0
	s_setprio 1
	v_mfma_f32_16x16x32_bf16 v[54:57], v[154:157], v[170:173], v[54:57]
	v_mfma_f32_16x16x32_bf16 v[50:53], v[162:165], v[170:173], v[50:53]
	v_mfma_f32_16x16x32_bf16 v[38:41], v[154:157], v[178:181], v[38:41]
	v_mfma_f32_16x16x32_bf16 v[34:37], v[162:165], v[178:181], v[34:37]
	v_mfma_f32_16x16x32_bf16 v[22:25], v[154:157], v[186:189], v[22:25]
	v_mfma_f32_16x16x32_bf16 v[18:21], v[162:165], v[186:189], v[18:21]
	v_mfma_f32_16x16x32_bf16 v[6:9], v[154:157], v[206:209], v[6:9]
	v_mfma_f32_16x16x32_bf16 v[2:5], v[162:165], v[206:209], v[2:5]
	v_mfma_f32_16x16x32_bf16 v[54:57], v[158:161], v[174:177], v[54:57]
	v_mfma_f32_16x16x32_bf16 v[50:53], v[166:169], v[174:177], v[50:53]
	v_mfma_f32_16x16x32_bf16 v[38:41], v[158:161], v[182:185], v[38:41]
	v_mfma_f32_16x16x32_bf16 v[34:37], v[166:169], v[182:185], v[34:37]
	v_mfma_f32_16x16x32_bf16 v[22:25], v[158:161], v[194:197], v[22:25]
	v_mfma_f32_16x16x32_bf16 v[18:21], v[166:169], v[194:197], v[18:21]
	v_mfma_f32_16x16x32_bf16 v[6:9], v[158:161], v[210:213], v[6:9]
	s_nop 1
	s_barrier
	v_mfma_f32_16x16x32_bf16 v[2:5], v[166:169], v[210:213], v[2:5]
	s_setprio 0
	s_add_i32 s33, 0, 0x18000
	v_add_u32_e32 v141, s33, v139
	s_add_i32 s57, 0, 0x1c000
	ds_read_b128 v[134:137], v141
	ds_read_b128 v[142:145], v141 offset:1024
	ds_read_b128 v[146:149], v141 offset:2048
	ds_read_b128 v[150:153], v141 offset:3072
	v_add_u32_e32 v141, s57, v139
	ds_read_b128 v[154:157], v141
	ds_read_b128 v[158:161], v141 offset:1024
	ds_read_b128 v[162:165], v141 offset:2048
	ds_read_b128 v[166:169], v141 offset:3072
	s_add_u32 s0, s34, 0x80000
	s_addc_u32 s1, s35, 0
	s_mov_b32 m0, s41
	v_lshl_add_u64 v[190:191], s[0:1], 0, v[130:131]
	ds_read_b128 v[170:173], v140 offset:32768
	ds_read_b128 v[174:177], v140 offset:33792
	ds_read_b128 v[178:181], v140 offset:34816
	ds_read_b128 v[182:185], v140 offset:35840
	ds_read_b128 v[186:189], v140 offset:36864
	ds_read_b128 v[194:197], v140 offset:37888
	ds_read_b128 v[206:209], v140 offset:38912
	ds_read_b128 v[210:213], v140 offset:39936
	global_load_lds_dwordx4 v[190:191], off
	v_lshl_add_u64 v[190:191], s[0:1], 0, v[132:133]
	s_mov_b32 m0, s42
	s_nop 0
	global_load_lds_dwordx4 v[190:191], off
	s_waitcnt vmcnt(8)
	s_waitcnt lgkmcnt(0)
	s_barrier
	s_setprio 1
	s_waitcnt lgkmcnt(0)
	v_mfma_f32_16x16x32_bf16 v[126:129], v[134:137], v[170:173], v[126:129]
	v_mfma_f32_16x16x32_bf16 v[122:125], v[146:149], v[170:173], v[122:125]
	v_mfma_f32_16x16x32_bf16 v[110:113], v[134:137], v[178:181], v[110:113]
	v_mfma_f32_16x16x32_bf16 v[106:109], v[146:149], v[178:181], v[106:109]
	v_mfma_f32_16x16x32_bf16 v[94:97], v[134:137], v[186:189], v[94:97]
	v_mfma_f32_16x16x32_bf16 v[90:93], v[146:149], v[186:189], v[90:93]
	v_mfma_f32_16x16x32_bf16 v[78:81], v[134:137], v[206:209], v[78:81]
	v_mfma_f32_16x16x32_bf16 v[74:77], v[146:149], v[206:209], v[74:77]
	v_mfma_f32_16x16x32_bf16 v[126:129], v[142:145], v[174:177], v[126:129]
	v_mfma_f32_16x16x32_bf16 v[122:125], v[150:153], v[174:177], v[122:125]
	v_mfma_f32_16x16x32_bf16 v[110:113], v[142:145], v[182:185], v[110:113]
	v_mfma_f32_16x16x32_bf16 v[106:109], v[150:153], v[182:185], v[106:109]
	v_mfma_f32_16x16x32_bf16 v[94:97], v[142:145], v[194:197], v[94:97]
	v_mfma_f32_16x16x32_bf16 v[90:93], v[150:153], v[194:197], v[90:93]
	v_mfma_f32_16x16x32_bf16 v[78:81], v[142:145], v[210:213], v[78:81]
	v_mfma_f32_16x16x32_bf16 v[74:77], v[150:153], v[210:213], v[74:77]
	s_setprio 0
	s_setprio 1
	v_mfma_f32_16x16x32_bf16 v[118:121], v[154:157], v[170:173], v[118:121]
	v_mfma_f32_16x16x32_bf16 v[114:117], v[162:165], v[170:173], v[114:117]
	v_mfma_f32_16x16x32_bf16 v[102:105], v[154:157], v[178:181], v[102:105]
	v_mfma_f32_16x16x32_bf16 v[98:101], v[162:165], v[178:181], v[98:101]
	v_mfma_f32_16x16x32_bf16 v[86:89], v[154:157], v[186:189], v[86:89]
	v_mfma_f32_16x16x32_bf16 v[82:85], v[162:165], v[186:189], v[82:85]
	v_mfma_f32_16x16x32_bf16 v[70:73], v[154:157], v[206:209], v[70:73]
	v_mfma_f32_16x16x32_bf16 v[66:69], v[162:165], v[206:209], v[66:69]
	v_mfma_f32_16x16x32_bf16 v[118:121], v[158:161], v[174:177], v[118:121]
	v_mfma_f32_16x16x32_bf16 v[114:117], v[166:169], v[174:177], v[114:117]
	v_mfma_f32_16x16x32_bf16 v[102:105], v[158:161], v[182:185], v[102:105]
	v_mfma_f32_16x16x32_bf16 v[98:101], v[166:169], v[182:185], v[98:101]
	v_mfma_f32_16x16x32_bf16 v[86:89], v[158:161], v[194:197], v[86:89]
	v_mfma_f32_16x16x32_bf16 v[82:85], v[166:169], v[194:197], v[82:85]
	v_mfma_f32_16x16x32_bf16 v[70:73], v[158:161], v[210:213], v[70:73]
	s_nop 1
	s_barrier
; #define PG8_STAGE(bufoff, gbase, voff) do { _Pragma("unroll") for (int _i = 0; _i < 2; ++_i) \
;         __builtin_amdgcn_global_load_lds((const unsigned*)((const char*)(gbase) + (voff)[_i]), (LAS unsigned*)(lds + (bufoff) + ldsw + _i * 8192), 16, 0, 0); } while (0)
; #define PG8_LDA(dst, b, h) do { _Pragma("unroll") for (int m = 0; m < 4; ++m) _Pragma("unroll") for (int k = 0; k < 2; ++k) dst[m][k] = *(const LAS bf16x8*)(lds + PG8_SA(b, h) + aoff + m * 2048 + k * 1024); } while (0)
; #define PG8_MMA(ai, bj, At, Bt) do { __builtin_amdgcn_s_setprio(1); _Pragma("unroll") for (int m = 0; m < 4; ++m) _Pragma("unroll") for (int n = 0; n < 2; ++n) _Pragma("unroll") for (int k = 0; k < 2; ++k) \
;         acc[ai][bj][m][n] = __builtin_amdgcn_mfma_f32_16x16x32_bf16(Bt[n][k], At[m][k], acc[ai][bj][m][n], 0, 0, 0); __builtin_amdgcn_s_setprio(0); } while (0)
; #define PG8_WAIT_V(n) asm volatile("s_waitcnt vmcnt(" #n ")" ::: "memory")
; #define PG8_WAIT_L(n) asm volatile("s_waitcnt lgkmcnt(" #n ")" ::: "memory")
; #define PG8_BAR __builtin_amdgcn_s_barrier()
; #define PG8_SCHED __builtin_amdgcn_sched_barrier(0)
; template <class Epi, bool ALIGN_EPI = true, bool SP2 = true>
; __device__ __forceinline__ void gemm_phase(LAS unsigned char* lds, const Gemm g, const StaticOrder& S, const Epi& E, unsigned long long& tacc, const int tmode) {
;     ...
;             PG8_WAIT_V(8); PG8_WAIT_L(0); PG8_BAR; PG8_MMA(0, 0, At, B0); PG8_MMA(0, 1, At, B1); PG8_BAR; PG8_SCHED;
;             PG8_LDA(At, 1, 1); PG8_STAGE(PG8_SB(1, 0), b3, voffB); PG8_STAGE(PG8_SB(1, 1), b3 + hstepB, voffB); PG8_STAGE(PG8_SA(1, 0), a3, voffA);
;             PG8_WAIT_V(8); PG8_WAIT_L(0); PG8_BAR; PG8_MMA(1, 0, At, B0); PG8_MMA(1, 1, At, B1); PG8_BAR; PG8_SCHED;
	v_mfma_f32_16x16x32_bf16 v[66:69], v[166:169], v[210:213], v[66:69]
	s_setprio 0
	s_add_u32 s0, s38, 0x4000
	s_addc_u32 s1, s39, 0
	s_add_i32 s33, s33, s2
	v_lshl_add_u64 v[190:191], s[0:1], 0, v[130:131]
	s_mov_b32 m0, s33
	ds_read_b128 v[170:173], v140 offset:49152
	ds_read_b128 v[174:177], v140 offset:50176
	ds_read_b128 v[178:181], v140 offset:51200
	ds_read_b128 v[182:185], v140 offset:52224
	ds_read_b128 v[186:189], v140 offset:53248
	ds_read_b128 v[194:197], v140 offset:54272
	ds_read_b128 v[206:209], v140 offset:55296
	ds_read_b128 v[210:213], v140 offset:56320
	global_load_lds_dwordx4 v[190:191], off
	s_add_i32 m0, s33, 0x2000
	v_lshl_add_u64 v[190:191], s[0:1], 0, v[132:133]
	s_add_u32 s0, s38, 0x84000
	s_addc_u32 s1, s39, 0
	s_add_i32 s33, s57, s2
	global_load_lds_dwordx4 v[190:191], off
	v_lshl_add_u64 v[190:191], s[0:1], 0, v[130:131]
	s_mov_b32 m0, s33
	s_nop 0
	global_load_lds_dwordx4 v[190:191], off
	v_lshl_add_u64 v[190:191], s[0:1], 0, v[132:133]
	s_add_i32 m0, s33, 0x2000
	s_nop 0
	global_load_lds_dwordx4 v[190:191], off
	v_lshl_add_u64 v[190:191], s[30:31], 0, v[130:131]
	s_mov_b32 m0, s45
	s_nop 0
	global_load_lds_dwordx4 v[190:191], off
	v_lshl_add_u64 v[190:191], s[30:31], 0, v[132:133]
	s_mov_b32 m0, s46
	s_nop 0
	global_load_lds_dwordx4 v[190:191], off
	s_waitcnt vmcnt(8)
	s_waitcnt lgkmcnt(0)
	s_barrier
	s_setprio 1
	s_waitcnt lgkmcnt(0)
	v_mfma_f32_16x16x32_bf16 v[62:65], v[134:137], v[170:173], v[62:65]
	v_mfma_f32_16x16x32_bf16 v[58:61], v[146:149], v[170:173], v[58:61]
	v_mfma_f32_16x16x32_bf16 v[46:49], v[134:137], v[178:181], v[46:49]
	v_mfma_f32_16x16x32_bf16 v[42:45], v[146:149], v[178:181], v[42:45]
	v_mfma_f32_16x16x32_bf16 v[30:33], v[134:137], v[186:189], v[30:33]
	v_mfma_f32_16x16x32_bf16 v[26:29], v[146:149], v[186:189], v[26:29]
	v_mfma_f32_16x16x32_bf16 v[14:17], v[134:137], v[206:209], v[14:17]
	v_mfma_f32_16x16x32_bf16 v[10:13], v[146:149], v[206:209], v[10:13]
	v_mfma_f32_16x16x32_bf16 v[62:65], v[142:145], v[174:177], v[62:65]
	v_mfma_f32_16x16x32_bf16 v[58:61], v[150:153], v[174:177], v[58:61]
	v_mfma_f32_16x16x32_bf16 v[46:49], v[142:145], v[182:185], v[46:49]
	v_mfma_f32_16x16x32_bf16 v[42:45], v[150:153], v[182:185], v[42:45]
	v_mfma_f32_16x16x32_bf16 v[30:33], v[142:145], v[194:197], v[30:33]
	v_mfma_f32_16x16x32_bf16 v[26:29], v[150:153], v[194:197], v[26:29]
	v_mfma_f32_16x16x32_bf16 v[14:17], v[142:145], v[210:213], v[14:17]
	v_mfma_f32_16x16x32_bf16 v[10:13], v[150:153], v[210:213], v[10:13]
	s_setprio 0
	s_setprio 1
	v_mfma_f32_16x16x32_bf16 v[54:57], v[154:157], v[170:173], v[54:57]
	v_mfma_f32_16x16x32_bf16 v[50:53], v[162:165], v[170:173], v[50:53]
	v_mfma_f32_16x16x32_bf16 v[38:41], v[154:157], v[178:181], v[38:41]
	v_mfma_f32_16x16x32_bf16 v[34:37], v[162:165], v[178:181], v[34:37]
	v_mfma_f32_16x16x32_bf16 v[22:25], v[154:157], v[186:189], v[22:25]
	v_mfma_f32_16x16x32_bf16 v[18:21], v[162:165], v[186:189], v[18:21]
	v_mfma_f32_16x16x32_bf16 v[6:9], v[154:157], v[206:209], v[6:9]
	v_mfma_f32_16x16x32_bf16 v[2:5], v[162:165], v[206:209], v[2:5]
	v_mfma_f32_16x16x32_bf16 v[54:57], v[158:161], v[174:177], v[54:57]
	v_mfma_f32_16x16x32_bf16 v[50:53], v[166:169], v[174:177], v[50:53]
	v_mfma_f32_16x16x32_bf16 v[38:41], v[158:161], v[182:185], v[38:41]
	v_mfma_f32_16x16x32_bf16 v[34:37], v[166:169], v[182:185], v[34:37]
	v_mfma_f32_16x16x32_bf16 v[22:25], v[158:161], v[194:197], v[22:25]
	v_mfma_f32_16x16x32_bf16 v[18:21], v[166:169], v[194:197], v[18:21]
	v_mfma_f32_16x16x32_bf16 v[6:9], v[158:161], v[210:213], v[6:9]
	s_nop 1
	s_barrier
	v_mfma_f32_16x16x32_bf16 v[2:5], v[166:169], v[210:213], v[2:5]
	s_setprio 0
	s_add_i32 s56, s56, 2
	s_add_u32 s22, s22, 0x8000
	s_addc_u32 s23, s23, 0
	s_add_u32 s54, s54, 0x8000
	s_addc_u32 s55, s55, 0
	s_cmp_lt_u32 s56, 30
	s_cbranch_scc1 .LBB0_133
	s_andn2_b64 vcc, exec, s[18:19]
	s_cbranch_vccnz .LBB0_136
	s_barrier

; #define PG8_STAGE(bufoff, gbase, voff) do { _Pragma("unroll") for (int _i = 0; _i < 2; ++_i) \
;         __builtin_amdgcn_global_load_lds((const unsigned*)((const char*)(gbase) + (voff)[_i]), (LAS unsigned*)(lds + (bufoff) + ldsw + _i * 8192), 16, 0, 0); } while (0)
; #define PG8_LDA(dst, b, h) do { _Pragma("unroll") for (int m = 0; m < 4; ++m) _Pragma("unroll") for (int k = 0; k < 2; ++k) dst[m][k] = *(const LAS bf16x8*)(lds + PG8_SA(b, h) + aoff + m * 2048 + k * 1024); } while (0)
; #define PG8_LDB(dst, b, h) do { _Pragma("unroll") for (int n = 0; n < 2; ++n) _Pragma("unroll") for (int k = 0; k < 2; ++k) dst[n][k] = *(const LAS bf16x8*)(lds + PG8_SB(b, h) + boff + n * 2048 + k * 1024); } while (0)
; #define PG8_MMA(ai, bj, At, Bt) do { __builtin_amdgcn_s_setprio(1); _Pragma("unroll") for (int m = 0; m < 4; ++m) _Pragma("unroll") for (int n = 0; n < 2; ++n) _Pragma("unroll") for (int k = 0; k < 2; ++k) \
;         acc[ai][bj][m][n] = __builtin_amdgcn_mfma_f32_16x16x32_bf16(Bt[n][k], At[m][k], acc[ai][bj][m][n], 0, 0, 0); __builtin_amdgcn_s_setprio(0); } while (0)
; #define PG8_WAIT_V(n) asm volatile("s_waitcnt vmcnt(" #n ")" ::: "memory")
; #define PG8_WAIT_L(n) asm volatile("s_waitcnt lgkmcnt(" #n ")" ::: "memory")
; #define PG8_BAR __builtin_amdgcn_s_barrier()
; #define PG8_SCHED __builtin_amdgcn_sched_barrier(0)
; template <class Epi, bool ALIGN_EPI = true, bool SP2 = true>
; __device__ __forceinline__ void gemm_phase(LAS unsigned char* lds, const Gemm g, const StaticOrder& S, const Epi& E, unsigned long long& tacc, const int tmode) {
;     ...
;             const bool last = (t == nt - 2);
;             const char* a1 = cA + (size_t)(t + 1) * kstepA;
;             const char* a2 = last ? nA : cA + (size_t)(t + 2) * kstepA; const char* b2 = last ? nB : cB + (size_t)(t + 2) * kstepB;
;             const char* a3 = a2 + kstepA; const char* b3 = b2 + kstepB;
;             if constexpr (SP2) {
;             PG8_LDB(B0, 0, 0); PG8_LDB(B1, 0, 1); PG8_SCHED; PG8_LDA(At, 0, 0); PG8_STAGE(PG8_SA(1, 1), a1 + hstepA, voffA);
;             PG8_WAIT_V(8); PG8_WAIT_L(0); PG8_BAR; PG8_MMA(0, 0, At, B0); PG8_MMA(0, 1, At, B1); PG8_BAR; PG8_SCHED;
;             PG8_LDA(At, 0, 1); PG8_STAGE(PG8_SB(0, 0), b2, voffB); PG8_STAGE(PG8_SB(0, 1), b2 + hstepB, voffB); PG8_STAGE(PG8_SA(0, 0), a2, voffA);
.LBB0_581:
	s_add_u32 s0, s22, 0xfff84000
	s_addc_u32 s1, s23, -1
	s_cmp_eq_u32 s56, 28
	s_cselect_b32 s34, s50, s0
	s_cselect_b32 s35, s25, s1
	s_cselect_b32 s38, s51, s54
	s_cselect_b32 s39, s21, s55
	s_add_u32 s30, s34, 0x4000
	s_addc_u32 s31, s35, 0
	s_add_i32 s0, 0, 0x10000
	v_add_u32_e32 v142, s0, v146
	s_add_i32 s33, 0, 0x14000
	ds_read_b128 v[132:135], v142
	ds_read_b128 v[136:139], v142 offset:1024
	ds_read_b128 v[148:151], v142 offset:2048
	ds_read_b128 v[152:155], v142 offset:3072
	v_add_u32_e32 v142, s33, v146
	ds_read_b128 v[156:159], v142
	ds_read_b128 v[160:163], v142 offset:1024
	ds_read_b128 v[164:167], v142 offset:2048
	ds_read_b128 v[168:171], v142 offset:3072
	v_lshl_add_u64 v[144:145], s[22:23], 0, v[130:131]
	s_add_i32 m0, s10, 0xc000
	ds_read_b128 v[172:175], v147
	ds_read_b128 v[176:179], v147 offset:1024
	ds_read_b128 v[180:183], v147 offset:2048
	ds_read_b128 v[184:187], v147 offset:3072
	ds_read_b128 v[188:191], v147 offset:4096
	ds_read_b128 v[194:197], v147 offset:5120
	ds_read_b128 v[206:209], v147 offset:6144
	ds_read_b128 v[210:213], v147 offset:7168
	global_load_lds_dwordx4 v[144:145], off
	v_lshl_add_u64 v[144:145], s[22:23], 0, v[140:141]
	s_add_i32 m0, s10, 0xe000
	s_nop 0
	global_load_lds_dwordx4 v[144:145], off
	s_waitcnt vmcnt(8)
	s_waitcnt lgkmcnt(0)
	s_barrier
	s_setprio 1
	s_waitcnt lgkmcnt(0)
	v_mfma_f32_16x16x32_bf16 v[126:129], v[132:135], v[172:175], v[126:129]
	v_mfma_f32_16x16x32_bf16 v[122:125], v[148:151], v[172:175], v[122:125]
	v_mfma_f32_16x16x32_bf16 v[118:121], v[132:135], v[180:183], v[118:121]
	v_mfma_f32_16x16x32_bf16 v[114:117], v[148:151], v[180:183], v[114:117]
	v_mfma_f32_16x16x32_bf16 v[110:113], v[132:135], v[188:191], v[110:113]
	v_mfma_f32_16x16x32_bf16 v[106:109], v[148:151], v[188:191], v[106:109]
	v_mfma_f32_16x16x32_bf16 v[102:105], v[132:135], v[206:209], v[102:105]
	v_mfma_f32_16x16x32_bf16 v[98:101], v[148:151], v[206:209], v[98:101]
	v_mfma_f32_16x16x32_bf16 v[126:129], v[136:139], v[176:179], v[126:129]
	v_mfma_f32_16x16x32_bf16 v[122:125], v[152:155], v[176:179], v[122:125]
	v_mfma_f32_16x16x32_bf16 v[118:121], v[136:139], v[184:187], v[118:121]
	v_mfma_f32_16x16x32_bf16 v[114:117], v[152:155], v[184:187], v[114:117]
	v_mfma_f32_16x16x32_bf16 v[110:113], v[136:139], v[194:197], v[110:113]
	v_mfma_f32_16x16x32_bf16 v[106:109], v[152:155], v[194:197], v[106:109]
	v_mfma_f32_16x16x32_bf16 v[102:105], v[136:139], v[210:213], v[102:105]
	v_mfma_f32_16x16x32_bf16 v[98:101], v[152:155], v[210:213], v[98:101]
	s_setprio 0
	s_setprio 1
	v_mfma_f32_16x16x32_bf16 v[62:65], v[156:159], v[172:175], v[62:65]
	v_mfma_f32_16x16x32_bf16 v[58:61], v[164:167], v[172:175], v[58:61]
	v_mfma_f32_16x16x32_bf16 v[54:57], v[156:159], v[180:183], v[54:57]
	v_mfma_f32_16x16x32_bf16 v[50:53], v[164:167], v[180:183], v[50:53]
	v_mfma_f32_16x16x32_bf16 v[46:49], v[156:159], v[188:191], v[46:49]
	v_mfma_f32_16x16x32_bf16 v[42:45], v[164:167], v[188:191], v[42:45]
	v_mfma_f32_16x16x32_bf16 v[38:41], v[156:159], v[206:209], v[38:41]
	v_mfma_f32_16x16x32_bf16 v[34:37], v[164:167], v[206:209], v[34:37]
	v_mfma_f32_16x16x32_bf16 v[62:65], v[160:163], v[176:179], v[62:65]
	v_mfma_f32_16x16x32_bf16 v[58:61], v[168:171], v[176:179], v[58:61]
	v_mfma_f32_16x16x32_bf16 v[54:57], v[160:163], v[184:187], v[54:57]
	v_mfma_f32_16x16x32_bf16 v[50:53], v[168:171], v[184:187], v[50:53]
	v_mfma_f32_16x16x32_bf16 v[46:49], v[160:163], v[194:197], v[46:49]
	v_mfma_f32_16x16x32_bf16 v[42:45], v[168:171], v[194:197], v[42:45]
	v_mfma_f32_16x16x32_bf16 v[38:41], v[160:163], v[210:213], v[38:41]
	s_nop 1
	s_barrier
	v_mfma_f32_16x16x32_bf16 v[34:37], v[168:171], v[210:213], v[34:37]
	s_setprio 0
	s_add_i32 s0, s0, s2
	v_lshl_add_u64 v[144:145], s[38:39], 0, v[130:131]
	s_mov_b32 m0, s0
	ds_read_b128 v[172:175], v147 offset:16384
	ds_read_b128 v[176:179], v147 offset:17408
	ds_read_b128 v[180:183], v147 offset:18432
	ds_read_b128 v[184:187], v147 offset:19456
	ds_read_b128 v[188:191], v147 offset:20480
	ds_read_b128 v[194:197], v147 offset:21504
	ds_read_b128 v[206:209], v147 offset:22528
	ds_read_b128 v[210:213], v147 offset:23552
	global_load_lds_dwordx4 v[144:145], off
	s_add_i32 m0, s0, 0x2000
	s_add_u32 s0, s38, 0x80000
	v_lshl_add_u64 v[144:145], s[38:39], 0, v[140:141]
	s_addc_u32 s1, s39, 0
	s_add_i32 s33, s33, s2
	global_load_lds_dwordx4 v[144:145], off
	v_lshl_add_u64 v[144:145], s[0:1], 0, v[130:131]
	s_mov_b32 m0, s33
	s_nop 0
	global_load_lds_dwordx4 v[144:145], off
	v_lshl_add_u64 v[144:145], s[0:1], 0, v[140:141]
	s_add_i32 m0, s33, 0x2000
	s_nop 0
	global_load_lds_dwordx4 v[144:145], off
	v_lshl_add_u64 v[144:145], s[34:35], 0, v[130:131]
	s_mov_b32 m0, s10
	s_nop 0
	global_load_lds_dwordx4 v[144:145], off
	v_lshl_add_u64 v[144:145], s[34:35], 0, v[140:141]
	s_mov_b32 m0, s40
	s_nop 0
	global_load_lds_dwordx4 v[144:145], off
	s_waitcnt vmcnt(8)
	s_waitcnt lgkmcnt(0)
	s_barrier
; #define PG8_STAGE(bufoff, gbase, voff) do { _Pragma("unroll") for (int _i = 0; _i < 2; ++_i) \
;         __builtin_amdgcn_global_load_lds((const unsigned*)((const char*)(gbase) + (voff)[_i]), (LAS unsigned*)(lds + (bufoff) + ldsw + _i * 8192), 16, 0, 0); } while (0)
; #define PG8_LDA(dst, b, h) do { _Pragma("unroll") for (int m = 0; m < 4; ++m) _Pragma("unroll") for (int k = 0; k < 2; ++k) dst[m][k] = *(const LAS bf16x8*)(lds + PG8_SA(b, h) + aoff + m * 2048 + k * 1024); } while (0)
; #define PG8_LDB(dst, b, h) do { _Pragma("unroll") for (int n = 0; n < 2; ++n) _Pragma("unroll") for (int k = 0; k < 2; ++k) dst[n][k] = *(const LAS bf16x8*)(lds + PG8_SB(b, h) + boff + n * 2048 + k * 1024); } while (0)
; #define PG8_MMA(ai, bj, At, Bt) do { __builtin_amdgcn_s_setprio(1); _Pragma("unroll") for (int m = 0; m < 4; ++m) _Pragma("unroll") for (int n = 0; n < 2; ++n) _Pragma("unroll") for (int k = 0; k < 2; ++k) \
;         acc[ai][bj][m][n] = __builtin_amdgcn_mfma_f32_16x16x32_bf16(Bt[n][k], At[m][k], acc[ai][bj][m][n], 0, 0, 0); __builtin_amdgcn_s_setprio(0); } while (0)
; #define PG8_WAIT_V(n) asm volatile("s_waitcnt vmcnt(" #n ")" ::: "memory")
; #define PG8_WAIT_L(n) asm volatile("s_waitcnt lgkmcnt(" #n ")" ::: "memory")
; #define PG8_BAR __builtin_amdgcn_s_barrier()
; #define PG8_SCHED __builtin_amdgcn_sched_barrier(0)
; template <class Epi, bool ALIGN_EPI = true, bool SP2 = true>
; __device__ __forceinline__ void gemm_phase(LAS unsigned char* lds, const Gemm g, const StaticOrder& S, const Epi& E, unsigned long long& tacc, const int tmode) {
;     ...
;             PG8_WAIT_V(8); PG8_WAIT_L(0); PG8_BAR; PG8_MMA(1, 0, At, B0); PG8_MMA(1, 1, At, B1); PG8_BAR; PG8_SCHED;
;             PG8_LDB(B0, 1, 0); PG8_LDB(B1, 1, 1); PG8_SCHED; PG8_LDA(At, 1, 0); PG8_STAGE(PG8_SA(0, 1), a2 + hstepA, voffA);
;             PG8_WAIT_V(8); PG8_WAIT_L(0); PG8_BAR; PG8_MMA(0, 0, At, B0); PG8_MMA(0, 1, At, B1); PG8_BAR; PG8_SCHED;
	s_setprio 1
	s_waitcnt lgkmcnt(0)
	v_mfma_f32_16x16x32_bf16 v[94:97], v[132:135], v[172:175], v[94:97]
	v_mfma_f32_16x16x32_bf16 v[90:93], v[148:151], v[172:175], v[90:93]
	v_mfma_f32_16x16x32_bf16 v[86:89], v[132:135], v[180:183], v[86:89]
	v_mfma_f32_16x16x32_bf16 v[82:85], v[148:151], v[180:183], v[82:85]
	v_mfma_f32_16x16x32_bf16 v[78:81], v[132:135], v[188:191], v[78:81]
	v_mfma_f32_16x16x32_bf16 v[74:77], v[148:151], v[188:191], v[74:77]
	v_mfma_f32_16x16x32_bf16 v[70:73], v[132:135], v[206:209], v[70:73]
	v_mfma_f32_16x16x32_bf16 v[66:69], v[148:151], v[206:209], v[66:69]
	v_mfma_f32_16x16x32_bf16 v[94:97], v[136:139], v[176:179], v[94:97]
	v_mfma_f32_16x16x32_bf16 v[90:93], v[152:155], v[176:179], v[90:93]
	v_mfma_f32_16x16x32_bf16 v[86:89], v[136:139], v[184:187], v[86:89]
	v_mfma_f32_16x16x32_bf16 v[82:85], v[152:155], v[184:187], v[82:85]
	v_mfma_f32_16x16x32_bf16 v[78:81], v[136:139], v[194:197], v[78:81]
	v_mfma_f32_16x16x32_bf16 v[74:77], v[152:155], v[194:197], v[74:77]
	v_mfma_f32_16x16x32_bf16 v[70:73], v[136:139], v[210:213], v[70:73]
	v_mfma_f32_16x16x32_bf16 v[66:69], v[152:155], v[210:213], v[66:69]
	s_setprio 0
	s_setprio 1
	v_mfma_f32_16x16x32_bf16 v[30:33], v[156:159], v[172:175], v[30:33]
	v_mfma_f32_16x16x32_bf16 v[26:29], v[164:167], v[172:175], v[26:29]
	v_mfma_f32_16x16x32_bf16 v[22:25], v[156:159], v[180:183], v[22:25]
	v_mfma_f32_16x16x32_bf16 v[18:21], v[164:167], v[180:183], v[18:21]
	v_mfma_f32_16x16x32_bf16 v[14:17], v[156:159], v[188:191], v[14:17]
	v_mfma_f32_16x16x32_bf16 v[10:13], v[164:167], v[188:191], v[10:13]
	v_mfma_f32_16x16x32_bf16 v[6:9], v[156:159], v[206:209], v[6:9]
	v_mfma_f32_16x16x32_bf16 v[2:5], v[164:167], v[206:209], v[2:5]
	v_mfma_f32_16x16x32_bf16 v[30:33], v[160:163], v[176:179], v[30:33]
	v_mfma_f32_16x16x32_bf16 v[26:29], v[168:171], v[176:179], v[26:29]
	v_mfma_f32_16x16x32_bf16 v[22:25], v[160:163], v[184:187], v[22:25]
	v_mfma_f32_16x16x32_bf16 v[18:21], v[168:171], v[184:187], v[18:21]
	v_mfma_f32_16x16x32_bf16 v[14:17], v[160:163], v[194:197], v[14:17]
	v_mfma_f32_16x16x32_bf16 v[10:13], v[168:171], v[194:197], v[10:13]
	v_mfma_f32_16x16x32_bf16 v[6:9], v[160:163], v[210:213], v[6:9]
	s_nop 1
	s_barrier
	v_mfma_f32_16x16x32_bf16 v[2:5], v[168:171], v[210:213], v[2:5]
	s_setprio 0
	s_add_i32 s33, 0, 0x18000
	v_add_u32_e32 v142, s33, v146
	s_add_i32 s57, 0, 0x1c000
	ds_read_b128 v[132:135], v142
	ds_read_b128 v[136:139], v142 offset:1024
	ds_read_b128 v[148:151], v142 offset:2048
	ds_read_b128 v[152:155], v142 offset:3072
	v_add_u32_e32 v142, s57, v146
	ds_read_b128 v[156:159], v142
	ds_read_b128 v[160:163], v142 offset:1024
	ds_read_b128 v[164:167], v142 offset:2048
	ds_read_b128 v[168:171], v142 offset:3072
	s_add_u32 s0, s34, 0x80000
	s_addc_u32 s1, s35, 0
	s_mov_b32 m0, s41
	v_lshl_add_u64 v[144:145], s[0:1], 0, v[130:131]
	ds_read_b128 v[172:175], v147 offset:32768
	ds_read_b128 v[176:179], v147 offset:33792
	ds_read_b128 v[180:183], v147 offset:34816
	ds_read_b128 v[184:187], v147 offset:35840
	ds_read_b128 v[188:191], v147 offset:36864
	ds_read_b128 v[194:197], v147 offset:37888
	ds_read_b128 v[206:209], v147 offset:38912
	ds_read_b128 v[210:213], v147 offset:39936
	global_load_lds_dwordx4 v[144:145], off
	v_lshl_add_u64 v[144:145], s[0:1], 0, v[140:141]
	s_mov_b32 m0, s42
	s_nop 0
	global_load_lds_dwordx4 v[144:145], off
	s_waitcnt vmcnt(8)
	s_waitcnt lgkmcnt(0)
	s_barrier
	s_setprio 1
	s_waitcnt lgkmcnt(0)
	v_mfma_f32_16x16x32_bf16 v[126:129], v[132:135], v[172:175], v[126:129]
	v_mfma_f32_16x16x32_bf16 v[122:125], v[148:151], v[172:175], v[122:125]
	v_mfma_f32_16x16x32_bf16 v[118:121], v[132:135], v[180:183], v[118:121]
	v_mfma_f32_16x16x32_bf16 v[114:117], v[148:151], v[180:183], v[114:117]
	v_mfma_f32_16x16x32_bf16 v[110:113], v[132:135], v[188:191], v[110:113]
	v_mfma_f32_16x16x32_bf16 v[106:109], v[148:151], v[188:191], v[106:109]
	v_mfma_f32_16x16x32_bf16 v[102:105], v[132:135], v[206:209], v[102:105]
	v_mfma_f32_16x16x32_bf16 v[98:101], v[148:151], v[206:209], v[98:101]
	v_mfma_f32_16x16x32_bf16 v[126:129], v[136:139], v[176:179], v[126:129]
	v_mfma_f32_16x16x32_bf16 v[122:125], v[152:155], v[176:179], v[122:125]
	v_mfma_f32_16x16x32_bf16 v[118:121], v[136:139], v[184:187], v[118:121]
	v_mfma_f32_16x16x32_bf16 v[114:117], v[152:155], v[184:187], v[114:117]
	v_mfma_f32_16x16x32_bf16 v[110:113], v[136:139], v[194:197], v[110:113]
	v_mfma_f32_16x16x32_bf16 v[106:109], v[152:155], v[194:197], v[106:109]
	v_mfma_f32_16x16x32_bf16 v[102:105], v[136:139], v[210:213], v[102:105]
	v_mfma_f32_16x16x32_bf16 v[98:101], v[152:155], v[210:213], v[98:101]
	s_setprio 0
	s_setprio 1
	v_mfma_f32_16x16x32_bf16 v[62:65], v[156:159], v[172:175], v[62:65]
	v_mfma_f32_16x16x32_bf16 v[58:61], v[164:167], v[172:175], v[58:61]
	v_mfma_f32_16x16x32_bf16 v[54:57], v[156:159], v[180:183], v[54:57]
	v_mfma_f32_16x16x32_bf16 v[50:53], v[164:167], v[180:183], v[50:53]
	v_mfma_f32_16x16x32_bf16 v[46:49], v[156:159], v[188:191], v[46:49]
	v_mfma_f32_16x16x32_bf16 v[42:45], v[164:167], v[188:191], v[42:45]
	v_mfma_f32_16x16x32_bf16 v[38:41], v[156:159], v[206:209], v[38:41]
	v_mfma_f32_16x16x32_bf16 v[34:37], v[164:167], v[206:209], v[34:37]
	v_mfma_f32_16x16x32_bf16 v[62:65], v[160:163], v[176:179], v[62:65]
	v_mfma_f32_16x16x32_bf16 v[58:61], v[168:171], v[176:179], v[58:61]
	v_mfma_f32_16x16x32_bf16 v[54:57], v[160:163], v[184:187], v[54:57]
	v_mfma_f32_16x16x32_bf16 v[50:53], v[168:171], v[184:187], v[50:53]
	v_mfma_f32_16x16x32_bf16 v[46:49], v[160:163], v[194:197], v[46:49]
	v_mfma_f32_16x16x32_bf16 v[42:45], v[168:171], v[194:197], v[42:45]
	v_mfma_f32_16x16x32_bf16 v[38:41], v[160:163], v[210:213], v[38:41]
	s_nop 1
	s_barrier
; #define PG8_STAGE(bufoff, gbase, voff) do { _Pragma("unroll") for (int _i = 0; _i < 2; ++_i) \
;         __builtin_amdgcn_global_load_lds((const unsigned*)((const char*)(gbase) + (voff)[_i]), (LAS unsigned*)(lds + (bufoff) + ldsw + _i * 8192), 16, 0, 0); } while (0)
; #define PG8_LDA(dst, b, h) do { _Pragma("unroll") for (int m = 0; m < 4; ++m) _Pragma("unroll") for (int k = 0; k < 2; ++k) dst[m][k] = *(const LAS bf16x8*)(lds + PG8_SA(b, h) + aoff + m * 2048 + k * 1024); } while (0)
; #define PG8_MMA(ai, bj, At, Bt) do { __builtin_amdgcn_s_setprio(1); _Pragma("unroll") for (int m = 0; m < 4; ++m) _Pragma("unroll") for (int n = 0; n < 2; ++n) _Pragma("unroll") for (int k = 0; k < 2; ++k) \
;         acc[ai][bj][m][n] = __builtin_amdgcn_mfma_f32_16x16x32_bf16(Bt[n][k], At[m][k], acc[ai][bj][m][n], 0, 0, 0); __builtin_amdgcn_s_setprio(0); } while (0)
; #define PG8_WAIT_V(n) asm volatile("s_waitcnt vmcnt(" #n ")" ::: "memory")
; #define PG8_WAIT_L(n) asm volatile("s_waitcnt lgkmcnt(" #n ")" ::: "memory")
; #define PG8_BAR __builtin_amdgcn_s_barrier()
; #define PG8_SCHED __builtin_amdgcn_sched_barrier(0)
; template <class Epi, bool ALIGN_EPI = true, bool SP2 = true>
; __device__ __forceinline__ void gemm_phase(LAS unsigned char* lds, const Gemm g, const StaticOrder& S, const Epi& E, unsigned long long& tacc, const int tmode) {
;     ...
;             PG8_WAIT_V(8); PG8_WAIT_L(0); PG8_BAR; PG8_MMA(0, 0, At, B0); PG8_MMA(0, 1, At, B1); PG8_BAR; PG8_SCHED;
;             PG8_LDA(At, 1, 1); PG8_STAGE(PG8_SB(1, 0), b3, voffB); PG8_STAGE(PG8_SB(1, 1), b3 + hstepB, voffB); PG8_STAGE(PG8_SA(1, 0), a3, voffA);
;             PG8_WAIT_V(8); PG8_WAIT_L(0); PG8_BAR; PG8_MMA(1, 0, At, B0); PG8_MMA(1, 1, At, B1); PG8_BAR; PG8_SCHED;
	v_mfma_f32_16x16x32_bf16 v[34:37], v[168:171], v[210:213], v[34:37]
	s_setprio 0
	s_add_u32 s0, s38, 0x4000
	s_addc_u32 s1, s39, 0
	s_add_i32 s33, s33, s2
	v_lshl_add_u64 v[144:145], s[0:1], 0, v[130:131]
	s_mov_b32 m0, s33
	ds_read_b128 v[172:175], v147 offset:49152
	ds_read_b128 v[176:179], v147 offset:50176
	ds_read_b128 v[180:183], v147 offset:51200
	ds_read_b128 v[184:187], v147 offset:52224
	ds_read_b128 v[188:191], v147 offset:53248
	ds_read_b128 v[194:197], v147 offset:54272
	ds_read_b128 v[206:209], v147 offset:55296
	ds_read_b128 v[210:213], v147 offset:56320
	global_load_lds_dwordx4 v[144:145], off
	s_add_i32 m0, s33, 0x2000
	v_lshl_add_u64 v[144:145], s[0:1], 0, v[140:141]
	s_add_u32 s0, s38, 0x84000
	s_addc_u32 s1, s39, 0
	s_add_i32 s33, s57, s2
	global_load_lds_dwordx4 v[144:145], off
	v_lshl_add_u64 v[144:145], s[0:1], 0, v[130:131]
	s_mov_b32 m0, s33
	s_nop 0
	global_load_lds_dwordx4 v[144:145], off
	v_lshl_add_u64 v[144:145], s[0:1], 0, v[140:141]
	s_add_i32 m0, s33, 0x2000
	s_nop 0
	global_load_lds_dwordx4 v[144:145], off
	v_lshl_add_u64 v[144:145], s[30:31], 0, v[130:131]
	s_mov_b32 m0, s45
	s_nop 0
	global_load_lds_dwordx4 v[144:145], off
	v_lshl_add_u64 v[144:145], s[30:31], 0, v[140:141]
	s_mov_b32 m0, s46
	s_nop 0
	global_load_lds_dwordx4 v[144:145], off
	s_waitcnt vmcnt(8)
	s_waitcnt lgkmcnt(0)
	s_barrier
	s_setprio 1
	s_waitcnt lgkmcnt(0)
	v_mfma_f32_16x16x32_bf16 v[94:97], v[132:135], v[172:175], v[94:97]
	v_mfma_f32_16x16x32_bf16 v[90:93], v[148:151], v[172:175], v[90:93]
	v_mfma_f32_16x16x32_bf16 v[86:89], v[132:135], v[180:183], v[86:89]
	v_mfma_f32_16x16x32_bf16 v[82:85], v[148:151], v[180:183], v[82:85]
	v_mfma_f32_16x16x32_bf16 v[78:81], v[132:135], v[188:191], v[78:81]
	v_mfma_f32_16x16x32_bf16 v[74:77], v[148:151], v[188:191], v[74:77]
	v_mfma_f32_16x16x32_bf16 v[70:73], v[132:135], v[206:209], v[70:73]
	v_mfma_f32_16x16x32_bf16 v[66:69], v[148:151], v[206:209], v[66:69]
	v_mfma_f32_16x16x32_bf16 v[94:97], v[136:139], v[176:179], v[94:97]
	v_mfma_f32_16x16x32_bf16 v[90:93], v[152:155], v[176:179], v[90:93]
	v_mfma_f32_16x16x32_bf16 v[86:89], v[136:139], v[184:187], v[86:89]
	v_mfma_f32_16x16x32_bf16 v[82:85], v[152:155], v[184:187], v[82:85]
	v_mfma_f32_16x16x32_bf16 v[78:81], v[136:139], v[194:197], v[78:81]
	v_mfma_f32_16x16x32_bf16 v[74:77], v[152:155], v[194:197], v[74:77]
	v_mfma_f32_16x16x32_bf16 v[70:73], v[136:139], v[210:213], v[70:73]
	v_mfma_f32_16x16x32_bf16 v[66:69], v[152:155], v[210:213], v[66:69]
	s_setprio 0
	s_setprio 1
	v_mfma_f32_16x16x32_bf16 v[30:33], v[156:159], v[172:175], v[30:33]
	v_mfma_f32_16x16x32_bf16 v[26:29], v[164:167], v[172:175], v[26:29]
	v_mfma_f32_16x16x32_bf16 v[22:25], v[156:159], v[180:183], v[22:25]
	v_mfma_f32_16x16x32_bf16 v[18:21], v[164:167], v[180:183], v[18:21]
	v_mfma_f32_16x16x32_bf16 v[14:17], v[156:159], v[188:191], v[14:17]
	v_mfma_f32_16x16x32_bf16 v[10:13], v[164:167], v[188:191], v[10:13]
	v_mfma_f32_16x16x32_bf16 v[6:9], v[156:159], v[206:209], v[6:9]
	v_mfma_f32_16x16x32_bf16 v[2:5], v[164:167], v[206:209], v[2:5]
	v_mfma_f32_16x16x32_bf16 v[30:33], v[160:163], v[176:179], v[30:33]
	v_mfma_f32_16x16x32_bf16 v[26:29], v[168:171], v[176:179], v[26:29]
	v_mfma_f32_16x16x32_bf16 v[22:25], v[160:163], v[184:187], v[22:25]
	v_mfma_f32_16x16x32_bf16 v[18:21], v[168:171], v[184:187], v[18:21]
	v_mfma_f32_16x16x32_bf16 v[14:17], v[160:163], v[194:197], v[14:17]
	v_mfma_f32_16x16x32_bf16 v[10:13], v[168:171], v[194:197], v[10:13]
	v_mfma_f32_16x16x32_bf16 v[6:9], v[160:163], v[210:213], v[6:9]
	s_nop 1
	s_barrier
	v_mfma_f32_16x16x32_bf16 v[2:5], v[168:171], v[210:213], v[2:5]
	s_setprio 0
	s_add_i32 s56, s56, 2
	s_add_u32 s22, s22, 0x8000
	s_addc_u32 s23, s23, 0
	s_add_u32 s54, s54, 0x8000
	s_addc_u32 s55, s55, 0
	s_cmp_lt_u32 s56, 30
	s_cbranch_scc1 .LBB0_581
	s_andn2_b64 vcc, exec, s[18:19]
	s_cbranch_vccnz .LBB0_584
	s_barrier

; #define PG8_STAGE(bufoff, gbase, voff) do { _Pragma("unroll") for (int _i = 0; _i < 2; ++_i) \
;         __builtin_amdgcn_global_load_lds((const unsigned*)((const char*)(gbase) + (voff)[_i]), (LAS unsigned*)(lds + (bufoff) + ldsw + _i * 8192), 16, 0, 0); } while (0)
; #define PG8_LDA(dst, b, h) do { _Pragma("unroll") for (int m = 0; m < 4; ++m) _Pragma("unroll") for (int k = 0; k < 2; ++k) dst[m][k] = *(const LAS bf16x8*)(lds + PG8_SA(b, h) + aoff + m * 2048 + k * 1024); } while (0)
; #define PG8_LDB(dst, b, h) do { _Pragma("unroll") for (int n = 0; n < 2; ++n) _Pragma("unroll") for (int k = 0; k < 2; ++k) dst[n][k] = *(const LAS bf16x8*)(lds + PG8_SB(b, h) + boff + n * 2048 + k * 1024); } while (0)
; #define PG8_MMA(ai, bj, At, Bt) do { __builtin_amdgcn_s_setprio(1); _Pragma("unroll") for (int m = 0; m < 4; ++m) _Pragma("unroll") for (int n = 0; n < 2; ++n) _Pragma("unroll") for (int k = 0; k < 2; ++k) \
;         acc[ai][bj][m][n] = __builtin_amdgcn_mfma_f32_16x16x32_bf16(Bt[n][k], At[m][k], acc[ai][bj][m][n], 0, 0, 0); __builtin_amdgcn_s_setprio(0); } while (0)
; #define PG8_WAIT_V(n) asm volatile("s_waitcnt vmcnt(" #n ")" ::: "memory")
; #define PG8_WAIT_L(n) asm volatile("s_waitcnt lgkmcnt(" #n ")" ::: "memory")
; template <class Epi, bool ALIGN_EPI = true, bool SP2 = true>
; __device__ __forceinline__ void gemm_phase(LAS unsigned char* lds, const Gemm g, const StaticOrder& S, const Epi& E, unsigned long long& tacc, const int tmode) {
;     ...
;         for (int t = 0; t < nt; t += 2) {
;             const bool last = (t == nt - 2);
;             const char* a1 = cA + (size_t)(t + 1) * kstepA;
;             const char* a2 = last ? nA : cA + (size_t)(t + 2) * kstepA; const char* b2 = last ? nB : cB + (size_t)(t + 2) * kstepB;
;             const char* a3 = a2 + kstepA; const char* b3 = b2 + kstepB;
;             if constexpr (SP2) {
;             PG8_LDB(B0, 0, 0); PG8_LDB(B1, 0, 1); PG8_SCHED; PG8_LDA(At, 0, 0); PG8_STAGE(PG8_SA(1, 1), a1 + hstepA, voffA);
;             PG8_WAIT_V(8); PG8_WAIT_L(0); PG8_BAR; PG8_MMA(0, 0, At, B0); PG8_MMA(0, 1, At, B1); PG8_BAR; PG8_SCHED;
;             PG8_LDA(At, 0, 1); PG8_STAGE(PG8_SB(0, 0), b2, voffB); PG8_STAGE(PG8_SB(0, 1), b2 + hstepB, voffB); PG8_STAGE(PG8_SA(0, 0), a2, voffA);
;             PG8_WAIT_V(8); PG8_WAIT_L(0); PG8_BAR; PG8_MMA(1, 0, At, B0); PG8_MMA(1, 1, At, B1); PG8_BAR; PG8_SCHED;
.LBB0_739:
	s_add_u32 s0, s22, 0xfff84000
	s_addc_u32 s1, s23, -1
	s_cmp_eq_u32 s65, 28
	s_cselect_b32 s34, s56, s0
	s_cselect_b32 s35, s25, s1
	s_cselect_b32 s40, s57, s60
	s_cselect_b32 s41, s21, s61
	s_add_u32 s30, s34, 0x4000
	s_addc_u32 s31, s35, 0
	s_add_i32 s0, 0, 0x10000
	v_add_u32_e32 v138, s0, v141
	s_add_i32 s33, 0, 0x14000
	ds_read_b128 v[134:137], v138
	ds_read_b128 v[144:147], v138 offset:1024
	ds_read_b128 v[148:151], v138 offset:2048
	ds_read_b128 v[152:155], v138 offset:3072
	v_add_u32_e32 v138, s33, v141
	ds_read_b128 v[156:159], v138
	ds_read_b128 v[160:163], v138 offset:1024
	ds_read_b128 v[164:167], v138 offset:2048
	ds_read_b128 v[168:171], v138 offset:3072
	v_lshl_add_u64 v[138:139], s[22:23], 0, v[130:131]
	s_add_i32 m0, s43, 0xc000
	ds_read_b128 v[172:175], v142
	ds_read_b128 v[176:179], v142 offset:1024
	ds_read_b128 v[180:183], v142 offset:2048
	ds_read_b128 v[184:187], v142 offset:3072
	ds_read_b128 v[188:191], v142 offset:4096
	ds_read_b128 v[206:209], v142 offset:5120
	ds_read_b128 v[210:213], v142 offset:6144
	ds_read_b128 v[214:217], v142 offset:7168
	global_load_lds_dwordx4 v[138:139], off
	v_lshl_add_u64 v[138:139], s[22:23], 0, v[132:133]
	s_add_i32 m0, s43, 0xe000
	s_nop 0
	global_load_lds_dwordx4 v[138:139], off
	s_waitcnt vmcnt(8)
	s_waitcnt lgkmcnt(0)
	s_barrier
	s_setprio 1
	s_waitcnt lgkmcnt(0)
	v_mfma_f32_16x16x32_bf16 v[126:129], v[134:137], v[172:175], v[126:129]
	v_mfma_f32_16x16x32_bf16 v[122:125], v[148:151], v[172:175], v[122:125]
	v_mfma_f32_16x16x32_bf16 v[110:113], v[134:137], v[180:183], v[110:113]
	v_mfma_f32_16x16x32_bf16 v[106:109], v[148:151], v[180:183], v[106:109]
	v_mfma_f32_16x16x32_bf16 v[94:97], v[134:137], v[188:191], v[94:97]
	v_mfma_f32_16x16x32_bf16 v[90:93], v[148:151], v[188:191], v[90:93]
	v_mfma_f32_16x16x32_bf16 v[78:81], v[134:137], v[210:213], v[78:81]
	v_mfma_f32_16x16x32_bf16 v[74:77], v[148:151], v[210:213], v[74:77]
	v_mfma_f32_16x16x32_bf16 v[126:129], v[144:147], v[176:179], v[126:129]
	v_mfma_f32_16x16x32_bf16 v[122:125], v[152:155], v[176:179], v[122:125]
	v_mfma_f32_16x16x32_bf16 v[110:113], v[144:147], v[184:187], v[110:113]
	v_mfma_f32_16x16x32_bf16 v[106:109], v[152:155], v[184:187], v[106:109]
	v_mfma_f32_16x16x32_bf16 v[94:97], v[144:147], v[206:209], v[94:97]
	v_mfma_f32_16x16x32_bf16 v[90:93], v[152:155], v[206:209], v[90:93]
	v_mfma_f32_16x16x32_bf16 v[78:81], v[144:147], v[214:217], v[78:81]
	v_mfma_f32_16x16x32_bf16 v[74:77], v[152:155], v[214:217], v[74:77]
	s_setprio 0
	s_setprio 1
	v_mfma_f32_16x16x32_bf16 v[118:121], v[156:159], v[172:175], v[118:121]
	v_mfma_f32_16x16x32_bf16 v[114:117], v[164:167], v[172:175], v[114:117]
	v_mfma_f32_16x16x32_bf16 v[102:105], v[156:159], v[180:183], v[102:105]
	v_mfma_f32_16x16x32_bf16 v[98:101], v[164:167], v[180:183], v[98:101]
	v_mfma_f32_16x16x32_bf16 v[86:89], v[156:159], v[188:191], v[86:89]
	v_mfma_f32_16x16x32_bf16 v[82:85], v[164:167], v[188:191], v[82:85]
	v_mfma_f32_16x16x32_bf16 v[70:73], v[156:159], v[210:213], v[70:73]
	v_mfma_f32_16x16x32_bf16 v[66:69], v[164:167], v[210:213], v[66:69]
	v_mfma_f32_16x16x32_bf16 v[118:121], v[160:163], v[176:179], v[118:121]
	v_mfma_f32_16x16x32_bf16 v[114:117], v[168:171], v[176:179], v[114:117]
	v_mfma_f32_16x16x32_bf16 v[102:105], v[160:163], v[184:187], v[102:105]
	v_mfma_f32_16x16x32_bf16 v[98:101], v[168:171], v[184:187], v[98:101]
	v_mfma_f32_16x16x32_bf16 v[86:89], v[160:163], v[206:209], v[86:89]
	v_mfma_f32_16x16x32_bf16 v[82:85], v[168:171], v[206:209], v[82:85]
	v_mfma_f32_16x16x32_bf16 v[70:73], v[160:163], v[214:217], v[70:73]
	s_nop 1
	s_barrier
	v_mfma_f32_16x16x32_bf16 v[66:69], v[168:171], v[214:217], v[66:69]
	s_setprio 0
	s_add_i32 s0, s0, s42
	v_lshl_add_u64 v[138:139], s[40:41], 0, v[130:131]
	s_mov_b32 m0, s0
	ds_read_b128 v[172:175], v142 offset:16384
	ds_read_b128 v[176:179], v142 offset:17408
	ds_read_b128 v[180:183], v142 offset:18432
	ds_read_b128 v[184:187], v142 offset:19456
	ds_read_b128 v[188:191], v142 offset:20480
	ds_read_b128 v[206:209], v142 offset:21504
	ds_read_b128 v[210:213], v142 offset:22528
	ds_read_b128 v[214:217], v142 offset:23552
	global_load_lds_dwordx4 v[138:139], off
	s_add_i32 m0, s0, 0x2000
	s_add_u32 s0, s40, 0x80000
	v_lshl_add_u64 v[138:139], s[40:41], 0, v[132:133]
	s_addc_u32 s1, s41, 0
	s_add_i32 s33, s33, s42
	global_load_lds_dwordx4 v[138:139], off
	v_lshl_add_u64 v[138:139], s[0:1], 0, v[130:131]
	s_mov_b32 m0, s33
	s_nop 0
	global_load_lds_dwordx4 v[138:139], off
	v_lshl_add_u64 v[138:139], s[0:1], 0, v[132:133]
	s_add_i32 m0, s33, 0x2000
	s_nop 0
	global_load_lds_dwordx4 v[138:139], off
	v_lshl_add_u64 v[138:139], s[34:35], 0, v[130:131]
	s_mov_b32 m0, s43
	s_nop 0
	global_load_lds_dwordx4 v[138:139], off
	v_lshl_add_u64 v[138:139], s[34:35], 0, v[132:133]
	s_mov_b32 m0, s44
	s_nop 0
	global_load_lds_dwordx4 v[138:139], off
	s_waitcnt vmcnt(8)
	s_waitcnt lgkmcnt(0)
	s_barrier
; #define PG8_STAGE(bufoff, gbase, voff) do { _Pragma("unroll") for (int _i = 0; _i < 2; ++_i) \
;         __builtin_amdgcn_global_load_lds((const unsigned*)((const char*)(gbase) + (voff)[_i]), (LAS unsigned*)(lds + (bufoff) + ldsw + _i * 8192), 16, 0, 0); } while (0)
; #define PG8_LDA(dst, b, h) do { _Pragma("unroll") for (int m = 0; m < 4; ++m) _Pragma("unroll") for (int k = 0; k < 2; ++k) dst[m][k] = *(const LAS bf16x8*)(lds + PG8_SA(b, h) + aoff + m * 2048 + k * 1024); } while (0)
; #define PG8_LDB(dst, b, h) do { _Pragma("unroll") for (int n = 0; n < 2; ++n) _Pragma("unroll") for (int k = 0; k < 2; ++k) dst[n][k] = *(const LAS bf16x8*)(lds + PG8_SB(b, h) + boff + n * 2048 + k * 1024); } while (0)
; #define PG8_MMA(ai, bj, At, Bt) do { __builtin_amdgcn_s_setprio(1); _Pragma("unroll") for (int m = 0; m < 4; ++m) _Pragma("unroll") for (int n = 0; n < 2; ++n) _Pragma("unroll") for (int k = 0; k < 2; ++k) \
;         acc[ai][bj][m][n] = __builtin_amdgcn_mfma_f32_16x16x32_bf16(Bt[n][k], At[m][k], acc[ai][bj][m][n], 0, 0, 0); __builtin_amdgcn_s_setprio(0); } while (0)
; #define PG8_WAIT_V(n) asm volatile("s_waitcnt vmcnt(" #n ")" ::: "memory")
; #define PG8_WAIT_L(n) asm volatile("s_waitcnt lgkmcnt(" #n ")" ::: "memory")
; #define PG8_BAR __builtin_amdgcn_s_barrier()
; #define PG8_SCHED __builtin_amdgcn_sched_barrier(0)
; template <class Epi, bool ALIGN_EPI = true, bool SP2 = true>
; __device__ __forceinline__ void gemm_phase(LAS unsigned char* lds, const Gemm g, const StaticOrder& S, const Epi& E, unsigned long long& tacc, const int tmode) {
;     ...
;             PG8_WAIT_V(8); PG8_WAIT_L(0); PG8_BAR; PG8_MMA(1, 0, At, B0); PG8_MMA(1, 1, At, B1); PG8_BAR; PG8_SCHED;
;             PG8_LDB(B0, 1, 0); PG8_LDB(B1, 1, 1); PG8_SCHED; PG8_LDA(At, 1, 0); PG8_STAGE(PG8_SA(0, 1), a2 + hstepA, voffA);
;             PG8_WAIT_V(8); PG8_WAIT_L(0); PG8_BAR; PG8_MMA(0, 0, At, B0); PG8_MMA(0, 1, At, B1); PG8_BAR; PG8_SCHED;
	s_setprio 1
	s_waitcnt lgkmcnt(0)
	v_mfma_f32_16x16x32_bf16 v[62:65], v[134:137], v[172:175], v[62:65]
	v_mfma_f32_16x16x32_bf16 v[58:61], v[148:151], v[172:175], v[58:61]
	v_mfma_f32_16x16x32_bf16 v[46:49], v[134:137], v[180:183], v[46:49]
	v_mfma_f32_16x16x32_bf16 v[42:45], v[148:151], v[180:183], v[42:45]
	v_mfma_f32_16x16x32_bf16 v[30:33], v[134:137], v[188:191], v[30:33]
	v_mfma_f32_16x16x32_bf16 v[26:29], v[148:151], v[188:191], v[26:29]
	v_mfma_f32_16x16x32_bf16 v[14:17], v[134:137], v[210:213], v[14:17]
	v_mfma_f32_16x16x32_bf16 v[10:13], v[148:151], v[210:213], v[10:13]
	v_mfma_f32_16x16x32_bf16 v[62:65], v[144:147], v[176:179], v[62:65]
	v_mfma_f32_16x16x32_bf16 v[58:61], v[152:155], v[176:179], v[58:61]
	v_mfma_f32_16x16x32_bf16 v[46:49], v[144:147], v[184:187], v[46:49]
	v_mfma_f32_16x16x32_bf16 v[42:45], v[152:155], v[184:187], v[42:45]
	v_mfma_f32_16x16x32_bf16 v[30:33], v[144:147], v[206:209], v[30:33]
	v_mfma_f32_16x16x32_bf16 v[26:29], v[152:155], v[206:209], v[26:29]
	v_mfma_f32_16x16x32_bf16 v[14:17], v[144:147], v[214:217], v[14:17]
	v_mfma_f32_16x16x32_bf16 v[10:13], v[152:155], v[214:217], v[10:13]
	s_setprio 0
	s_setprio 1
	v_mfma_f32_16x16x32_bf16 v[54:57], v[156:159], v[172:175], v[54:57]
	v_mfma_f32_16x16x32_bf16 v[50:53], v[164:167], v[172:175], v[50:53]
	v_mfma_f32_16x16x32_bf16 v[38:41], v[156:159], v[180:183], v[38:41]
	v_mfma_f32_16x16x32_bf16 v[34:37], v[164:167], v[180:183], v[34:37]
	v_mfma_f32_16x16x32_bf16 v[22:25], v[156:159], v[188:191], v[22:25]
	v_mfma_f32_16x16x32_bf16 v[18:21], v[164:167], v[188:191], v[18:21]
	v_mfma_f32_16x16x32_bf16 v[6:9], v[156:159], v[210:213], v[6:9]
	v_mfma_f32_16x16x32_bf16 v[2:5], v[164:167], v[210:213], v[2:5]
	v_mfma_f32_16x16x32_bf16 v[54:57], v[160:163], v[176:179], v[54:57]
	v_mfma_f32_16x16x32_bf16 v[50:53], v[168:171], v[176:179], v[50:53]
	v_mfma_f32_16x16x32_bf16 v[38:41], v[160:163], v[184:187], v[38:41]
	v_mfma_f32_16x16x32_bf16 v[34:37], v[168:171], v[184:187], v[34:37]
	v_mfma_f32_16x16x32_bf16 v[22:25], v[160:163], v[206:209], v[22:25]
	v_mfma_f32_16x16x32_bf16 v[18:21], v[168:171], v[206:209], v[18:21]
	v_mfma_f32_16x16x32_bf16 v[6:9], v[160:163], v[214:217], v[6:9]
	s_nop 1
	s_barrier
	v_mfma_f32_16x16x32_bf16 v[2:5], v[168:171], v[214:217], v[2:5]
	s_setprio 0
	s_add_i32 s33, 0, 0x18000
	v_add_u32_e32 v138, s33, v141
	s_add_i32 s64, 0, 0x1c000
	ds_read_b128 v[134:137], v138
	ds_read_b128 v[144:147], v138 offset:1024
	ds_read_b128 v[148:151], v138 offset:2048
	ds_read_b128 v[152:155], v138 offset:3072
	v_add_u32_e32 v138, s64, v141
	ds_read_b128 v[156:159], v138
	ds_read_b128 v[160:163], v138 offset:1024
	ds_read_b128 v[164:167], v138 offset:2048
	ds_read_b128 v[168:171], v138 offset:3072
	s_add_u32 s0, s34, 0x80000
	s_addc_u32 s1, s35, 0
	s_mov_b32 m0, s45
	v_lshl_add_u64 v[138:139], s[0:1], 0, v[130:131]
	ds_read_b128 v[172:175], v142 offset:32768
	ds_read_b128 v[176:179], v142 offset:33792
	ds_read_b128 v[180:183], v142 offset:34816
	ds_read_b128 v[184:187], v142 offset:35840
	ds_read_b128 v[188:191], v142 offset:36864
	ds_read_b128 v[206:209], v142 offset:37888
	ds_read_b128 v[210:213], v142 offset:38912
	ds_read_b128 v[214:217], v142 offset:39936
	global_load_lds_dwordx4 v[138:139], off
	v_lshl_add_u64 v[138:139], s[0:1], 0, v[132:133]
	s_mov_b32 m0, s46
	s_nop 0
	global_load_lds_dwordx4 v[138:139], off
	s_waitcnt vmcnt(8)
	s_waitcnt lgkmcnt(0)
	s_barrier
	s_setprio 1
	s_waitcnt lgkmcnt(0)
	v_mfma_f32_16x16x32_bf16 v[126:129], v[134:137], v[172:175], v[126:129]
	v_mfma_f32_16x16x32_bf16 v[122:125], v[148:151], v[172:175], v[122:125]
	v_mfma_f32_16x16x32_bf16 v[110:113], v[134:137], v[180:183], v[110:113]
	v_mfma_f32_16x16x32_bf16 v[106:109], v[148:151], v[180:183], v[106:109]
	v_mfma_f32_16x16x32_bf16 v[94:97], v[134:137], v[188:191], v[94:97]
	v_mfma_f32_16x16x32_bf16 v[90:93], v[148:151], v[188:191], v[90:93]
	v_mfma_f32_16x16x32_bf16 v[78:81], v[134:137], v[210:213], v[78:81]
	v_mfma_f32_16x16x32_bf16 v[74:77], v[148:151], v[210:213], v[74:77]
	v_mfma_f32_16x16x32_bf16 v[126:129], v[144:147], v[176:179], v[126:129]
	v_mfma_f32_16x16x32_bf16 v[122:125], v[152:155], v[176:179], v[122:125]
	v_mfma_f32_16x16x32_bf16 v[110:113], v[144:147], v[184:187], v[110:113]
	v_mfma_f32_16x16x32_bf16 v[106:109], v[152:155], v[184:187], v[106:109]
	v_mfma_f32_16x16x32_bf16 v[94:97], v[144:147], v[206:209], v[94:97]
	v_mfma_f32_16x16x32_bf16 v[90:93], v[152:155], v[206:209], v[90:93]
	v_mfma_f32_16x16x32_bf16 v[78:81], v[144:147], v[214:217], v[78:81]
	v_mfma_f32_16x16x32_bf16 v[74:77], v[152:155], v[214:217], v[74:77]
	s_setprio 0
	s_setprio 1
	v_mfma_f32_16x16x32_bf16 v[118:121], v[156:159], v[172:175], v[118:121]
	v_mfma_f32_16x16x32_bf16 v[114:117], v[164:167], v[172:175], v[114:117]
	v_mfma_f32_16x16x32_bf16 v[102:105], v[156:159], v[180:183], v[102:105]
	v_mfma_f32_16x16x32_bf16 v[98:101], v[164:167], v[180:183], v[98:101]
	v_mfma_f32_16x16x32_bf16 v[86:89], v[156:159], v[188:191], v[86:89]
	v_mfma_f32_16x16x32_bf16 v[82:85], v[164:167], v[188:191], v[82:85]
	v_mfma_f32_16x16x32_bf16 v[70:73], v[156:159], v[210:213], v[70:73]
	v_mfma_f32_16x16x32_bf16 v[66:69], v[164:167], v[210:213], v[66:69]
	v_mfma_f32_16x16x32_bf16 v[118:121], v[160:163], v[176:179], v[118:121]
	v_mfma_f32_16x16x32_bf16 v[114:117], v[168:171], v[176:179], v[114:117]
	v_mfma_f32_16x16x32_bf16 v[102:105], v[160:163], v[184:187], v[102:105]
	v_mfma_f32_16x16x32_bf16 v[98:101], v[168:171], v[184:187], v[98:101]
	v_mfma_f32_16x16x32_bf16 v[86:89], v[160:163], v[206:209], v[86:89]
	v_mfma_f32_16x16x32_bf16 v[82:85], v[168:171], v[206:209], v[82:85]
	v_mfma_f32_16x16x32_bf16 v[70:73], v[160:163], v[214:217], v[70:73]
	s_nop 1
	s_barrier
; #define PG8_STAGE(bufoff, gbase, voff) do { _Pragma("unroll") for (int _i = 0; _i < 2; ++_i) \
;         __builtin_amdgcn_global_load_lds((const unsigned*)((const char*)(gbase) + (voff)[_i]), (LAS unsigned*)(lds + (bufoff) + ldsw + _i * 8192), 16, 0, 0); } while (0)
; #define PG8_LDA(dst, b, h) do { _Pragma("unroll") for (int m = 0; m < 4; ++m) _Pragma("unroll") for (int k = 0; k < 2; ++k) dst[m][k] = *(const LAS bf16x8*)(lds + PG8_SA(b, h) + aoff + m * 2048 + k * 1024); } while (0)
; #define PG8_MMA(ai, bj, At, Bt) do { __builtin_amdgcn_s_setprio(1); _Pragma("unroll") for (int m = 0; m < 4; ++m) _Pragma("unroll") for (int n = 0; n < 2; ++n) _Pragma("unroll") for (int k = 0; k < 2; ++k) \
;         acc[ai][bj][m][n] = __builtin_amdgcn_mfma_f32_16x16x32_bf16(Bt[n][k], At[m][k], acc[ai][bj][m][n], 0, 0, 0); __builtin_amdgcn_s_setprio(0); } while (0)
; #define PG8_WAIT_V(n) asm volatile("s_waitcnt vmcnt(" #n ")" ::: "memory")
; #define PG8_WAIT_L(n) asm volatile("s_waitcnt lgkmcnt(" #n ")" ::: "memory")
; #define PG8_BAR __builtin_amdgcn_s_barrier()
; #define PG8_SCHED __builtin_amdgcn_sched_barrier(0)
; template <class Epi, bool ALIGN_EPI = true, bool SP2 = true>
; __device__ __forceinline__ void gemm_phase(LAS unsigned char* lds, const Gemm g, const StaticOrder& S, const Epi& E, unsigned long long& tacc, const int tmode) {
;     ...
;             PG8_WAIT_V(8); PG8_WAIT_L(0); PG8_BAR; PG8_MMA(0, 0, At, B0); PG8_MMA(0, 1, At, B1); PG8_BAR; PG8_SCHED;
;             PG8_LDA(At, 1, 1); PG8_STAGE(PG8_SB(1, 0), b3, voffB); PG8_STAGE(PG8_SB(1, 1), b3 + hstepB, voffB); PG8_STAGE(PG8_SA(1, 0), a3, voffA);
;             PG8_WAIT_V(8); PG8_WAIT_L(0); PG8_BAR; PG8_MMA(1, 0, At, B0); PG8_MMA(1, 1, At, B1); PG8_BAR; PG8_SCHED;
	v_mfma_f32_16x16x32_bf16 v[66:69], v[168:171], v[214:217], v[66:69]
	s_setprio 0
	s_add_u32 s0, s40, 0x4000
	s_addc_u32 s1, s41, 0
	s_add_i32 s33, s33, s42
	v_lshl_add_u64 v[138:139], s[0:1], 0, v[130:131]
	s_mov_b32 m0, s33
	ds_read_b128 v[172:175], v142 offset:49152
	ds_read_b128 v[176:179], v142 offset:50176
	ds_read_b128 v[180:183], v142 offset:51200
	ds_read_b128 v[184:187], v142 offset:52224
	ds_read_b128 v[188:191], v142 offset:53248
	ds_read_b128 v[206:209], v142 offset:54272
	ds_read_b128 v[210:213], v142 offset:55296
	ds_read_b128 v[214:217], v142 offset:56320
	global_load_lds_dwordx4 v[138:139], off
	s_add_i32 m0, s33, 0x2000
	v_lshl_add_u64 v[138:139], s[0:1], 0, v[132:133]
	s_add_u32 s0, s40, 0x84000
	s_addc_u32 s1, s41, 0
	s_add_i32 s33, s64, s42
	global_load_lds_dwordx4 v[138:139], off
	v_lshl_add_u64 v[138:139], s[0:1], 0, v[130:131]
	s_mov_b32 m0, s33
	s_nop 0
	global_load_lds_dwordx4 v[138:139], off
	v_lshl_add_u64 v[138:139], s[0:1], 0, v[132:133]
	s_add_i32 m0, s33, 0x2000
	s_nop 0
	global_load_lds_dwordx4 v[138:139], off
	v_lshl_add_u64 v[138:139], s[30:31], 0, v[130:131]
	s_mov_b32 m0, s49
	s_nop 0
	global_load_lds_dwordx4 v[138:139], off
	v_lshl_add_u64 v[138:139], s[30:31], 0, v[132:133]
	s_mov_b32 m0, s50
	s_nop 0
	global_load_lds_dwordx4 v[138:139], off
	s_waitcnt vmcnt(8)
	s_waitcnt lgkmcnt(0)
	s_barrier
	s_setprio 1
	s_waitcnt lgkmcnt(0)
	v_mfma_f32_16x16x32_bf16 v[62:65], v[134:137], v[172:175], v[62:65]
	v_mfma_f32_16x16x32_bf16 v[58:61], v[148:151], v[172:175], v[58:61]
	v_mfma_f32_16x16x32_bf16 v[46:49], v[134:137], v[180:183], v[46:49]
	v_mfma_f32_16x16x32_bf16 v[42:45], v[148:151], v[180:183], v[42:45]
	v_mfma_f32_16x16x32_bf16 v[30:33], v[134:137], v[188:191], v[30:33]
	v_mfma_f32_16x16x32_bf16 v[26:29], v[148:151], v[188:191], v[26:29]
	v_mfma_f32_16x16x32_bf16 v[14:17], v[134:137], v[210:213], v[14:17]
	v_mfma_f32_16x16x32_bf16 v[10:13], v[148:151], v[210:213], v[10:13]
	v_mfma_f32_16x16x32_bf16 v[62:65], v[144:147], v[176:179], v[62:65]
	v_mfma_f32_16x16x32_bf16 v[58:61], v[152:155], v[176:179], v[58:61]
	v_mfma_f32_16x16x32_bf16 v[46:49], v[144:147], v[184:187], v[46:49]
	v_mfma_f32_16x16x32_bf16 v[42:45], v[152:155], v[184:187], v[42:45]
	v_mfma_f32_16x16x32_bf16 v[30:33], v[144:147], v[206:209], v[30:33]
	v_mfma_f32_16x16x32_bf16 v[26:29], v[152:155], v[206:209], v[26:29]
	v_mfma_f32_16x16x32_bf16 v[14:17], v[144:147], v[214:217], v[14:17]
	v_mfma_f32_16x16x32_bf16 v[10:13], v[152:155], v[214:217], v[10:13]
	s_setprio 0
	s_setprio 1
	v_mfma_f32_16x16x32_bf16 v[54:57], v[156:159], v[172:175], v[54:57]
	v_mfma_f32_16x16x32_bf16 v[50:53], v[164:167], v[172:175], v[50:53]
	v_mfma_f32_16x16x32_bf16 v[38:41], v[156:159], v[180:183], v[38:41]
	v_mfma_f32_16x16x32_bf16 v[34:37], v[164:167], v[180:183], v[34:37]
	v_mfma_f32_16x16x32_bf16 v[22:25], v[156:159], v[188:191], v[22:25]
	v_mfma_f32_16x16x32_bf16 v[18:21], v[164:167], v[188:191], v[18:21]
	v_mfma_f32_16x16x32_bf16 v[6:9], v[156:159], v[210:213], v[6:9]
	v_mfma_f32_16x16x32_bf16 v[2:5], v[164:167], v[210:213], v[2:5]
	v_mfma_f32_16x16x32_bf16 v[54:57], v[160:163], v[176:179], v[54:57]
	v_mfma_f32_16x16x32_bf16 v[50:53], v[168:171], v[176:179], v[50:53]
	v_mfma_f32_16x16x32_bf16 v[38:41], v[160:163], v[184:187], v[38:41]
	v_mfma_f32_16x16x32_bf16 v[34:37], v[168:171], v[184:187], v[34:37]
	v_mfma_f32_16x16x32_bf16 v[22:25], v[160:163], v[206:209], v[22:25]
	v_mfma_f32_16x16x32_bf16 v[18:21], v[168:171], v[206:209], v[18:21]
	v_mfma_f32_16x16x32_bf16 v[6:9], v[160:163], v[214:217], v[6:9]
	s_nop 1
	s_barrier
	v_mfma_f32_16x16x32_bf16 v[2:5], v[168:171], v[214:217], v[2:5]
	s_setprio 0
	s_add_i32 s65, s65, 2
	s_add_u32 s22, s22, 0x8000
	s_addc_u32 s23, s23, 0
	s_add_u32 s60, s60, 0x8000
	s_addc_u32 s61, s61, 0
	s_cmp_lt_u32 s65, 30
	s_cbranch_scc1 .LBB0_739
	s_andn2_b64 vcc, exec, s[18:19]
	s_cbranch_vccnz .LBB0_742
	s_barrier

; #define PG8_STAGE(bufoff, gbase, voff) do { _Pragma("unroll") for (int _i = 0; _i < 2; ++_i) \
;         __builtin_amdgcn_global_load_lds((const unsigned*)((const char*)(gbase) + (voff)[_i]), (LAS unsigned*)(lds + (bufoff) + ldsw + _i * 8192), 16, 0, 0); } while (0)
; #define PG8_LDA(dst, b, h) do { _Pragma("unroll") for (int m = 0; m < 4; ++m) _Pragma("unroll") for (int k = 0; k < 2; ++k) dst[m][k] = *(const LAS bf16x8*)(lds + PG8_SA(b, h) + aoff + m * 2048 + k * 1024); } while (0)
; #define PG8_LDB(dst, b, h) do { _Pragma("unroll") for (int n = 0; n < 2; ++n) _Pragma("unroll") for (int k = 0; k < 2; ++k) dst[n][k] = *(const LAS bf16x8*)(lds + PG8_SB(b, h) + boff + n * 2048 + k * 1024); } while (0)
; #define PG8_MMA(ai, bj, At, Bt) do { __builtin_amdgcn_s_setprio(1); _Pragma("unroll") for (int m = 0; m < 4; ++m) _Pragma("unroll") for (int n = 0; n < 2; ++n) _Pragma("unroll") for (int k = 0; k < 2; ++k) \
;         acc[ai][bj][m][n] = __builtin_amdgcn_mfma_f32_16x16x32_bf16(Bt[n][k], At[m][k], acc[ai][bj][m][n], 0, 0, 0); __builtin_amdgcn_s_setprio(0); } while (0)
; #define PG8_WAIT_V(n) asm volatile("s_waitcnt vmcnt(" #n ")" ::: "memory")
; #define PG8_WAIT_L(n) asm volatile("s_waitcnt lgkmcnt(" #n ")" ::: "memory")
; template <class Epi, bool ALIGN_EPI = true, bool SP2 = true>
; __device__ __forceinline__ void gemm_phase(LAS unsigned char* lds, const Gemm g, const StaticOrder& S, const Epi& E, unsigned long long& tacc, const int tmode) {
;     ...
;         for (int t = 0; t < nt; t += 2) {
;             const bool last = (t == nt - 2);
;             const char* a1 = cA + (size_t)(t + 1) * kstepA;
;             const char* a2 = last ? nA : cA + (size_t)(t + 2) * kstepA; const char* b2 = last ? nB : cB + (size_t)(t + 2) * kstepB;
;             const char* a3 = a2 + kstepA; const char* b3 = b2 + kstepB;
;             if constexpr (SP2) {
;             PG8_LDB(B0, 0, 0); PG8_LDB(B1, 0, 1); PG8_SCHED; PG8_LDA(At, 0, 0); PG8_STAGE(PG8_SA(1, 1), a1 + hstepA, voffA);
;             PG8_WAIT_V(8); PG8_WAIT_L(0); PG8_BAR; PG8_MMA(0, 0, At, B0); PG8_MMA(0, 1, At, B1); PG8_BAR; PG8_SCHED;
;             PG8_LDA(At, 0, 1); PG8_STAGE(PG8_SB(0, 0), b2, voffB); PG8_STAGE(PG8_SB(0, 1), b2 + hstepB, voffB); PG8_STAGE(PG8_SA(0, 0), a2, voffA);
;             PG8_WAIT_V(8); PG8_WAIT_L(0); PG8_BAR; PG8_MMA(1, 0, At, B0); PG8_MMA(1, 1, At, B1); PG8_BAR; PG8_SCHED;
.LBB0_1045:
	s_add_i32 s1, s0, 2
	s_add_u32 s33, s20, s42
	s_addc_u32 s34, s21, s43
	s_add_i32 s64, 0, 0x10000
	s_cmp_eq_u32 s17, s0
	s_cselect_b32 s45, s23, s34
	s_cselect_b32 s44, s22, s33
	v_add_u32_e32 v149, s64, v147
	s_cselect_b32 s35, s31, vcc_lo
	s_cselect_b32 s34, s30, s37
	s_add_i32 s0, 0, 0x14000
	ds_read_b128 v[150:153], v149
	ds_read_b128 v[154:157], v149 offset:1024
	ds_read_b128 v[158:161], v149 offset:2048
	ds_read_b128 v[162:165], v149 offset:3072
	v_add_u32_e32 v149, s0, v147
	ds_read_b128 v[166:169], v149
	ds_read_b128 v[170:173], v149 offset:1024
	ds_read_b128 v[174:177], v149 offset:2048
	ds_read_b128 v[178:181], v149 offset:3072
	v_lshl_add_u64 v[190:191], s[20:21], 0, v[144:145]
	s_add_i32 m0, s57, 0xc000
	ds_read_b128 v[182:185], v148
	ds_read_b128 v[186:189], v148 offset:1024
	ds_read_b128 v[194:197], v148 offset:2048
	ds_read_b128 v[206:209], v148 offset:3072
	ds_read_b128 v[210:213], v148 offset:4096
	ds_read_b128 v[214:217], v148 offset:5120
	ds_read_b128 v[218:221], v148 offset:6144
	ds_read_b128 v[222:225], v148 offset:7168
	global_load_lds_dwordx4 v[190:191], off
	v_lshl_add_u64 v[190:191], s[20:21], 0, v[142:143]
	s_add_i32 m0, s57, 0xe000
	s_nop 0
	global_load_lds_dwordx4 v[190:191], off
	s_waitcnt vmcnt(8)
	s_waitcnt lgkmcnt(0)
	s_barrier
	s_setprio 1
	s_waitcnt lgkmcnt(0)
	v_mfma_f32_16x16x32_bf16 v[126:129], v[150:153], v[182:185], v[126:129]
	v_mfma_f32_16x16x32_bf16 v[122:125], v[158:161], v[182:185], v[122:125]
	v_mfma_f32_16x16x32_bf16 v[118:121], v[150:153], v[194:197], v[118:121]
	v_mfma_f32_16x16x32_bf16 v[110:113], v[158:161], v[194:197], v[110:113]
	v_mfma_f32_16x16x32_bf16 v[102:105], v[150:153], v[210:213], v[102:105]
	v_mfma_f32_16x16x32_bf16 v[94:97], v[158:161], v[210:213], v[94:97]
	v_mfma_f32_16x16x32_bf16 v[86:89], v[150:153], v[218:221], v[86:89]
	v_mfma_f32_16x16x32_bf16 v[78:81], v[158:161], v[218:221], v[78:81]
	v_mfma_f32_16x16x32_bf16 v[126:129], v[154:157], v[186:189], v[126:129]
	v_mfma_f32_16x16x32_bf16 v[122:125], v[162:165], v[186:189], v[122:125]
	v_mfma_f32_16x16x32_bf16 v[118:121], v[154:157], v[206:209], v[118:121]
	v_mfma_f32_16x16x32_bf16 v[110:113], v[162:165], v[206:209], v[110:113]
	v_mfma_f32_16x16x32_bf16 v[102:105], v[154:157], v[214:217], v[102:105]
	v_mfma_f32_16x16x32_bf16 v[94:97], v[162:165], v[214:217], v[94:97]
	v_mfma_f32_16x16x32_bf16 v[86:89], v[154:157], v[222:225], v[86:89]
	v_mfma_f32_16x16x32_bf16 v[78:81], v[162:165], v[222:225], v[78:81]
	s_setprio 0
	s_setprio 1
	v_mfma_f32_16x16x32_bf16 v[114:117], v[166:169], v[182:185], v[114:117]
	v_mfma_f32_16x16x32_bf16 v[106:109], v[174:177], v[182:185], v[106:109]
	v_mfma_f32_16x16x32_bf16 v[98:101], v[166:169], v[194:197], v[98:101]
	v_mfma_f32_16x16x32_bf16 v[90:93], v[174:177], v[194:197], v[90:93]
	v_mfma_f32_16x16x32_bf16 v[82:85], v[166:169], v[210:213], v[82:85]
	v_mfma_f32_16x16x32_bf16 v[74:77], v[174:177], v[210:213], v[74:77]
	v_mfma_f32_16x16x32_bf16 v[70:73], v[166:169], v[218:221], v[70:73]
	v_mfma_f32_16x16x32_bf16 v[66:69], v[174:177], v[218:221], v[66:69]
	v_mfma_f32_16x16x32_bf16 v[114:117], v[170:173], v[186:189], v[114:117]
	v_mfma_f32_16x16x32_bf16 v[106:109], v[178:181], v[186:189], v[106:109]
	v_mfma_f32_16x16x32_bf16 v[98:101], v[170:173], v[206:209], v[98:101]
	v_mfma_f32_16x16x32_bf16 v[90:93], v[178:181], v[206:209], v[90:93]
	v_mfma_f32_16x16x32_bf16 v[82:85], v[170:173], v[214:217], v[82:85]
	v_mfma_f32_16x16x32_bf16 v[74:77], v[178:181], v[214:217], v[74:77]
	v_mfma_f32_16x16x32_bf16 v[70:73], v[170:173], v[222:225], v[70:73]
	s_nop 1
	s_barrier
	v_mfma_f32_16x16x32_bf16 v[66:69], v[178:181], v[222:225], v[66:69]
	s_setprio 0
	s_add_i32 s33, s64, s55
	v_lshl_add_u64 v[190:191], s[34:35], 0, v[132:133]
	s_mov_b32 m0, s33
	ds_read_b128 v[182:185], v148 offset:16384
	ds_read_b128 v[186:189], v148 offset:17408
	ds_read_b128 v[194:197], v148 offset:18432
	ds_read_b128 v[206:209], v148 offset:19456
	ds_read_b128 v[210:213], v148 offset:20480
	ds_read_b128 v[214:217], v148 offset:21504
	ds_read_b128 v[218:221], v148 offset:22528
	ds_read_b128 v[222:225], v148 offset:23552
	global_load_lds_dwordx4 v[190:191], off
	s_add_i32 m0, s33, 0x2000
	s_add_u32 s66, s34, s54
	v_lshl_add_u64 v[190:191], s[34:35], 0, v[134:135]
	s_addc_u32 s67, s35, 0
	s_add_i32 s0, s0, s55
	global_load_lds_dwordx4 v[190:191], off
	v_lshl_add_u64 v[190:191], s[66:67], 0, v[132:133]
	s_mov_b32 m0, s0
	v_lshl_add_u64 v[236:237], s[44:45], 0, v[136:137]
	global_load_lds_dwordx4 v[190:191], off
	v_lshl_add_u64 v[190:191], s[66:67], 0, v[134:135]
	s_add_i32 m0, s0, 0x2000
	s_nop 0
	global_load_lds_dwordx4 v[190:191], off
	v_lshl_add_u64 v[190:191], s[44:45], 0, v[130:131]
	s_mov_b32 m0, s57
	s_nop 0
	global_load_lds_dwordx4 v[190:191], off
	s_mov_b32 m0, s60
	s_nop 0
	global_load_lds_dwordx4 v[236:237], off
	s_waitcnt vmcnt(8)
	s_waitcnt lgkmcnt(0)
	s_barrier
; #define PG8_STAGE(bufoff, gbase, voff) do { _Pragma("unroll") for (int _i = 0; _i < 2; ++_i) \
;         __builtin_amdgcn_global_load_lds((const unsigned*)((const char*)(gbase) + (voff)[_i]), (LAS unsigned*)(lds + (bufoff) + ldsw + _i * 8192), 16, 0, 0); } while (0)
; #define PG8_LDA(dst, b, h) do { _Pragma("unroll") for (int m = 0; m < 4; ++m) _Pragma("unroll") for (int k = 0; k < 2; ++k) dst[m][k] = *(const LAS bf16x8*)(lds + PG8_SA(b, h) + aoff + m * 2048 + k * 1024); } while (0)
; #define PG8_LDB(dst, b, h) do { _Pragma("unroll") for (int n = 0; n < 2; ++n) _Pragma("unroll") for (int k = 0; k < 2; ++k) dst[n][k] = *(const LAS bf16x8*)(lds + PG8_SB(b, h) + boff + n * 2048 + k * 1024); } while (0)
; #define PG8_MMA(ai, bj, At, Bt) do { __builtin_amdgcn_s_setprio(1); _Pragma("unroll") for (int m = 0; m < 4; ++m) _Pragma("unroll") for (int n = 0; n < 2; ++n) _Pragma("unroll") for (int k = 0; k < 2; ++k) \
;         acc[ai][bj][m][n] = __builtin_amdgcn_mfma_f32_16x16x32_bf16(Bt[n][k], At[m][k], acc[ai][bj][m][n], 0, 0, 0); __builtin_amdgcn_s_setprio(0); } while (0)
; #define PG8_WAIT_V(n) asm volatile("s_waitcnt vmcnt(" #n ")" ::: "memory")
; #define PG8_WAIT_L(n) asm volatile("s_waitcnt lgkmcnt(" #n ")" ::: "memory")
; #define PG8_BAR __builtin_amdgcn_s_barrier()
; #define PG8_SCHED __builtin_amdgcn_sched_barrier(0)
; template <class Epi, bool ALIGN_EPI = true, bool SP2 = true>
; __device__ __forceinline__ void gemm_phase(LAS unsigned char* lds, const Gemm g, const StaticOrder& S, const Epi& E, unsigned long long& tacc, const int tmode) {
;     ...
;             PG8_WAIT_V(8); PG8_WAIT_L(0); PG8_BAR; PG8_MMA(1, 0, At, B0); PG8_MMA(1, 1, At, B1); PG8_BAR; PG8_SCHED;
;             PG8_LDB(B0, 1, 0); PG8_LDB(B1, 1, 1); PG8_SCHED; PG8_LDA(At, 1, 0); PG8_STAGE(PG8_SA(0, 1), a2 + hstepA, voffA);
;             PG8_WAIT_V(8); PG8_WAIT_L(0); PG8_BAR; PG8_MMA(0, 0, At, B0); PG8_MMA(0, 1, At, B1); PG8_BAR; PG8_SCHED;
	s_setprio 1
	s_waitcnt lgkmcnt(0)
	v_mfma_f32_16x16x32_bf16 v[62:65], v[150:153], v[182:185], v[62:65]
	v_mfma_f32_16x16x32_bf16 v[58:61], v[158:161], v[182:185], v[58:61]
	v_mfma_f32_16x16x32_bf16 v[54:57], v[150:153], v[194:197], v[54:57]
	v_mfma_f32_16x16x32_bf16 v[46:49], v[158:161], v[194:197], v[46:49]
	v_mfma_f32_16x16x32_bf16 v[38:41], v[150:153], v[210:213], v[38:41]
	v_mfma_f32_16x16x32_bf16 v[30:33], v[158:161], v[210:213], v[30:33]
	v_mfma_f32_16x16x32_bf16 v[22:25], v[150:153], v[218:221], v[22:25]
	v_mfma_f32_16x16x32_bf16 v[14:17], v[158:161], v[218:221], v[14:17]
	v_mfma_f32_16x16x32_bf16 v[62:65], v[154:157], v[186:189], v[62:65]
	v_mfma_f32_16x16x32_bf16 v[58:61], v[162:165], v[186:189], v[58:61]
	v_mfma_f32_16x16x32_bf16 v[54:57], v[154:157], v[206:209], v[54:57]
	v_mfma_f32_16x16x32_bf16 v[46:49], v[162:165], v[206:209], v[46:49]
	v_mfma_f32_16x16x32_bf16 v[38:41], v[154:157], v[214:217], v[38:41]
	v_mfma_f32_16x16x32_bf16 v[30:33], v[162:165], v[214:217], v[30:33]
	v_mfma_f32_16x16x32_bf16 v[22:25], v[154:157], v[222:225], v[22:25]
	v_mfma_f32_16x16x32_bf16 v[14:17], v[162:165], v[222:225], v[14:17]
	s_setprio 0
	s_setprio 1
	v_mfma_f32_16x16x32_bf16 v[50:53], v[166:169], v[182:185], v[50:53]
	v_mfma_f32_16x16x32_bf16 v[42:45], v[174:177], v[182:185], v[42:45]
	v_mfma_f32_16x16x32_bf16 v[34:37], v[166:169], v[194:197], v[34:37]
	v_mfma_f32_16x16x32_bf16 v[26:29], v[174:177], v[194:197], v[26:29]
	v_mfma_f32_16x16x32_bf16 v[18:21], v[166:169], v[210:213], v[18:21]
	v_mfma_f32_16x16x32_bf16 v[10:13], v[174:177], v[210:213], v[10:13]
	v_mfma_f32_16x16x32_bf16 v[6:9], v[166:169], v[218:221], v[6:9]
	v_mfma_f32_16x16x32_bf16 v[2:5], v[174:177], v[218:221], v[2:5]
	v_mfma_f32_16x16x32_bf16 v[50:53], v[170:173], v[186:189], v[50:53]
	v_mfma_f32_16x16x32_bf16 v[42:45], v[178:181], v[186:189], v[42:45]
	v_mfma_f32_16x16x32_bf16 v[34:37], v[170:173], v[206:209], v[34:37]
	v_mfma_f32_16x16x32_bf16 v[26:29], v[178:181], v[206:209], v[26:29]
	v_mfma_f32_16x16x32_bf16 v[18:21], v[170:173], v[214:217], v[18:21]
	v_mfma_f32_16x16x32_bf16 v[10:13], v[178:181], v[214:217], v[10:13]
	v_mfma_f32_16x16x32_bf16 v[6:9], v[170:173], v[222:225], v[6:9]
	s_nop 1
	s_barrier
	v_mfma_f32_16x16x32_bf16 v[2:5], v[178:181], v[222:225], v[2:5]
	s_setprio 0
	s_add_i32 s0, 0, 0x18000
	v_add_u32_e32 v149, s0, v147
	s_add_i32 s33, 0, 0x1c000
	ds_read_b128 v[150:153], v149
	ds_read_b128 v[154:157], v149 offset:1024
	ds_read_b128 v[158:161], v149 offset:2048
	ds_read_b128 v[162:165], v149 offset:3072
	v_add_u32_e32 v149, s33, v147
	ds_read_b128 v[166:169], v149
	ds_read_b128 v[170:173], v149 offset:1024
	ds_read_b128 v[174:177], v149 offset:2048
	ds_read_b128 v[178:181], v149 offset:3072
	s_add_u32 s44, s44, s51
	s_addc_u32 s45, s45, 0
	s_mov_b32 m0, s61
	v_lshl_add_u64 v[238:239], s[44:45], 0, v[130:131]
	ds_read_b128 v[182:185], v148 offset:32768
	ds_read_b128 v[186:189], v148 offset:33792
	ds_read_b128 v[194:197], v148 offset:34816
	ds_read_b128 v[206:209], v148 offset:35840
	ds_read_b128 v[210:213], v148 offset:36864
	ds_read_b128 v[214:217], v148 offset:37888
	ds_read_b128 v[218:221], v148 offset:38912
	ds_read_b128 v[222:225], v148 offset:39936
	global_load_lds_dwordx4 v[238:239], off
	v_lshl_add_u64 v[238:239], s[44:45], 0, v[136:137]
	s_mov_b32 m0, s65
	s_nop 0
	global_load_lds_dwordx4 v[238:239], off
	s_waitcnt vmcnt(8)
	s_waitcnt lgkmcnt(0)
	s_barrier
	s_setprio 1
	s_waitcnt lgkmcnt(0)
	v_mfma_f32_16x16x32_bf16 v[126:129], v[150:153], v[182:185], v[126:129]
	v_mfma_f32_16x16x32_bf16 v[122:125], v[158:161], v[182:185], v[122:125]
	v_mfma_f32_16x16x32_bf16 v[118:121], v[150:153], v[194:197], v[118:121]
	v_mfma_f32_16x16x32_bf16 v[110:113], v[158:161], v[194:197], v[110:113]
	v_mfma_f32_16x16x32_bf16 v[102:105], v[150:153], v[210:213], v[102:105]
	v_mfma_f32_16x16x32_bf16 v[94:97], v[158:161], v[210:213], v[94:97]
	v_mfma_f32_16x16x32_bf16 v[86:89], v[150:153], v[218:221], v[86:89]
	v_mfma_f32_16x16x32_bf16 v[78:81], v[158:161], v[218:221], v[78:81]
	v_mfma_f32_16x16x32_bf16 v[126:129], v[154:157], v[186:189], v[126:129]
	v_mfma_f32_16x16x32_bf16 v[122:125], v[162:165], v[186:189], v[122:125]
	v_mfma_f32_16x16x32_bf16 v[118:121], v[154:157], v[206:209], v[118:121]
	v_mfma_f32_16x16x32_bf16 v[110:113], v[162:165], v[206:209], v[110:113]
	v_mfma_f32_16x16x32_bf16 v[102:105], v[154:157], v[214:217], v[102:105]
	v_mfma_f32_16x16x32_bf16 v[94:97], v[162:165], v[214:217], v[94:97]
	v_mfma_f32_16x16x32_bf16 v[86:89], v[154:157], v[222:225], v[86:89]
	v_mfma_f32_16x16x32_bf16 v[78:81], v[162:165], v[222:225], v[78:81]
	s_setprio 0
	s_setprio 1
	v_mfma_f32_16x16x32_bf16 v[114:117], v[166:169], v[182:185], v[114:117]
	v_mfma_f32_16x16x32_bf16 v[106:109], v[174:177], v[182:185], v[106:109]
	v_mfma_f32_16x16x32_bf16 v[98:101], v[166:169], v[194:197], v[98:101]
	v_mfma_f32_16x16x32_bf16 v[90:93], v[174:177], v[194:197], v[90:93]
	v_mfma_f32_16x16x32_bf16 v[82:85], v[166:169], v[210:213], v[82:85]
	v_mfma_f32_16x16x32_bf16 v[74:77], v[174:177], v[210:213], v[74:77]
	v_mfma_f32_16x16x32_bf16 v[70:73], v[166:169], v[218:221], v[70:73]
	v_mfma_f32_16x16x32_bf16 v[66:69], v[174:177], v[218:221], v[66:69]
	v_mfma_f32_16x16x32_bf16 v[114:117], v[170:173], v[186:189], v[114:117]
	v_mfma_f32_16x16x32_bf16 v[106:109], v[178:181], v[186:189], v[106:109]
	v_mfma_f32_16x16x32_bf16 v[98:101], v[170:173], v[206:209], v[98:101]
	v_mfma_f32_16x16x32_bf16 v[90:93], v[178:181], v[206:209], v[90:93]
	v_mfma_f32_16x16x32_bf16 v[82:85], v[170:173], v[214:217], v[82:85]
	v_mfma_f32_16x16x32_bf16 v[74:77], v[178:181], v[214:217], v[74:77]
	v_mfma_f32_16x16x32_bf16 v[70:73], v[170:173], v[222:225], v[70:73]
	s_nop 1
	s_barrier
; #define PG8_STAGE(bufoff, gbase, voff) do { _Pragma("unroll") for (int _i = 0; _i < 2; ++_i) \
;         __builtin_amdgcn_global_load_lds((const unsigned*)((const char*)(gbase) + (voff)[_i]), (LAS unsigned*)(lds + (bufoff) + ldsw + _i * 8192), 16, 0, 0); } while (0)
; #define PG8_LDA(dst, b, h) do { _Pragma("unroll") for (int m = 0; m < 4; ++m) _Pragma("unroll") for (int k = 0; k < 2; ++k) dst[m][k] = *(const LAS bf16x8*)(lds + PG8_SA(b, h) + aoff + m * 2048 + k * 1024); } while (0)
; #define PG8_MMA(ai, bj, At, Bt) do { __builtin_amdgcn_s_setprio(1); _Pragma("unroll") for (int m = 0; m < 4; ++m) _Pragma("unroll") for (int n = 0; n < 2; ++n) _Pragma("unroll") for (int k = 0; k < 2; ++k) \
;         acc[ai][bj][m][n] = __builtin_amdgcn_mfma_f32_16x16x32_bf16(Bt[n][k], At[m][k], acc[ai][bj][m][n], 0, 0, 0); __builtin_amdgcn_s_setprio(0); } while (0)
; #define PG8_WAIT_V(n) asm volatile("s_waitcnt vmcnt(" #n ")" ::: "memory")
; #define PG8_WAIT_L(n) asm volatile("s_waitcnt lgkmcnt(" #n ")" ::: "memory")
; #define PG8_BAR __builtin_amdgcn_s_barrier()
; #define PG8_SCHED __builtin_amdgcn_sched_barrier(0)
; template <class Epi, bool ALIGN_EPI = true, bool SP2 = true>
; __device__ __forceinline__ void gemm_phase(LAS unsigned char* lds, const Gemm g, const StaticOrder& S, const Epi& E, unsigned long long& tacc, const int tmode) {
;     ...
;             PG8_WAIT_V(8); PG8_WAIT_L(0); PG8_BAR; PG8_MMA(0, 0, At, B0); PG8_MMA(0, 1, At, B1); PG8_BAR; PG8_SCHED;
;             PG8_LDA(At, 1, 1); PG8_STAGE(PG8_SB(1, 0), b3, voffB); PG8_STAGE(PG8_SB(1, 1), b3 + hstepB, voffB); PG8_STAGE(PG8_SA(1, 0), a3, voffA);
;             PG8_WAIT_V(8); PG8_WAIT_L(0); PG8_BAR; PG8_MMA(1, 0, At, B0); PG8_MMA(1, 1, At, B1); PG8_BAR; PG8_SCHED;
	v_mfma_f32_16x16x32_bf16 v[66:69], v[178:181], v[222:225], v[66:69]
	s_setprio 0
	s_add_u32 s34, s34, 0x4000
	s_addc_u32 s35, s35, 0
	s_add_i32 s0, s0, s55
	v_lshl_add_u64 v[238:239], s[34:35], 0, v[132:133]
	s_mov_b32 m0, s0
	ds_read_b128 v[182:185], v148 offset:49152
	ds_read_b128 v[186:189], v148 offset:50176
	ds_read_b128 v[194:197], v148 offset:51200
	ds_read_b128 v[206:209], v148 offset:52224
	ds_read_b128 v[210:213], v148 offset:53248
	ds_read_b128 v[214:217], v148 offset:54272
	ds_read_b128 v[218:221], v148 offset:55296
	ds_read_b128 v[222:225], v148 offset:56320
	global_load_lds_dwordx4 v[238:239], off
	s_add_i32 m0, s0, 0x2000
	v_lshl_add_u64 v[238:239], s[34:35], 0, v[134:135]
	s_add_u32 s34, s34, s54
	s_addc_u32 s35, s35, 0
	s_add_i32 s0, s33, s55
	global_load_lds_dwordx4 v[238:239], off
	v_lshl_add_u64 v[238:239], s[34:35], 0, v[132:133]
	s_mov_b32 m0, s0
	v_lshl_add_u64 v[190:191], v[190:191], 0, s[4:5]
	global_load_lds_dwordx4 v[238:239], off
	v_lshl_add_u64 v[238:239], s[34:35], 0, v[134:135]
	s_add_i32 m0, s0, 0x2000
	s_nop 0
	global_load_lds_dwordx4 v[238:239], off
	s_mov_b32 m0, s72
	s_nop 0
	global_load_lds_dwordx4 v[190:191], off
	v_lshl_add_u64 v[190:191], v[236:237], 0, s[4:5]
	s_mov_b32 m0, s73
	s_nop 0
	global_load_lds_dwordx4 v[190:191], off
	s_waitcnt vmcnt(8)
	s_waitcnt lgkmcnt(0)
	s_barrier
	s_setprio 1
	s_waitcnt lgkmcnt(0)
	v_mfma_f32_16x16x32_bf16 v[62:65], v[150:153], v[182:185], v[62:65]
	v_mfma_f32_16x16x32_bf16 v[58:61], v[158:161], v[182:185], v[58:61]
	v_mfma_f32_16x16x32_bf16 v[54:57], v[150:153], v[194:197], v[54:57]
	v_mfma_f32_16x16x32_bf16 v[46:49], v[158:161], v[194:197], v[46:49]
	v_mfma_f32_16x16x32_bf16 v[38:41], v[150:153], v[210:213], v[38:41]
	v_mfma_f32_16x16x32_bf16 v[30:33], v[158:161], v[210:213], v[30:33]
	v_mfma_f32_16x16x32_bf16 v[22:25], v[150:153], v[218:221], v[22:25]
	v_mfma_f32_16x16x32_bf16 v[14:17], v[158:161], v[218:221], v[14:17]
	v_mfma_f32_16x16x32_bf16 v[62:65], v[154:157], v[186:189], v[62:65]
	v_mfma_f32_16x16x32_bf16 v[58:61], v[162:165], v[186:189], v[58:61]
	v_mfma_f32_16x16x32_bf16 v[54:57], v[154:157], v[206:209], v[54:57]
	v_mfma_f32_16x16x32_bf16 v[46:49], v[162:165], v[206:209], v[46:49]
	v_mfma_f32_16x16x32_bf16 v[38:41], v[154:157], v[214:217], v[38:41]
	v_mfma_f32_16x16x32_bf16 v[30:33], v[162:165], v[214:217], v[30:33]
	v_mfma_f32_16x16x32_bf16 v[22:25], v[154:157], v[222:225], v[22:25]
	v_mfma_f32_16x16x32_bf16 v[14:17], v[162:165], v[222:225], v[14:17]
	s_setprio 0
	s_setprio 1
	v_mfma_f32_16x16x32_bf16 v[50:53], v[166:169], v[182:185], v[50:53]
	v_mfma_f32_16x16x32_bf16 v[42:45], v[174:177], v[182:185], v[42:45]
	v_mfma_f32_16x16x32_bf16 v[34:37], v[166:169], v[194:197], v[34:37]
	v_mfma_f32_16x16x32_bf16 v[26:29], v[174:177], v[194:197], v[26:29]
	v_mfma_f32_16x16x32_bf16 v[18:21], v[166:169], v[210:213], v[18:21]
	v_mfma_f32_16x16x32_bf16 v[10:13], v[174:177], v[210:213], v[10:13]
	v_mfma_f32_16x16x32_bf16 v[6:9], v[166:169], v[218:221], v[6:9]
	v_mfma_f32_16x16x32_bf16 v[2:5], v[174:177], v[218:221], v[2:5]
	v_mfma_f32_16x16x32_bf16 v[50:53], v[170:173], v[186:189], v[50:53]
	v_mfma_f32_16x16x32_bf16 v[42:45], v[178:181], v[186:189], v[42:45]
	v_mfma_f32_16x16x32_bf16 v[34:37], v[170:173], v[206:209], v[34:37]
	v_mfma_f32_16x16x32_bf16 v[26:29], v[178:181], v[206:209], v[26:29]
	v_mfma_f32_16x16x32_bf16 v[18:21], v[170:173], v[214:217], v[18:21]
	v_mfma_f32_16x16x32_bf16 v[10:13], v[178:181], v[214:217], v[10:13]
	v_mfma_f32_16x16x32_bf16 v[6:9], v[170:173], v[222:225], v[6:9]
	s_nop 1
	s_barrier
	v_mfma_f32_16x16x32_bf16 v[2:5], v[178:181], v[222:225], v[2:5]
	s_setprio 0
	s_add_u32 s37, s37, 0x8000
	s_addc_u32 vcc_lo, vcc_lo, 0
	s_add_u32 s42, s42, 0x100
	s_addc_u32 s43, s43, 0
	v_lshl_add_u64 v[144:145], v[144:145], 0, s[58:59]
	v_lshl_add_u64 v[142:143], v[142:143], 0, s[58:59]
	s_cmp_lt_u32 s1, s50
	s_mov_b32 s0, s1
	s_cbranch_scc1 .LBB0_1045
	s_andn2_b64 vcc, exec, s[28:29]
	s_cbranch_vccnz .LBB0_1048
	s_barrier

; #define PG8_STAGE(bufoff, gbase, voff) do { _Pragma("unroll") for (int _i = 0; _i < 2; ++_i) \
;         __builtin_amdgcn_global_load_lds((const unsigned*)((const char*)(gbase) + (voff)[_i]), (LAS unsigned*)(lds + (bufoff) + ldsw + _i * 8192), 16, 0, 0); } while (0)
; #define PG8_LDA(dst, b, h) do { _Pragma("unroll") for (int m = 0; m < 4; ++m) _Pragma("unroll") for (int k = 0; k < 2; ++k) dst[m][k] = *(const LAS bf16x8*)(lds + PG8_SA(b, h) + aoff + m * 2048 + k * 1024); } while (0)
; #define PG8_LDB(dst, b, h) do { _Pragma("unroll") for (int n = 0; n < 2; ++n) _Pragma("unroll") for (int k = 0; k < 2; ++k) dst[n][k] = *(const LAS bf16x8*)(lds + PG8_SB(b, h) + boff + n * 2048 + k * 1024); } while (0)
; #define PG8_MMA(ai, bj, At, Bt) do { __builtin_amdgcn_s_setprio(1); _Pragma("unroll") for (int m = 0; m < 4; ++m) _Pragma("unroll") for (int n = 0; n < 2; ++n) _Pragma("unroll") for (int k = 0; k < 2; ++k) \
;         acc[ai][bj][m][n] = __builtin_amdgcn_mfma_f32_16x16x32_bf16(Bt[n][k], At[m][k], acc[ai][bj][m][n], 0, 0, 0); __builtin_amdgcn_s_setprio(0); } while (0)
; #define PG8_WAIT_V(n) asm volatile("s_waitcnt vmcnt(" #n ")" ::: "memory")
; #define PG8_WAIT_L(n) asm volatile("s_waitcnt lgkmcnt(" #n ")" ::: "memory")
; template <class Epi, bool ALIGN_EPI = true, bool SP2 = true>
; __device__ __forceinline__ void gemm_phase(LAS unsigned char* lds, const Gemm g, const StaticOrder& S, const Epi& E, unsigned long long& tacc, const int tmode) {
;     ...
;         for (int t = 0; t < nt; t += 2) {
;             const bool last = (t == nt - 2);
;             const char* a1 = cA + (size_t)(t + 1) * kstepA;
;             const char* a2 = last ? nA : cA + (size_t)(t + 2) * kstepA; const char* b2 = last ? nB : cB + (size_t)(t + 2) * kstepB;
;             const char* a3 = a2 + kstepA; const char* b3 = b2 + kstepB;
;             if constexpr (SP2) {
;             PG8_LDB(B0, 0, 0); PG8_LDB(B1, 0, 1); PG8_SCHED; PG8_LDA(At, 0, 0); PG8_STAGE(PG8_SA(1, 1), a1 + hstepA, voffA);
;             PG8_WAIT_V(8); PG8_WAIT_L(0); PG8_BAR; PG8_MMA(0, 0, At, B0); PG8_MMA(0, 1, At, B1); PG8_BAR; PG8_SCHED;
;             PG8_LDA(At, 0, 1); PG8_STAGE(PG8_SB(0, 0), b2, voffB); PG8_STAGE(PG8_SB(0, 1), b2 + hstepB, voffB); PG8_STAGE(PG8_SA(0, 0), a2, voffA);
;             PG8_WAIT_V(8); PG8_WAIT_L(0); PG8_BAR; PG8_MMA(1, 0, At, B0); PG8_MMA(1, 1, At, B1); PG8_BAR; PG8_SCHED;
.LBB0_1154:
	s_add_u32 s0, s22, 0xfff84000
	s_addc_u32 s1, s23, -1
	s_cmp_eq_u32 s61, 28
	s_cselect_b32 s34, s55, s0
	s_cselect_b32 s35, s25, s1
	s_cselect_b32 s40, s56, s57
	s_cselect_b32 s41, s21, s60
	s_add_u32 s30, s34, 0x4000
	s_addc_u32 s31, s35, 0
	s_add_i32 s0, 0, 0x10000
	v_add_u32_e32 v130, s0, v137
	s_add_i32 s33, 0, 0x14000
	ds_read_b128 v[140:143], v130
	ds_read_b128 v[144:147], v130 offset:1024
	ds_read_b128 v[148:151], v130 offset:2048
	ds_read_b128 v[152:155], v130 offset:3072
	v_add_u32_e32 v130, s33, v137
	ds_read_b128 v[156:159], v130
	ds_read_b128 v[160:163], v130 offset:1024
	ds_read_b128 v[164:167], v130 offset:2048
	ds_read_b128 v[168:171], v130 offset:3072
	v_lshl_add_u64 v[214:215], s[22:23], 0, v[132:133]
	s_add_i32 m0, s44, 0xc000
	ds_read_b128 v[172:175], v138
	ds_read_b128 v[176:179], v138 offset:1024
	ds_read_b128 v[180:183], v138 offset:2048
	ds_read_b128 v[184:187], v138 offset:3072
	ds_read_b128 v[188:191], v138 offset:4096
	ds_read_b128 v[194:197], v138 offset:5120
	ds_read_b128 v[206:209], v138 offset:6144
	ds_read_b128 v[210:213], v138 offset:7168
	global_load_lds_dwordx4 v[214:215], off
	v_lshl_add_u64 v[214:215], s[22:23], 0, v[134:135]
	s_add_i32 m0, s44, 0xe000
	s_nop 0
	global_load_lds_dwordx4 v[214:215], off
	s_waitcnt vmcnt(8)
	s_waitcnt lgkmcnt(0)
	s_barrier
	s_setprio 1
	s_waitcnt lgkmcnt(0)
	v_mfma_f32_16x16x32_bf16 v[126:129], v[140:143], v[172:175], v[126:129]
	v_mfma_f32_16x16x32_bf16 v[122:125], v[148:151], v[172:175], v[122:125]
	v_mfma_f32_16x16x32_bf16 v[110:113], v[140:143], v[180:183], v[110:113]
	v_mfma_f32_16x16x32_bf16 v[106:109], v[148:151], v[180:183], v[106:109]
	v_mfma_f32_16x16x32_bf16 v[94:97], v[140:143], v[188:191], v[94:97]
	v_mfma_f32_16x16x32_bf16 v[90:93], v[148:151], v[188:191], v[90:93]
	v_mfma_f32_16x16x32_bf16 v[78:81], v[140:143], v[206:209], v[78:81]
	v_mfma_f32_16x16x32_bf16 v[74:77], v[148:151], v[206:209], v[74:77]
	v_mfma_f32_16x16x32_bf16 v[126:129], v[144:147], v[176:179], v[126:129]
	v_mfma_f32_16x16x32_bf16 v[122:125], v[152:155], v[176:179], v[122:125]
	v_mfma_f32_16x16x32_bf16 v[110:113], v[144:147], v[184:187], v[110:113]
	v_mfma_f32_16x16x32_bf16 v[106:109], v[152:155], v[184:187], v[106:109]
	v_mfma_f32_16x16x32_bf16 v[94:97], v[144:147], v[194:197], v[94:97]
	v_mfma_f32_16x16x32_bf16 v[90:93], v[152:155], v[194:197], v[90:93]
	v_mfma_f32_16x16x32_bf16 v[78:81], v[144:147], v[210:213], v[78:81]
	v_mfma_f32_16x16x32_bf16 v[74:77], v[152:155], v[210:213], v[74:77]
	s_setprio 0
	s_setprio 1
	v_mfma_f32_16x16x32_bf16 v[118:121], v[156:159], v[172:175], v[118:121]
	v_mfma_f32_16x16x32_bf16 v[114:117], v[164:167], v[172:175], v[114:117]
	v_mfma_f32_16x16x32_bf16 v[102:105], v[156:159], v[180:183], v[102:105]
	v_mfma_f32_16x16x32_bf16 v[98:101], v[164:167], v[180:183], v[98:101]
	v_mfma_f32_16x16x32_bf16 v[86:89], v[156:159], v[188:191], v[86:89]
	v_mfma_f32_16x16x32_bf16 v[82:85], v[164:167], v[188:191], v[82:85]
	v_mfma_f32_16x16x32_bf16 v[70:73], v[156:159], v[206:209], v[70:73]
	v_mfma_f32_16x16x32_bf16 v[66:69], v[164:167], v[206:209], v[66:69]
	v_mfma_f32_16x16x32_bf16 v[118:121], v[160:163], v[176:179], v[118:121]
	v_mfma_f32_16x16x32_bf16 v[114:117], v[168:171], v[176:179], v[114:117]
	v_mfma_f32_16x16x32_bf16 v[102:105], v[160:163], v[184:187], v[102:105]
	v_mfma_f32_16x16x32_bf16 v[98:101], v[168:171], v[184:187], v[98:101]
	v_mfma_f32_16x16x32_bf16 v[86:89], v[160:163], v[194:197], v[86:89]
	v_mfma_f32_16x16x32_bf16 v[82:85], v[168:171], v[194:197], v[82:85]
	v_mfma_f32_16x16x32_bf16 v[70:73], v[160:163], v[210:213], v[70:73]
	s_nop 1
	s_barrier
	v_mfma_f32_16x16x32_bf16 v[66:69], v[168:171], v[210:213], v[66:69]
	s_setprio 0
	s_add_i32 s0, s0, s43
	v_lshl_add_u64 v[214:215], s[40:41], 0, v[132:133]
	s_mov_b32 m0, s0
	ds_read_b128 v[172:175], v138 offset:16384
	ds_read_b128 v[176:179], v138 offset:17408
	ds_read_b128 v[180:183], v138 offset:18432
	ds_read_b128 v[184:187], v138 offset:19456
	ds_read_b128 v[188:191], v138 offset:20480
	ds_read_b128 v[194:197], v138 offset:21504
	ds_read_b128 v[206:209], v138 offset:22528
	ds_read_b128 v[210:213], v138 offset:23552
	global_load_lds_dwordx4 v[214:215], off
	s_add_i32 m0, s0, 0x2000
	s_add_u32 s0, s40, 0x80000
	v_lshl_add_u64 v[214:215], s[40:41], 0, v[134:135]
	s_addc_u32 s1, s41, 0
	s_add_i32 s33, s33, s43
	global_load_lds_dwordx4 v[214:215], off
	v_lshl_add_u64 v[214:215], s[0:1], 0, v[132:133]
	s_mov_b32 m0, s33
	s_nop 0
	global_load_lds_dwordx4 v[214:215], off
	v_lshl_add_u64 v[214:215], s[0:1], 0, v[134:135]
	s_add_i32 m0, s33, 0x2000
	s_nop 0
	global_load_lds_dwordx4 v[214:215], off
	v_lshl_add_u64 v[214:215], s[34:35], 0, v[132:133]
	s_mov_b32 m0, s44
	s_nop 0
	global_load_lds_dwordx4 v[214:215], off
	v_lshl_add_u64 v[214:215], s[34:35], 0, v[134:135]
	s_mov_b32 m0, s45
	s_nop 0
	global_load_lds_dwordx4 v[214:215], off
	s_waitcnt vmcnt(8)
	s_waitcnt lgkmcnt(0)
	s_barrier
; #define PG8_STAGE(bufoff, gbase, voff) do { _Pragma("unroll") for (int _i = 0; _i < 2; ++_i) \
;         __builtin_amdgcn_global_load_lds((const unsigned*)((const char*)(gbase) + (voff)[_i]), (LAS unsigned*)(lds + (bufoff) + ldsw + _i * 8192), 16, 0, 0); } while (0)
; #define PG8_LDA(dst, b, h) do { _Pragma("unroll") for (int m = 0; m < 4; ++m) _Pragma("unroll") for (int k = 0; k < 2; ++k) dst[m][k] = *(const LAS bf16x8*)(lds + PG8_SA(b, h) + aoff + m * 2048 + k * 1024); } while (0)
; #define PG8_LDB(dst, b, h) do { _Pragma("unroll") for (int n = 0; n < 2; ++n) _Pragma("unroll") for (int k = 0; k < 2; ++k) dst[n][k] = *(const LAS bf16x8*)(lds + PG8_SB(b, h) + boff + n * 2048 + k * 1024); } while (0)
; #define PG8_MMA(ai, bj, At, Bt) do { __builtin_amdgcn_s_setprio(1); _Pragma("unroll") for (int m = 0; m < 4; ++m) _Pragma("unroll") for (int n = 0; n < 2; ++n) _Pragma("unroll") for (int k = 0; k < 2; ++k) \
;         acc[ai][bj][m][n] = __builtin_amdgcn_mfma_f32_16x16x32_bf16(Bt[n][k], At[m][k], acc[ai][bj][m][n], 0, 0, 0); __builtin_amdgcn_s_setprio(0); } while (0)
; #define PG8_WAIT_V(n) asm volatile("s_waitcnt vmcnt(" #n ")" ::: "memory")
; #define PG8_WAIT_L(n) asm volatile("s_waitcnt lgkmcnt(" #n ")" ::: "memory")
; #define PG8_BAR __builtin_amdgcn_s_barrier()
; #define PG8_SCHED __builtin_amdgcn_sched_barrier(0)
; template <class Epi, bool ALIGN_EPI = true, bool SP2 = true>
; __device__ __forceinline__ void gemm_phase(LAS unsigned char* lds, const Gemm g, const StaticOrder& S, const Epi& E, unsigned long long& tacc, const int tmode) {
;     ...
;             PG8_WAIT_V(8); PG8_WAIT_L(0); PG8_BAR; PG8_MMA(1, 0, At, B0); PG8_MMA(1, 1, At, B1); PG8_BAR; PG8_SCHED;
;             PG8_LDB(B0, 1, 0); PG8_LDB(B1, 1, 1); PG8_SCHED; PG8_LDA(At, 1, 0); PG8_STAGE(PG8_SA(0, 1), a2 + hstepA, voffA);
;             PG8_WAIT_V(8); PG8_WAIT_L(0); PG8_BAR; PG8_MMA(0, 0, At, B0); PG8_MMA(0, 1, At, B1); PG8_BAR; PG8_SCHED;
	s_setprio 1
	s_waitcnt lgkmcnt(0)
	v_mfma_f32_16x16x32_bf16 v[62:65], v[140:143], v[172:175], v[62:65]
	v_mfma_f32_16x16x32_bf16 v[58:61], v[148:151], v[172:175], v[58:61]
	v_mfma_f32_16x16x32_bf16 v[46:49], v[140:143], v[180:183], v[46:49]
	v_mfma_f32_16x16x32_bf16 v[42:45], v[148:151], v[180:183], v[42:45]
	v_mfma_f32_16x16x32_bf16 v[30:33], v[140:143], v[188:191], v[30:33]
	v_mfma_f32_16x16x32_bf16 v[26:29], v[148:151], v[188:191], v[26:29]
	v_mfma_f32_16x16x32_bf16 v[14:17], v[140:143], v[206:209], v[14:17]
	v_mfma_f32_16x16x32_bf16 v[10:13], v[148:151], v[206:209], v[10:13]
	v_mfma_f32_16x16x32_bf16 v[62:65], v[144:147], v[176:179], v[62:65]
	v_mfma_f32_16x16x32_bf16 v[58:61], v[152:155], v[176:179], v[58:61]
	v_mfma_f32_16x16x32_bf16 v[46:49], v[144:147], v[184:187], v[46:49]
	v_mfma_f32_16x16x32_bf16 v[42:45], v[152:155], v[184:187], v[42:45]
	v_mfma_f32_16x16x32_bf16 v[30:33], v[144:147], v[194:197], v[30:33]
	v_mfma_f32_16x16x32_bf16 v[26:29], v[152:155], v[194:197], v[26:29]
	v_mfma_f32_16x16x32_bf16 v[14:17], v[144:147], v[210:213], v[14:17]
	v_mfma_f32_16x16x32_bf16 v[10:13], v[152:155], v[210:213], v[10:13]
	s_setprio 0
	s_setprio 1
	v_mfma_f32_16x16x32_bf16 v[54:57], v[156:159], v[172:175], v[54:57]
	v_mfma_f32_16x16x32_bf16 v[50:53], v[164:167], v[172:175], v[50:53]
	v_mfma_f32_16x16x32_bf16 v[38:41], v[156:159], v[180:183], v[38:41]
	v_mfma_f32_16x16x32_bf16 v[34:37], v[164:167], v[180:183], v[34:37]
	v_mfma_f32_16x16x32_bf16 v[22:25], v[156:159], v[188:191], v[22:25]
	v_mfma_f32_16x16x32_bf16 v[18:21], v[164:167], v[188:191], v[18:21]
	v_mfma_f32_16x16x32_bf16 v[6:9], v[156:159], v[206:209], v[6:9]
	v_mfma_f32_16x16x32_bf16 v[2:5], v[164:167], v[206:209], v[2:5]
	v_mfma_f32_16x16x32_bf16 v[54:57], v[160:163], v[176:179], v[54:57]
	v_mfma_f32_16x16x32_bf16 v[50:53], v[168:171], v[176:179], v[50:53]
	v_mfma_f32_16x16x32_bf16 v[38:41], v[160:163], v[184:187], v[38:41]
	v_mfma_f32_16x16x32_bf16 v[34:37], v[168:171], v[184:187], v[34:37]
	v_mfma_f32_16x16x32_bf16 v[22:25], v[160:163], v[194:197], v[22:25]
	v_mfma_f32_16x16x32_bf16 v[18:21], v[168:171], v[194:197], v[18:21]
	v_mfma_f32_16x16x32_bf16 v[6:9], v[160:163], v[210:213], v[6:9]
	s_nop 1
	s_barrier
	v_mfma_f32_16x16x32_bf16 v[2:5], v[168:171], v[210:213], v[2:5]
	s_setprio 0
	s_add_i32 s33, 0, 0x18000
	v_add_u32_e32 v130, s33, v137
	s_add_i32 s64, 0, 0x1c000
	ds_read_b128 v[140:143], v130
	ds_read_b128 v[144:147], v130 offset:1024
	ds_read_b128 v[148:151], v130 offset:2048
	ds_read_b128 v[152:155], v130 offset:3072
	v_add_u32_e32 v130, s64, v137
	ds_read_b128 v[156:159], v130
	ds_read_b128 v[160:163], v130 offset:1024
	ds_read_b128 v[164:167], v130 offset:2048
	ds_read_b128 v[168:171], v130 offset:3072
	s_add_u32 s0, s34, 0x80000
	s_addc_u32 s1, s35, 0
	s_mov_b32 m0, s46
	v_lshl_add_u64 v[214:215], s[0:1], 0, v[132:133]
	ds_read_b128 v[172:175], v138 offset:32768
	ds_read_b128 v[176:179], v138 offset:33792
	ds_read_b128 v[180:183], v138 offset:34816
	ds_read_b128 v[184:187], v138 offset:35840
	ds_read_b128 v[188:191], v138 offset:36864
	ds_read_b128 v[194:197], v138 offset:37888
	ds_read_b128 v[206:209], v138 offset:38912
	ds_read_b128 v[210:213], v138 offset:39936
	global_load_lds_dwordx4 v[214:215], off
	v_lshl_add_u64 v[214:215], s[0:1], 0, v[134:135]
	s_mov_b32 m0, s47
	s_nop 0
	global_load_lds_dwordx4 v[214:215], off
	s_waitcnt vmcnt(8)
	s_waitcnt lgkmcnt(0)
	s_barrier
	s_setprio 1
	s_waitcnt lgkmcnt(0)
	v_mfma_f32_16x16x32_bf16 v[126:129], v[140:143], v[172:175], v[126:129]
	v_mfma_f32_16x16x32_bf16 v[122:125], v[148:151], v[172:175], v[122:125]
	v_mfma_f32_16x16x32_bf16 v[110:113], v[140:143], v[180:183], v[110:113]
	v_mfma_f32_16x16x32_bf16 v[106:109], v[148:151], v[180:183], v[106:109]
	v_mfma_f32_16x16x32_bf16 v[94:97], v[140:143], v[188:191], v[94:97]
	v_mfma_f32_16x16x32_bf16 v[90:93], v[148:151], v[188:191], v[90:93]
	v_mfma_f32_16x16x32_bf16 v[78:81], v[140:143], v[206:209], v[78:81]
	v_mfma_f32_16x16x32_bf16 v[74:77], v[148:151], v[206:209], v[74:77]
	v_mfma_f32_16x16x32_bf16 v[126:129], v[144:147], v[176:179], v[126:129]
	v_mfma_f32_16x16x32_bf16 v[122:125], v[152:155], v[176:179], v[122:125]
	v_mfma_f32_16x16x32_bf16 v[110:113], v[144:147], v[184:187], v[110:113]
	v_mfma_f32_16x16x32_bf16 v[106:109], v[152:155], v[184:187], v[106:109]
	v_mfma_f32_16x16x32_bf16 v[94:97], v[144:147], v[194:197], v[94:97]
	v_mfma_f32_16x16x32_bf16 v[90:93], v[152:155], v[194:197], v[90:93]
	v_mfma_f32_16x16x32_bf16 v[78:81], v[144:147], v[210:213], v[78:81]
	v_mfma_f32_16x16x32_bf16 v[74:77], v[152:155], v[210:213], v[74:77]
	s_setprio 0
	s_setprio 1
	v_mfma_f32_16x16x32_bf16 v[118:121], v[156:159], v[172:175], v[118:121]
	v_mfma_f32_16x16x32_bf16 v[114:117], v[164:167], v[172:175], v[114:117]
	v_mfma_f32_16x16x32_bf16 v[102:105], v[156:159], v[180:183], v[102:105]
	v_mfma_f32_16x16x32_bf16 v[98:101], v[164:167], v[180:183], v[98:101]
	v_mfma_f32_16x16x32_bf16 v[86:89], v[156:159], v[188:191], v[86:89]
	v_mfma_f32_16x16x32_bf16 v[82:85], v[164:167], v[188:191], v[82:85]
	v_mfma_f32_16x16x32_bf16 v[70:73], v[156:159], v[206:209], v[70:73]
	v_mfma_f32_16x16x32_bf16 v[66:69], v[164:167], v[206:209], v[66:69]
	v_mfma_f32_16x16x32_bf16 v[118:121], v[160:163], v[176:179], v[118:121]
	v_mfma_f32_16x16x32_bf16 v[114:117], v[168:171], v[176:179], v[114:117]
	v_mfma_f32_16x16x32_bf16 v[102:105], v[160:163], v[184:187], v[102:105]
	v_mfma_f32_16x16x32_bf16 v[98:101], v[168:171], v[184:187], v[98:101]
	v_mfma_f32_16x16x32_bf16 v[86:89], v[160:163], v[194:197], v[86:89]
	v_mfma_f32_16x16x32_bf16 v[82:85], v[168:171], v[194:197], v[82:85]
	v_mfma_f32_16x16x32_bf16 v[70:73], v[160:163], v[210:213], v[70:73]
	s_nop 1
	s_barrier
; #define PG8_STAGE(bufoff, gbase, voff) do { _Pragma("unroll") for (int _i = 0; _i < 2; ++_i) \
;         __builtin_amdgcn_global_load_lds((const unsigned*)((const char*)(gbase) + (voff)[_i]), (LAS unsigned*)(lds + (bufoff) + ldsw + _i * 8192), 16, 0, 0); } while (0)
; #define PG8_LDA(dst, b, h) do { _Pragma("unroll") for (int m = 0; m < 4; ++m) _Pragma("unroll") for (int k = 0; k < 2; ++k) dst[m][k] = *(const LAS bf16x8*)(lds + PG8_SA(b, h) + aoff + m * 2048 + k * 1024); } while (0)
; #define PG8_MMA(ai, bj, At, Bt) do { __builtin_amdgcn_s_setprio(1); _Pragma("unroll") for (int m = 0; m < 4; ++m) _Pragma("unroll") for (int n = 0; n < 2; ++n) _Pragma("unroll") for (int k = 0; k < 2; ++k) \
;         acc[ai][bj][m][n] = __builtin_amdgcn_mfma_f32_16x16x32_bf16(Bt[n][k], At[m][k], acc[ai][bj][m][n], 0, 0, 0); __builtin_amdgcn_s_setprio(0); } while (0)
; #define PG8_WAIT_V(n) asm volatile("s_waitcnt vmcnt(" #n ")" ::: "memory")
; #define PG8_WAIT_L(n) asm volatile("s_waitcnt lgkmcnt(" #n ")" ::: "memory")
; #define PG8_BAR __builtin_amdgcn_s_barrier()
; #define PG8_SCHED __builtin_amdgcn_sched_barrier(0)
; template <class Epi, bool ALIGN_EPI = true, bool SP2 = true>
; __device__ __forceinline__ void gemm_phase(LAS unsigned char* lds, const Gemm g, const StaticOrder& S, const Epi& E, unsigned long long& tacc, const int tmode) {
;     ...
;             PG8_WAIT_V(8); PG8_WAIT_L(0); PG8_BAR; PG8_MMA(0, 0, At, B0); PG8_MMA(0, 1, At, B1); PG8_BAR; PG8_SCHED;
;             PG8_LDA(At, 1, 1); PG8_STAGE(PG8_SB(1, 0), b3, voffB); PG8_STAGE(PG8_SB(1, 1), b3 + hstepB, voffB); PG8_STAGE(PG8_SA(1, 0), a3, voffA);
;             PG8_WAIT_V(8); PG8_WAIT_L(0); PG8_BAR; PG8_MMA(1, 0, At, B0); PG8_MMA(1, 1, At, B1); PG8_BAR; PG8_SCHED;
	v_mfma_f32_16x16x32_bf16 v[66:69], v[168:171], v[210:213], v[66:69]
	s_setprio 0
	s_add_u32 s0, s40, 0x4000
	s_addc_u32 s1, s41, 0
	s_add_i32 s33, s33, s43
	v_lshl_add_u64 v[214:215], s[0:1], 0, v[132:133]
	s_mov_b32 m0, s33
	ds_read_b128 v[172:175], v138 offset:49152
	ds_read_b128 v[176:179], v138 offset:50176
	ds_read_b128 v[180:183], v138 offset:51200
	ds_read_b128 v[184:187], v138 offset:52224
	ds_read_b128 v[188:191], v138 offset:53248
	ds_read_b128 v[194:197], v138 offset:54272
	ds_read_b128 v[206:209], v138 offset:55296
	ds_read_b128 v[210:213], v138 offset:56320
	global_load_lds_dwordx4 v[214:215], off
	s_add_i32 m0, s33, 0x2000
	v_lshl_add_u64 v[214:215], s[0:1], 0, v[134:135]
	s_add_u32 s0, s40, 0x84000
	s_addc_u32 s1, s41, 0
	s_add_i32 s33, s64, s43
	global_load_lds_dwordx4 v[214:215], off
	v_lshl_add_u64 v[214:215], s[0:1], 0, v[132:133]
	s_mov_b32 m0, s33
	s_nop 0
	global_load_lds_dwordx4 v[214:215], off
	v_lshl_add_u64 v[214:215], s[0:1], 0, v[134:135]
	s_add_i32 m0, s33, 0x2000
	s_nop 0
	global_load_lds_dwordx4 v[214:215], off
	v_lshl_add_u64 v[214:215], s[30:31], 0, v[132:133]
	s_mov_b32 m0, s50
	s_nop 0
	global_load_lds_dwordx4 v[214:215], off
	v_lshl_add_u64 v[214:215], s[30:31], 0, v[134:135]
	s_mov_b32 m0, s51
	s_nop 0
	global_load_lds_dwordx4 v[214:215], off
	s_waitcnt vmcnt(8)
	s_waitcnt lgkmcnt(0)
	s_barrier
	s_setprio 1
	s_waitcnt lgkmcnt(0)
	v_mfma_f32_16x16x32_bf16 v[62:65], v[140:143], v[172:175], v[62:65]
	v_mfma_f32_16x16x32_bf16 v[58:61], v[148:151], v[172:175], v[58:61]
	v_mfma_f32_16x16x32_bf16 v[46:49], v[140:143], v[180:183], v[46:49]
	v_mfma_f32_16x16x32_bf16 v[42:45], v[148:151], v[180:183], v[42:45]
	v_mfma_f32_16x16x32_bf16 v[30:33], v[140:143], v[188:191], v[30:33]
	v_mfma_f32_16x16x32_bf16 v[26:29], v[148:151], v[188:191], v[26:29]
	v_mfma_f32_16x16x32_bf16 v[14:17], v[140:143], v[206:209], v[14:17]
	v_mfma_f32_16x16x32_bf16 v[10:13], v[148:151], v[206:209], v[10:13]
	v_mfma_f32_16x16x32_bf16 v[62:65], v[144:147], v[176:179], v[62:65]
	v_mfma_f32_16x16x32_bf16 v[58:61], v[152:155], v[176:179], v[58:61]
	v_mfma_f32_16x16x32_bf16 v[46:49], v[144:147], v[184:187], v[46:49]
	v_mfma_f32_16x16x32_bf16 v[42:45], v[152:155], v[184:187], v[42:45]
	v_mfma_f32_16x16x32_bf16 v[30:33], v[144:147], v[194:197], v[30:33]
	v_mfma_f32_16x16x32_bf16 v[26:29], v[152:155], v[194:197], v[26:29]
	v_mfma_f32_16x16x32_bf16 v[14:17], v[144:147], v[210:213], v[14:17]
	v_mfma_f32_16x16x32_bf16 v[10:13], v[152:155], v[210:213], v[10:13]
	s_setprio 0
	s_setprio 1
	v_mfma_f32_16x16x32_bf16 v[54:57], v[156:159], v[172:175], v[54:57]
	v_mfma_f32_16x16x32_bf16 v[50:53], v[164:167], v[172:175], v[50:53]
	v_mfma_f32_16x16x32_bf16 v[38:41], v[156:159], v[180:183], v[38:41]
	v_mfma_f32_16x16x32_bf16 v[34:37], v[164:167], v[180:183], v[34:37]
	v_mfma_f32_16x16x32_bf16 v[22:25], v[156:159], v[188:191], v[22:25]
	v_mfma_f32_16x16x32_bf16 v[18:21], v[164:167], v[188:191], v[18:21]
	v_mfma_f32_16x16x32_bf16 v[6:9], v[156:159], v[206:209], v[6:9]
	v_mfma_f32_16x16x32_bf16 v[2:5], v[164:167], v[206:209], v[2:5]
	v_mfma_f32_16x16x32_bf16 v[54:57], v[160:163], v[176:179], v[54:57]
	v_mfma_f32_16x16x32_bf16 v[50:53], v[168:171], v[176:179], v[50:53]
	v_mfma_f32_16x16x32_bf16 v[38:41], v[160:163], v[184:187], v[38:41]
	v_mfma_f32_16x16x32_bf16 v[34:37], v[168:171], v[184:187], v[34:37]
	v_mfma_f32_16x16x32_bf16 v[22:25], v[160:163], v[194:197], v[22:25]
	v_mfma_f32_16x16x32_bf16 v[18:21], v[168:171], v[194:197], v[18:21]
	v_mfma_f32_16x16x32_bf16 v[6:9], v[160:163], v[210:213], v[6:9]
	s_nop 1
	s_barrier
	v_mfma_f32_16x16x32_bf16 v[2:5], v[168:171], v[210:213], v[2:5]
	s_setprio 0
	s_add_i32 s61, s61, 2
	s_add_u32 s22, s22, 0x8000
	s_addc_u32 s23, s23, 0
	s_add_u32 s57, s57, 0x8000
	s_addc_u32 s60, s60, 0
	s_cmp_lt_u32 s61, 30
	s_cbranch_scc1 .LBB0_1154
	s_andn2_b64 vcc, exec, s[18:19]
	s_cbranch_vccnz .LBB0_1157
	s_barrier

; #define PG8_STAGE(bufoff, gbase, voff) do { _Pragma("unroll") for (int _i = 0; _i < 2; ++_i) \
;         __builtin_amdgcn_global_load_lds((const unsigned*)((const char*)(gbase) + (voff)[_i]), (LAS unsigned*)(lds + (bufoff) + ldsw + _i * 8192), 16, 0, 0); } while (0)
; #define PG8_LDA(dst, b, h) do { _Pragma("unroll") for (int m = 0; m < 4; ++m) _Pragma("unroll") for (int k = 0; k < 2; ++k) dst[m][k] = *(const LAS bf16x8*)(lds + PG8_SA(b, h) + aoff + m * 2048 + k * 1024); } while (0)
; #define PG8_LDB(dst, b, h) do { _Pragma("unroll") for (int n = 0; n < 2; ++n) _Pragma("unroll") for (int k = 0; k < 2; ++k) dst[n][k] = *(const LAS bf16x8*)(lds + PG8_SB(b, h) + boff + n * 2048 + k * 1024); } while (0)
; #define PG8_MMA(ai, bj, At, Bt) do { __builtin_amdgcn_s_setprio(1); _Pragma("unroll") for (int m = 0; m < 4; ++m) _Pragma("unroll") for (int n = 0; n < 2; ++n) _Pragma("unroll") for (int k = 0; k < 2; ++k) \
;         acc[ai][bj][m][n] = __builtin_amdgcn_mfma_f32_16x16x32_bf16(Bt[n][k], At[m][k], acc[ai][bj][m][n], 0, 0, 0); __builtin_amdgcn_s_setprio(0); } while (0)
; #define PG8_WAIT_V(n) asm volatile("s_waitcnt vmcnt(" #n ")" ::: "memory")
; #define PG8_WAIT_L(n) asm volatile("s_waitcnt lgkmcnt(" #n ")" ::: "memory")
; template <class Epi, bool ALIGN_EPI = true, bool SP2 = true>
; __device__ __forceinline__ void gemm_phase(LAS unsigned char* lds, const Gemm g, const StaticOrder& S, const Epi& E, unsigned long long& tacc, const int tmode) {
;     ...
;         for (int t = 0; t < nt; t += 2) {
;             const bool last = (t == nt - 2);
;             const char* a1 = cA + (size_t)(t + 1) * kstepA;
;             const char* a2 = last ? nA : cA + (size_t)(t + 2) * kstepA; const char* b2 = last ? nB : cB + (size_t)(t + 2) * kstepB;
;             const char* a3 = a2 + kstepA; const char* b3 = b2 + kstepB;
;             if constexpr (SP2) {
;             PG8_LDB(B0, 0, 0); PG8_LDB(B1, 0, 1); PG8_SCHED; PG8_LDA(At, 0, 0); PG8_STAGE(PG8_SA(1, 1), a1 + hstepA, voffA);
;             PG8_WAIT_V(8); PG8_WAIT_L(0); PG8_BAR; PG8_MMA(0, 0, At, B0); PG8_MMA(0, 1, At, B1); PG8_BAR; PG8_SCHED;
;             PG8_LDA(At, 0, 1); PG8_STAGE(PG8_SB(0, 0), b2, voffB); PG8_STAGE(PG8_SB(0, 1), b2 + hstepB, voffB); PG8_STAGE(PG8_SA(0, 0), a2, voffA);
;             PG8_WAIT_V(8); PG8_WAIT_L(0); PG8_BAR; PG8_MMA(1, 0, At, B0); PG8_MMA(1, 1, At, B1); PG8_BAR; PG8_SCHED;
.LBB0_1224:
	s_add_u32 s0, s22, s46
	s_addc_u32 s1, s23, s47
	s_add_u32 s0, s0, 0x8000
	s_addc_u32 s1, s1, 0
	s_add_u32 s33, s36, s46
	s_addc_u32 s48, s37, s47
	s_cmp_eq_u32 s46, 0x1f8000
	s_cselect_b32 s34, vcc_lo, s0
	s_cselect_b32 s35, s27, s1
	s_cselect_b32 s50, vcc_hi, s33
	s_cselect_b32 s51, s25, s48
	s_add_u32 s48, s34, 0x4000
	s_addc_u32 s49, s35, 0
	s_add_i32 s0, 0, 0x10000
	v_add_u32_e32 v141, s0, v139
	s_add_i32 s33, 0, 0x14000
	ds_read_b128 v[142:145], v141
	ds_read_b128 v[146:149], v141 offset:1024
	ds_read_b128 v[150:153], v141 offset:2048
	ds_read_b128 v[154:157], v141 offset:3072
	v_add_u32_e32 v141, s33, v139
	ds_read_b128 v[158:161], v141
	ds_read_b128 v[162:165], v141 offset:1024
	ds_read_b128 v[166:169], v141 offset:2048
	ds_read_b128 v[170:173], v141 offset:3072
	v_lshl_add_u64 v[190:191], v[134:135], 0, s[46:47]
	s_add_i32 m0, s65, 0xc000
	ds_read_b128 v[174:177], v140
	ds_read_b128 v[178:181], v140 offset:1024
	ds_read_b128 v[182:185], v140 offset:2048
	ds_read_b128 v[186:189], v140 offset:3072
	ds_read_b128 v[194:197], v140 offset:4096
	ds_read_b128 v[206:209], v140 offset:5120
	ds_read_b128 v[210:213], v140 offset:6144
	ds_read_b128 v[214:217], v140 offset:7168
	global_load_lds_dwordx4 v[190:191], off
	v_lshl_add_u64 v[190:191], v[136:137], 0, s[46:47]
	s_add_i32 m0, s65, 0xe000
	s_nop 0
	global_load_lds_dwordx4 v[190:191], off
	s_waitcnt vmcnt(8)
	s_waitcnt lgkmcnt(0)
	s_barrier
	s_setprio 1
	s_waitcnt lgkmcnt(0)
	v_mfma_f32_16x16x32_bf16 v[126:129], v[142:145], v[174:177], v[126:129]
	v_mfma_f32_16x16x32_bf16 v[122:125], v[150:153], v[174:177], v[122:125]
	v_mfma_f32_16x16x32_bf16 v[118:121], v[142:145], v[182:185], v[118:121]
	v_mfma_f32_16x16x32_bf16 v[110:113], v[150:153], v[182:185], v[110:113]
	v_mfma_f32_16x16x32_bf16 v[102:105], v[142:145], v[194:197], v[102:105]
	v_mfma_f32_16x16x32_bf16 v[94:97], v[150:153], v[194:197], v[94:97]
	v_mfma_f32_16x16x32_bf16 v[86:89], v[142:145], v[210:213], v[86:89]
	v_mfma_f32_16x16x32_bf16 v[78:81], v[150:153], v[210:213], v[78:81]
	v_mfma_f32_16x16x32_bf16 v[126:129], v[146:149], v[178:181], v[126:129]
	v_mfma_f32_16x16x32_bf16 v[122:125], v[154:157], v[178:181], v[122:125]
	v_mfma_f32_16x16x32_bf16 v[118:121], v[146:149], v[186:189], v[118:121]
	v_mfma_f32_16x16x32_bf16 v[110:113], v[154:157], v[186:189], v[110:113]
	v_mfma_f32_16x16x32_bf16 v[102:105], v[146:149], v[206:209], v[102:105]
	v_mfma_f32_16x16x32_bf16 v[94:97], v[154:157], v[206:209], v[94:97]
	v_mfma_f32_16x16x32_bf16 v[86:89], v[146:149], v[214:217], v[86:89]
	v_mfma_f32_16x16x32_bf16 v[78:81], v[154:157], v[214:217], v[78:81]
	s_setprio 0
	s_setprio 1
	v_mfma_f32_16x16x32_bf16 v[114:117], v[158:161], v[174:177], v[114:117]
	v_mfma_f32_16x16x32_bf16 v[106:109], v[166:169], v[174:177], v[106:109]
	v_mfma_f32_16x16x32_bf16 v[98:101], v[158:161], v[182:185], v[98:101]
	v_mfma_f32_16x16x32_bf16 v[90:93], v[166:169], v[182:185], v[90:93]
	v_mfma_f32_16x16x32_bf16 v[82:85], v[158:161], v[194:197], v[82:85]
	v_mfma_f32_16x16x32_bf16 v[74:77], v[166:169], v[194:197], v[74:77]
	v_mfma_f32_16x16x32_bf16 v[70:73], v[158:161], v[210:213], v[70:73]
	v_mfma_f32_16x16x32_bf16 v[66:69], v[166:169], v[210:213], v[66:69]
	v_mfma_f32_16x16x32_bf16 v[114:117], v[162:165], v[178:181], v[114:117]
	v_mfma_f32_16x16x32_bf16 v[106:109], v[170:173], v[178:181], v[106:109]
	v_mfma_f32_16x16x32_bf16 v[98:101], v[162:165], v[186:189], v[98:101]
	v_mfma_f32_16x16x32_bf16 v[90:93], v[170:173], v[186:189], v[90:93]
	v_mfma_f32_16x16x32_bf16 v[82:85], v[162:165], v[206:209], v[82:85]
	v_mfma_f32_16x16x32_bf16 v[74:77], v[170:173], v[206:209], v[74:77]
	v_mfma_f32_16x16x32_bf16 v[70:73], v[162:165], v[214:217], v[70:73]
	s_nop 1
	s_barrier
	v_mfma_f32_16x16x32_bf16 v[66:69], v[170:173], v[214:217], v[66:69]
	s_setprio 0
	s_add_i32 s0, s0, s61
	v_lshl_add_u64 v[190:191], s[50:51], 0, v[130:131]
	s_mov_b32 m0, s0
	ds_read_b128 v[174:177], v140 offset:16384
	ds_read_b128 v[178:181], v140 offset:17408
	ds_read_b128 v[182:185], v140 offset:18432
	ds_read_b128 v[186:189], v140 offset:19456
	ds_read_b128 v[194:197], v140 offset:20480
	ds_read_b128 v[206:209], v140 offset:21504
	ds_read_b128 v[210:213], v140 offset:22528
	ds_read_b128 v[214:217], v140 offset:23552
	global_load_lds_dwordx4 v[190:191], off
	s_add_i32 m0, s0, 0x2000
	s_add_u32 s0, s50, 0x200000
	v_lshl_add_u64 v[190:191], s[50:51], 0, v[132:133]
	s_addc_u32 s1, s51, 0
	s_add_i32 s33, s33, s61
	global_load_lds_dwordx4 v[190:191], off
	v_lshl_add_u64 v[190:191], s[0:1], 0, v[130:131]
	s_mov_b32 m0, s33
	s_nop 0
	global_load_lds_dwordx4 v[190:191], off
	v_lshl_add_u64 v[190:191], s[0:1], 0, v[132:133]
	s_add_i32 m0, s33, 0x2000
	s_nop 0
	global_load_lds_dwordx4 v[190:191], off
	v_lshl_add_u64 v[190:191], s[34:35], 0, v[130:131]
	s_mov_b32 m0, s65
	s_nop 0
	global_load_lds_dwordx4 v[190:191], off
	v_lshl_add_u64 v[190:191], s[34:35], 0, v[132:133]
	s_mov_b32 m0, s71
	s_nop 0
	global_load_lds_dwordx4 v[190:191], off
	s_waitcnt vmcnt(8)
	s_waitcnt lgkmcnt(0)
	s_barrier
; #define PG8_STAGE(bufoff, gbase, voff) do { _Pragma("unroll") for (int _i = 0; _i < 2; ++_i) \
;         __builtin_amdgcn_global_load_lds((const unsigned*)((const char*)(gbase) + (voff)[_i]), (LAS unsigned*)(lds + (bufoff) + ldsw + _i * 8192), 16, 0, 0); } while (0)
; #define PG8_LDA(dst, b, h) do { _Pragma("unroll") for (int m = 0; m < 4; ++m) _Pragma("unroll") for (int k = 0; k < 2; ++k) dst[m][k] = *(const LAS bf16x8*)(lds + PG8_SA(b, h) + aoff + m * 2048 + k * 1024); } while (0)
; #define PG8_LDB(dst, b, h) do { _Pragma("unroll") for (int n = 0; n < 2; ++n) _Pragma("unroll") for (int k = 0; k < 2; ++k) dst[n][k] = *(const LAS bf16x8*)(lds + PG8_SB(b, h) + boff + n * 2048 + k * 1024); } while (0)
; #define PG8_MMA(ai, bj, At, Bt) do { __builtin_amdgcn_s_setprio(1); _Pragma("unroll") for (int m = 0; m < 4; ++m) _Pragma("unroll") for (int n = 0; n < 2; ++n) _Pragma("unroll") for (int k = 0; k < 2; ++k) \
;         acc[ai][bj][m][n] = __builtin_amdgcn_mfma_f32_16x16x32_bf16(Bt[n][k], At[m][k], acc[ai][bj][m][n], 0, 0, 0); __builtin_amdgcn_s_setprio(0); } while (0)
; #define PG8_WAIT_V(n) asm volatile("s_waitcnt vmcnt(" #n ")" ::: "memory")
; #define PG8_WAIT_L(n) asm volatile("s_waitcnt lgkmcnt(" #n ")" ::: "memory")
; #define PG8_BAR __builtin_amdgcn_s_barrier()
; #define PG8_SCHED __builtin_amdgcn_sched_barrier(0)
; template <class Epi, bool ALIGN_EPI = true, bool SP2 = true>
; __device__ __forceinline__ void gemm_phase(LAS unsigned char* lds, const Gemm g, const StaticOrder& S, const Epi& E, unsigned long long& tacc, const int tmode) {
;     ...
;             PG8_WAIT_V(8); PG8_WAIT_L(0); PG8_BAR; PG8_MMA(1, 0, At, B0); PG8_MMA(1, 1, At, B1); PG8_BAR; PG8_SCHED;
;             PG8_LDB(B0, 1, 0); PG8_LDB(B1, 1, 1); PG8_SCHED; PG8_LDA(At, 1, 0); PG8_STAGE(PG8_SA(0, 1), a2 + hstepA, voffA);
;             PG8_WAIT_V(8); PG8_WAIT_L(0); PG8_BAR; PG8_MMA(0, 0, At, B0); PG8_MMA(0, 1, At, B1); PG8_BAR; PG8_SCHED;
	s_setprio 1
	s_waitcnt lgkmcnt(0)
	v_mfma_f32_16x16x32_bf16 v[62:65], v[142:145], v[174:177], v[62:65]
	v_mfma_f32_16x16x32_bf16 v[58:61], v[150:153], v[174:177], v[58:61]
	v_mfma_f32_16x16x32_bf16 v[54:57], v[142:145], v[182:185], v[54:57]
	v_mfma_f32_16x16x32_bf16 v[46:49], v[150:153], v[182:185], v[46:49]
	v_mfma_f32_16x16x32_bf16 v[38:41], v[142:145], v[194:197], v[38:41]
	v_mfma_f32_16x16x32_bf16 v[30:33], v[150:153], v[194:197], v[30:33]
	v_mfma_f32_16x16x32_bf16 v[22:25], v[142:145], v[210:213], v[22:25]
	v_mfma_f32_16x16x32_bf16 v[14:17], v[150:153], v[210:213], v[14:17]
	v_mfma_f32_16x16x32_bf16 v[62:65], v[146:149], v[178:181], v[62:65]
	v_mfma_f32_16x16x32_bf16 v[58:61], v[154:157], v[178:181], v[58:61]
	v_mfma_f32_16x16x32_bf16 v[54:57], v[146:149], v[186:189], v[54:57]
	v_mfma_f32_16x16x32_bf16 v[46:49], v[154:157], v[186:189], v[46:49]
	v_mfma_f32_16x16x32_bf16 v[38:41], v[146:149], v[206:209], v[38:41]
	v_mfma_f32_16x16x32_bf16 v[30:33], v[154:157], v[206:209], v[30:33]
	v_mfma_f32_16x16x32_bf16 v[22:25], v[146:149], v[214:217], v[22:25]
	v_mfma_f32_16x16x32_bf16 v[14:17], v[154:157], v[214:217], v[14:17]
	s_setprio 0
	s_setprio 1
	v_mfma_f32_16x16x32_bf16 v[50:53], v[158:161], v[174:177], v[50:53]
	v_mfma_f32_16x16x32_bf16 v[42:45], v[166:169], v[174:177], v[42:45]
	v_mfma_f32_16x16x32_bf16 v[34:37], v[158:161], v[182:185], v[34:37]
	v_mfma_f32_16x16x32_bf16 v[26:29], v[166:169], v[182:185], v[26:29]
	v_mfma_f32_16x16x32_bf16 v[18:21], v[158:161], v[194:197], v[18:21]
	v_mfma_f32_16x16x32_bf16 v[10:13], v[166:169], v[194:197], v[10:13]
	v_mfma_f32_16x16x32_bf16 v[6:9], v[158:161], v[210:213], v[6:9]
	v_mfma_f32_16x16x32_bf16 v[2:5], v[166:169], v[210:213], v[2:5]
	v_mfma_f32_16x16x32_bf16 v[50:53], v[162:165], v[178:181], v[50:53]
	v_mfma_f32_16x16x32_bf16 v[42:45], v[170:173], v[178:181], v[42:45]
	v_mfma_f32_16x16x32_bf16 v[34:37], v[162:165], v[186:189], v[34:37]
	v_mfma_f32_16x16x32_bf16 v[26:29], v[170:173], v[186:189], v[26:29]
	v_mfma_f32_16x16x32_bf16 v[18:21], v[162:165], v[206:209], v[18:21]
	v_mfma_f32_16x16x32_bf16 v[10:13], v[170:173], v[206:209], v[10:13]
	v_mfma_f32_16x16x32_bf16 v[6:9], v[162:165], v[214:217], v[6:9]
	s_nop 1
	s_barrier
	v_mfma_f32_16x16x32_bf16 v[2:5], v[170:173], v[214:217], v[2:5]
	s_setprio 0
	s_add_i32 s33, 0, 0x18000
	v_add_u32_e32 v141, s33, v139
	s_add_i32 s64, 0, 0x1c000
	ds_read_b128 v[142:145], v141
	ds_read_b128 v[146:149], v141 offset:1024
	ds_read_b128 v[150:153], v141 offset:2048
	ds_read_b128 v[154:157], v141 offset:3072
	v_add_u32_e32 v141, s64, v139
	ds_read_b128 v[158:161], v141
	ds_read_b128 v[162:165], v141 offset:1024
	ds_read_b128 v[166:169], v141 offset:2048
	ds_read_b128 v[170:173], v141 offset:3072
	s_add_u32 s0, s34, 0x200000
	s_addc_u32 s1, s35, 0
	s_mov_b32 m0, s72
	v_lshl_add_u64 v[190:191], s[0:1], 0, v[130:131]
	ds_read_b128 v[174:177], v140 offset:32768
	ds_read_b128 v[178:181], v140 offset:33792
	ds_read_b128 v[182:185], v140 offset:34816
	ds_read_b128 v[186:189], v140 offset:35840
	ds_read_b128 v[194:197], v140 offset:36864
	ds_read_b128 v[206:209], v140 offset:37888
	ds_read_b128 v[210:213], v140 offset:38912
	ds_read_b128 v[214:217], v140 offset:39936
	global_load_lds_dwordx4 v[190:191], off
	v_lshl_add_u64 v[190:191], s[0:1], 0, v[132:133]
	s_mov_b32 m0, s73
	s_nop 0
	global_load_lds_dwordx4 v[190:191], off
	s_waitcnt vmcnt(8)
	s_waitcnt lgkmcnt(0)
	s_barrier
	s_setprio 1
	s_waitcnt lgkmcnt(0)
	v_mfma_f32_16x16x32_bf16 v[126:129], v[142:145], v[174:177], v[126:129]
	v_mfma_f32_16x16x32_bf16 v[122:125], v[150:153], v[174:177], v[122:125]
	v_mfma_f32_16x16x32_bf16 v[118:121], v[142:145], v[182:185], v[118:121]
	v_mfma_f32_16x16x32_bf16 v[110:113], v[150:153], v[182:185], v[110:113]
	v_mfma_f32_16x16x32_bf16 v[102:105], v[142:145], v[194:197], v[102:105]
	v_mfma_f32_16x16x32_bf16 v[94:97], v[150:153], v[194:197], v[94:97]
	v_mfma_f32_16x16x32_bf16 v[86:89], v[142:145], v[210:213], v[86:89]
	v_mfma_f32_16x16x32_bf16 v[78:81], v[150:153], v[210:213], v[78:81]
	v_mfma_f32_16x16x32_bf16 v[126:129], v[146:149], v[178:181], v[126:129]
	v_mfma_f32_16x16x32_bf16 v[122:125], v[154:157], v[178:181], v[122:125]
	v_mfma_f32_16x16x32_bf16 v[118:121], v[146:149], v[186:189], v[118:121]
	v_mfma_f32_16x16x32_bf16 v[110:113], v[154:157], v[186:189], v[110:113]
	v_mfma_f32_16x16x32_bf16 v[102:105], v[146:149], v[206:209], v[102:105]
	v_mfma_f32_16x16x32_bf16 v[94:97], v[154:157], v[206:209], v[94:97]
	v_mfma_f32_16x16x32_bf16 v[86:89], v[146:149], v[214:217], v[86:89]
	v_mfma_f32_16x16x32_bf16 v[78:81], v[154:157], v[214:217], v[78:81]
	s_setprio 0
	s_setprio 1
	v_mfma_f32_16x16x32_bf16 v[114:117], v[158:161], v[174:177], v[114:117]
	v_mfma_f32_16x16x32_bf16 v[106:109], v[166:169], v[174:177], v[106:109]
	v_mfma_f32_16x16x32_bf16 v[98:101], v[158:161], v[182:185], v[98:101]
	v_mfma_f32_16x16x32_bf16 v[90:93], v[166:169], v[182:185], v[90:93]
	v_mfma_f32_16x16x32_bf16 v[82:85], v[158:161], v[194:197], v[82:85]
	v_mfma_f32_16x16x32_bf16 v[74:77], v[166:169], v[194:197], v[74:77]
	v_mfma_f32_16x16x32_bf16 v[70:73], v[158:161], v[210:213], v[70:73]
	v_mfma_f32_16x16x32_bf16 v[66:69], v[166:169], v[210:213], v[66:69]
	v_mfma_f32_16x16x32_bf16 v[114:117], v[162:165], v[178:181], v[114:117]
	v_mfma_f32_16x16x32_bf16 v[106:109], v[170:173], v[178:181], v[106:109]
	v_mfma_f32_16x16x32_bf16 v[98:101], v[162:165], v[186:189], v[98:101]
	v_mfma_f32_16x16x32_bf16 v[90:93], v[170:173], v[186:189], v[90:93]
	v_mfma_f32_16x16x32_bf16 v[82:85], v[162:165], v[206:209], v[82:85]
	v_mfma_f32_16x16x32_bf16 v[74:77], v[170:173], v[206:209], v[74:77]
	v_mfma_f32_16x16x32_bf16 v[70:73], v[162:165], v[214:217], v[70:73]
	s_nop 1
	s_barrier
; #define PG8_STAGE(bufoff, gbase, voff) do { _Pragma("unroll") for (int _i = 0; _i < 2; ++_i) \
;         __builtin_amdgcn_global_load_lds((const unsigned*)((const char*)(gbase) + (voff)[_i]), (LAS unsigned*)(lds + (bufoff) + ldsw + _i * 8192), 16, 0, 0); } while (0)
; #define PG8_LDA(dst, b, h) do { _Pragma("unroll") for (int m = 0; m < 4; ++m) _Pragma("unroll") for (int k = 0; k < 2; ++k) dst[m][k] = *(const LAS bf16x8*)(lds + PG8_SA(b, h) + aoff + m * 2048 + k * 1024); } while (0)
; #define PG8_MMA(ai, bj, At, Bt) do { __builtin_amdgcn_s_setprio(1); _Pragma("unroll") for (int m = 0; m < 4; ++m) _Pragma("unroll") for (int n = 0; n < 2; ++n) _Pragma("unroll") for (int k = 0; k < 2; ++k) \
;         acc[ai][bj][m][n] = __builtin_amdgcn_mfma_f32_16x16x32_bf16(Bt[n][k], At[m][k], acc[ai][bj][m][n], 0, 0, 0); __builtin_amdgcn_s_setprio(0); } while (0)
; #define PG8_WAIT_V(n) asm volatile("s_waitcnt vmcnt(" #n ")" ::: "memory")
; #define PG8_WAIT_L(n) asm volatile("s_waitcnt lgkmcnt(" #n ")" ::: "memory")
; #define PG8_BAR __builtin_amdgcn_s_barrier()
; #define PG8_SCHED __builtin_amdgcn_sched_barrier(0)
; template <class Epi, bool ALIGN_EPI = true, bool SP2 = true>
; __device__ __forceinline__ void gemm_phase(LAS unsigned char* lds, const Gemm g, const StaticOrder& S, const Epi& E, unsigned long long& tacc, const int tmode) {
;     ...
;             PG8_WAIT_V(8); PG8_WAIT_L(0); PG8_BAR; PG8_MMA(0, 0, At, B0); PG8_MMA(0, 1, At, B1); PG8_BAR; PG8_SCHED;
;             PG8_LDA(At, 1, 1); PG8_STAGE(PG8_SB(1, 0), b3, voffB); PG8_STAGE(PG8_SB(1, 1), b3 + hstepB, voffB); PG8_STAGE(PG8_SA(1, 0), a3, voffA);
;             PG8_WAIT_V(8); PG8_WAIT_L(0); PG8_BAR; PG8_MMA(1, 0, At, B0); PG8_MMA(1, 1, At, B1); PG8_BAR; PG8_SCHED;
	v_mfma_f32_16x16x32_bf16 v[66:69], v[170:173], v[214:217], v[66:69]
	s_setprio 0
	s_add_u32 s0, s50, 0x4000
	s_addc_u32 s1, s51, 0
	s_add_i32 s33, s33, s61
	v_lshl_add_u64 v[190:191], s[0:1], 0, v[130:131]
	s_mov_b32 m0, s33
	ds_read_b128 v[174:177], v140 offset:49152
	ds_read_b128 v[178:181], v140 offset:50176
	ds_read_b128 v[182:185], v140 offset:51200
	ds_read_b128 v[186:189], v140 offset:52224
	ds_read_b128 v[194:197], v140 offset:53248
	ds_read_b128 v[206:209], v140 offset:54272
	ds_read_b128 v[210:213], v140 offset:55296
	ds_read_b128 v[214:217], v140 offset:56320
	global_load_lds_dwordx4 v[190:191], off
	s_add_i32 m0, s33, 0x2000
	v_lshl_add_u64 v[190:191], s[0:1], 0, v[132:133]
	s_add_u32 s0, s50, 0x204000
	s_addc_u32 s1, s51, 0
	s_add_i32 s33, s64, s61
	global_load_lds_dwordx4 v[190:191], off
	v_lshl_add_u64 v[190:191], s[0:1], 0, v[130:131]
	s_mov_b32 m0, s33
	s_nop 0
	global_load_lds_dwordx4 v[190:191], off
	v_lshl_add_u64 v[190:191], s[0:1], 0, v[132:133]
	s_add_i32 m0, s33, 0x2000
	s_nop 0
	global_load_lds_dwordx4 v[190:191], off
	v_lshl_add_u64 v[190:191], s[48:49], 0, v[130:131]
	s_mov_b32 m0, s84
	s_nop 0
	global_load_lds_dwordx4 v[190:191], off
	v_lshl_add_u64 v[190:191], s[48:49], 0, v[132:133]
	s_mov_b32 m0, s85
	s_nop 0
	global_load_lds_dwordx4 v[190:191], off
	s_waitcnt vmcnt(8)
	s_waitcnt lgkmcnt(0)
	s_barrier
	s_setprio 1
	s_waitcnt lgkmcnt(0)
	v_mfma_f32_16x16x32_bf16 v[62:65], v[142:145], v[174:177], v[62:65]
	v_mfma_f32_16x16x32_bf16 v[58:61], v[150:153], v[174:177], v[58:61]
	v_mfma_f32_16x16x32_bf16 v[54:57], v[142:145], v[182:185], v[54:57]
	v_mfma_f32_16x16x32_bf16 v[46:49], v[150:153], v[182:185], v[46:49]
	v_mfma_f32_16x16x32_bf16 v[38:41], v[142:145], v[194:197], v[38:41]
	v_mfma_f32_16x16x32_bf16 v[30:33], v[150:153], v[194:197], v[30:33]
	v_mfma_f32_16x16x32_bf16 v[22:25], v[142:145], v[210:213], v[22:25]
	v_mfma_f32_16x16x32_bf16 v[14:17], v[150:153], v[210:213], v[14:17]
	v_mfma_f32_16x16x32_bf16 v[62:65], v[146:149], v[178:181], v[62:65]
	v_mfma_f32_16x16x32_bf16 v[58:61], v[154:157], v[178:181], v[58:61]
	v_mfma_f32_16x16x32_bf16 v[54:57], v[146:149], v[186:189], v[54:57]
	v_mfma_f32_16x16x32_bf16 v[46:49], v[154:157], v[186:189], v[46:49]
	v_mfma_f32_16x16x32_bf16 v[38:41], v[146:149], v[206:209], v[38:41]
	v_mfma_f32_16x16x32_bf16 v[30:33], v[154:157], v[206:209], v[30:33]
	v_mfma_f32_16x16x32_bf16 v[22:25], v[146:149], v[214:217], v[22:25]
	v_mfma_f32_16x16x32_bf16 v[14:17], v[154:157], v[214:217], v[14:17]
	s_setprio 0
	s_setprio 1
	v_mfma_f32_16x16x32_bf16 v[50:53], v[158:161], v[174:177], v[50:53]
	v_mfma_f32_16x16x32_bf16 v[42:45], v[166:169], v[174:177], v[42:45]
	v_mfma_f32_16x16x32_bf16 v[34:37], v[158:161], v[182:185], v[34:37]
	v_mfma_f32_16x16x32_bf16 v[26:29], v[166:169], v[182:185], v[26:29]
	v_mfma_f32_16x16x32_bf16 v[18:21], v[158:161], v[194:197], v[18:21]
	v_mfma_f32_16x16x32_bf16 v[10:13], v[166:169], v[194:197], v[10:13]
	v_mfma_f32_16x16x32_bf16 v[6:9], v[158:161], v[210:213], v[6:9]
	v_mfma_f32_16x16x32_bf16 v[2:5], v[166:169], v[210:213], v[2:5]
	v_mfma_f32_16x16x32_bf16 v[50:53], v[162:165], v[178:181], v[50:53]
	v_mfma_f32_16x16x32_bf16 v[42:45], v[170:173], v[178:181], v[42:45]
	v_mfma_f32_16x16x32_bf16 v[34:37], v[162:165], v[186:189], v[34:37]
	v_mfma_f32_16x16x32_bf16 v[26:29], v[170:173], v[186:189], v[26:29]
	v_mfma_f32_16x16x32_bf16 v[18:21], v[162:165], v[206:209], v[18:21]
	v_mfma_f32_16x16x32_bf16 v[10:13], v[170:173], v[206:209], v[10:13]
	v_mfma_f32_16x16x32_bf16 v[6:9], v[162:165], v[214:217], v[6:9]
	s_nop 1
	s_barrier
	v_mfma_f32_16x16x32_bf16 v[2:5], v[170:173], v[214:217], v[2:5]
	s_setprio 0
	s_add_i32 s81, s81, 2
	s_add_u32 s46, s46, 0x8000
	s_addc_u32 s47, s47, 0
	s_cmpk_lt_u32 s81, 0x7e
	s_cbranch_scc1 .LBB0_1224
	s_andn2_b64 vcc, exec, s[20:21]
	s_cbranch_vccnz .LBB0_1227
	s_barrier

; #define PG8_STAGE(bufoff, gbase, voff) do { _Pragma("unroll") for (int _i = 0; _i < 2; ++_i) \
;         __builtin_amdgcn_global_load_lds((const unsigned*)((const char*)(gbase) + (voff)[_i]), (LAS unsigned*)(lds + (bufoff) + ldsw + _i * 8192), 16, 0, 0); } while (0)
; #define PG8_LDA(dst, b, h) do { _Pragma("unroll") for (int m = 0; m < 4; ++m) _Pragma("unroll") for (int k = 0; k < 2; ++k) dst[m][k] = *(const LAS bf16x8*)(lds + PG8_SA(b, h) + aoff + m * 2048 + k * 1024); } while (0)
; #define PG8_LDB(dst, b, h) do { _Pragma("unroll") for (int n = 0; n < 2; ++n) _Pragma("unroll") for (int k = 0; k < 2; ++k) dst[n][k] = *(const LAS bf16x8*)(lds + PG8_SB(b, h) + boff + n * 2048 + k * 1024); } while (0)
; #define PG8_MMA(ai, bj, At, Bt) do { __builtin_amdgcn_s_setprio(1); _Pragma("unroll") for (int m = 0; m < 4; ++m) _Pragma("unroll") for (int n = 0; n < 2; ++n) _Pragma("unroll") for (int k = 0; k < 2; ++k) \
;         acc[ai][bj][m][n] = __builtin_amdgcn_mfma_f32_16x16x32_bf16(Bt[n][k], At[m][k], acc[ai][bj][m][n], 0, 0, 0); __builtin_amdgcn_s_setprio(0); } while (0)
; #define PG8_WAIT_V(n) asm volatile("s_waitcnt vmcnt(" #n ")" ::: "memory")
; #define PG8_WAIT_L(n) asm volatile("s_waitcnt lgkmcnt(" #n ")" ::: "memory")
; template <class Epi, bool ALIGN_EPI = true, bool SP2 = true>
; __device__ __forceinline__ void gemm_phase(LAS unsigned char* lds, const Gemm g, const StaticOrder& S, const Epi& E, unsigned long long& tacc, const int tmode) {
;     ...
;         for (int t = 0; t < nt; t += 2) {
;             const bool last = (t == nt - 2);
;             const char* a1 = cA + (size_t)(t + 1) * kstepA;
;             const char* a2 = last ? nA : cA + (size_t)(t + 2) * kstepA; const char* b2 = last ? nB : cB + (size_t)(t + 2) * kstepB;
;             const char* a3 = a2 + kstepA; const char* b3 = b2 + kstepB;
;             if constexpr (SP2) {
;             PG8_LDB(B0, 0, 0); PG8_LDB(B1, 0, 1); PG8_SCHED; PG8_LDA(At, 0, 0); PG8_STAGE(PG8_SA(1, 1), a1 + hstepA, voffA);
;             PG8_WAIT_V(8); PG8_WAIT_L(0); PG8_BAR; PG8_MMA(0, 0, At, B0); PG8_MMA(0, 1, At, B1); PG8_BAR; PG8_SCHED;
;             PG8_LDA(At, 0, 1); PG8_STAGE(PG8_SB(0, 0), b2, voffB); PG8_STAGE(PG8_SB(0, 1), b2 + hstepB, voffB); PG8_STAGE(PG8_SA(0, 0), a2, voffA);
;             PG8_WAIT_V(8); PG8_WAIT_L(0); PG8_BAR; PG8_MMA(1, 0, At, B0); PG8_MMA(1, 1, At, B1); PG8_BAR; PG8_SCHED;
.LBB0_1285:
	s_add_u32 s0, s22, s40
	s_addc_u32 s1, s23, s41
	s_add_u32 s0, s0, 0x8000
	s_addc_u32 s1, s1, 0
	s_add_u32 s33, s86, s40
	s_addc_u32 s46, s87, s41
	s_cmp_eq_u32 s40, 0x1f8000
	s_cselect_b32 s34, vcc_lo, s0
	s_cselect_b32 s35, s27, s1
	s_cselect_b32 s48, vcc_hi, s33
	s_cselect_b32 s49, s25, s46
	s_add_u32 s46, s34, 0x4000
	s_addc_u32 s47, s35, 0
	s_add_i32 s0, 0, 0x10000
	v_add_u32_e32 v141, s0, v135
	s_add_i32 s33, 0, 0x14000
	ds_read_b128 v[142:145], v141
	ds_read_b128 v[146:149], v141 offset:1024
	ds_read_b128 v[150:153], v141 offset:2048
	ds_read_b128 v[154:157], v141 offset:3072
	v_add_u32_e32 v141, s33, v135
	ds_read_b128 v[158:161], v141
	ds_read_b128 v[162:165], v141 offset:1024
	ds_read_b128 v[166:169], v141 offset:2048
	ds_read_b128 v[170:173], v141 offset:3072
	v_lshl_add_u64 v[190:191], v[128:129], 0, s[40:41]
	s_add_i32 m0, s60, 0xc000
	ds_read_b128 v[174:177], v140
	ds_read_b128 v[178:181], v140 offset:1024
	ds_read_b128 v[182:185], v140 offset:2048
	ds_read_b128 v[186:189], v140 offset:3072
	ds_read_b128 v[194:197], v140 offset:4096
	ds_read_b128 v[206:209], v140 offset:5120
	ds_read_b128 v[210:213], v140 offset:6144
	ds_read_b128 v[214:217], v140 offset:7168
	global_load_lds_dwordx4 v[190:191], off
	v_lshl_add_u64 v[190:191], v[132:133], 0, s[40:41]
	s_add_i32 m0, s60, 0xe000
	s_nop 0
	global_load_lds_dwordx4 v[190:191], off
	s_waitcnt vmcnt(8)
	s_waitcnt lgkmcnt(0)
	s_barrier
	s_setprio 1
	s_waitcnt lgkmcnt(0)
	v_mfma_f32_16x16x32_bf16 v[118:121], v[142:145], v[174:177], v[118:121]
	v_mfma_f32_16x16x32_bf16 v[114:117], v[150:153], v[174:177], v[114:117]
	v_mfma_f32_16x16x32_bf16 v[136:139], v[142:145], v[182:185], v[136:139]
	v_mfma_f32_16x16x32_bf16 v[86:89], v[150:153], v[182:185], v[86:89]
	v_mfma_f32_16x16x32_bf16 v[110:113], v[142:145], v[194:197], v[110:113]
	v_mfma_f32_16x16x32_bf16 v[102:105], v[150:153], v[194:197], v[102:105]
	v_mfma_f32_16x16x32_bf16 v[122:125], v[142:145], v[210:213], v[122:125]
	v_mfma_f32_16x16x32_bf16 v[78:81], v[150:153], v[210:213], v[78:81]
	v_mfma_f32_16x16x32_bf16 v[118:121], v[146:149], v[178:181], v[118:121]
	v_mfma_f32_16x16x32_bf16 v[114:117], v[154:157], v[178:181], v[114:117]
	v_mfma_f32_16x16x32_bf16 v[136:139], v[146:149], v[186:189], v[136:139]
	v_mfma_f32_16x16x32_bf16 v[86:89], v[154:157], v[186:189], v[86:89]
	v_mfma_f32_16x16x32_bf16 v[110:113], v[146:149], v[206:209], v[110:113]
	v_mfma_f32_16x16x32_bf16 v[102:105], v[154:157], v[206:209], v[102:105]
	v_mfma_f32_16x16x32_bf16 v[122:125], v[146:149], v[214:217], v[122:125]
	v_mfma_f32_16x16x32_bf16 v[78:81], v[154:157], v[214:217], v[78:81]
	s_setprio 0
	s_setprio 1
	v_mfma_f32_16x16x32_bf16 v[98:101], v[158:161], v[174:177], v[98:101]
	v_mfma_f32_16x16x32_bf16 v[82:85], v[166:169], v[174:177], v[82:85]
	v_mfma_f32_16x16x32_bf16 v[90:93], v[158:161], v[182:185], v[90:93]
	v_mfma_f32_16x16x32_bf16 v[94:97], v[166:169], v[182:185], v[94:97]
	v_mfma_f32_16x16x32_bf16 v[106:109], v[158:161], v[194:197], v[106:109]
	v_mfma_f32_16x16x32_bf16 v[74:77], v[166:169], v[194:197], v[74:77]
	v_mfma_f32_16x16x32_bf16 v[70:73], v[158:161], v[210:213], v[70:73]
	v_mfma_f32_16x16x32_bf16 v[66:69], v[166:169], v[210:213], v[66:69]
	v_mfma_f32_16x16x32_bf16 v[98:101], v[162:165], v[178:181], v[98:101]
	v_mfma_f32_16x16x32_bf16 v[82:85], v[170:173], v[178:181], v[82:85]
	v_mfma_f32_16x16x32_bf16 v[90:93], v[162:165], v[186:189], v[90:93]
	v_mfma_f32_16x16x32_bf16 v[94:97], v[170:173], v[186:189], v[94:97]
	v_mfma_f32_16x16x32_bf16 v[106:109], v[162:165], v[206:209], v[106:109]
	v_mfma_f32_16x16x32_bf16 v[74:77], v[170:173], v[206:209], v[74:77]
	v_mfma_f32_16x16x32_bf16 v[70:73], v[162:165], v[214:217], v[70:73]
	s_nop 1
	s_barrier
	v_mfma_f32_16x16x32_bf16 v[66:69], v[170:173], v[214:217], v[66:69]
	s_setprio 0
	s_add_i32 s0, s0, s57
	v_lshl_add_u64 v[190:191], s[48:49], 0, v[130:131]
	s_mov_b32 m0, s0
	ds_read_b128 v[174:177], v140 offset:16384
	ds_read_b128 v[178:181], v140 offset:17408
	ds_read_b128 v[182:185], v140 offset:18432
	ds_read_b128 v[186:189], v140 offset:19456
	ds_read_b128 v[194:197], v140 offset:20480
	ds_read_b128 v[206:209], v140 offset:21504
	ds_read_b128 v[210:213], v140 offset:22528
	ds_read_b128 v[214:217], v140 offset:23552
	global_load_lds_dwordx4 v[190:191], off
	s_add_i32 m0, s0, 0x2000
	s_add_u32 s0, s48, 0x200000
	v_lshl_add_u64 v[190:191], s[48:49], 0, v[126:127]
	s_addc_u32 s1, s49, 0
	s_add_i32 s33, s33, s57
	global_load_lds_dwordx4 v[190:191], off
	v_lshl_add_u64 v[190:191], s[0:1], 0, v[130:131]
	s_mov_b32 m0, s33
	s_nop 0
	global_load_lds_dwordx4 v[190:191], off
	v_lshl_add_u64 v[190:191], s[0:1], 0, v[126:127]
	s_add_i32 m0, s33, 0x2000
	s_nop 0
	global_load_lds_dwordx4 v[190:191], off
	v_lshl_add_u64 v[190:191], s[34:35], 0, v[130:131]
	s_mov_b32 m0, s60
	s_nop 0
	global_load_lds_dwordx4 v[190:191], off
	v_lshl_add_u64 v[190:191], s[34:35], 0, v[126:127]
	s_mov_b32 m0, s61
	s_nop 0
	global_load_lds_dwordx4 v[190:191], off
	s_waitcnt vmcnt(8)
	s_waitcnt lgkmcnt(0)
	s_barrier
; #define PG8_STAGE(bufoff, gbase, voff) do { _Pragma("unroll") for (int _i = 0; _i < 2; ++_i) \
;         __builtin_amdgcn_global_load_lds((const unsigned*)((const char*)(gbase) + (voff)[_i]), (LAS unsigned*)(lds + (bufoff) + ldsw + _i * 8192), 16, 0, 0); } while (0)
; #define PG8_LDA(dst, b, h) do { _Pragma("unroll") for (int m = 0; m < 4; ++m) _Pragma("unroll") for (int k = 0; k < 2; ++k) dst[m][k] = *(const LAS bf16x8*)(lds + PG8_SA(b, h) + aoff + m * 2048 + k * 1024); } while (0)
; #define PG8_LDB(dst, b, h) do { _Pragma("unroll") for (int n = 0; n < 2; ++n) _Pragma("unroll") for (int k = 0; k < 2; ++k) dst[n][k] = *(const LAS bf16x8*)(lds + PG8_SB(b, h) + boff + n * 2048 + k * 1024); } while (0)
; #define PG8_MMA(ai, bj, At, Bt) do { __builtin_amdgcn_s_setprio(1); _Pragma("unroll") for (int m = 0; m < 4; ++m) _Pragma("unroll") for (int n = 0; n < 2; ++n) _Pragma("unroll") for (int k = 0; k < 2; ++k) \
;         acc[ai][bj][m][n] = __builtin_amdgcn_mfma_f32_16x16x32_bf16(Bt[n][k], At[m][k], acc[ai][bj][m][n], 0, 0, 0); __builtin_amdgcn_s_setprio(0); } while (0)
; #define PG8_WAIT_V(n) asm volatile("s_waitcnt vmcnt(" #n ")" ::: "memory")
; #define PG8_WAIT_L(n) asm volatile("s_waitcnt lgkmcnt(" #n ")" ::: "memory")
; #define PG8_BAR __builtin_amdgcn_s_barrier()
; #define PG8_SCHED __builtin_amdgcn_sched_barrier(0)
; template <class Epi, bool ALIGN_EPI = true, bool SP2 = true>
; __device__ __forceinline__ void gemm_phase(LAS unsigned char* lds, const Gemm g, const StaticOrder& S, const Epi& E, unsigned long long& tacc, const int tmode) {
;     ...
;             PG8_WAIT_V(8); PG8_WAIT_L(0); PG8_BAR; PG8_MMA(1, 0, At, B0); PG8_MMA(1, 1, At, B1); PG8_BAR; PG8_SCHED;
;             PG8_LDB(B0, 1, 0); PG8_LDB(B1, 1, 1); PG8_SCHED; PG8_LDA(At, 1, 0); PG8_STAGE(PG8_SA(0, 1), a2 + hstepA, voffA);
;             PG8_WAIT_V(8); PG8_WAIT_L(0); PG8_BAR; PG8_MMA(0, 0, At, B0); PG8_MMA(0, 1, At, B1); PG8_BAR; PG8_SCHED;
	s_setprio 1
	s_waitcnt lgkmcnt(0)
	v_mfma_f32_16x16x32_bf16 v[62:65], v[142:145], v[174:177], v[62:65]
	v_mfma_f32_16x16x32_bf16 v[58:61], v[150:153], v[174:177], v[58:61]
	v_mfma_f32_16x16x32_bf16 v[54:57], v[142:145], v[182:185], v[54:57]
	v_mfma_f32_16x16x32_bf16 v[46:49], v[150:153], v[182:185], v[46:49]
	v_mfma_f32_16x16x32_bf16 v[38:41], v[142:145], v[194:197], v[38:41]
	v_mfma_f32_16x16x32_bf16 v[30:33], v[150:153], v[194:197], v[30:33]
	v_mfma_f32_16x16x32_bf16 v[22:25], v[142:145], v[210:213], v[22:25]
	v_mfma_f32_16x16x32_bf16 v[14:17], v[150:153], v[210:213], v[14:17]
	v_mfma_f32_16x16x32_bf16 v[62:65], v[146:149], v[178:181], v[62:65]
	v_mfma_f32_16x16x32_bf16 v[58:61], v[154:157], v[178:181], v[58:61]
	v_mfma_f32_16x16x32_bf16 v[54:57], v[146:149], v[186:189], v[54:57]
	v_mfma_f32_16x16x32_bf16 v[46:49], v[154:157], v[186:189], v[46:49]
	v_mfma_f32_16x16x32_bf16 v[38:41], v[146:149], v[206:209], v[38:41]
	v_mfma_f32_16x16x32_bf16 v[30:33], v[154:157], v[206:209], v[30:33]
	v_mfma_f32_16x16x32_bf16 v[22:25], v[146:149], v[214:217], v[22:25]
	v_mfma_f32_16x16x32_bf16 v[14:17], v[154:157], v[214:217], v[14:17]
	s_setprio 0
	s_setprio 1
	v_mfma_f32_16x16x32_bf16 v[50:53], v[158:161], v[174:177], v[50:53]
	v_mfma_f32_16x16x32_bf16 v[42:45], v[166:169], v[174:177], v[42:45]
	v_mfma_f32_16x16x32_bf16 v[34:37], v[158:161], v[182:185], v[34:37]
	v_mfma_f32_16x16x32_bf16 v[26:29], v[166:169], v[182:185], v[26:29]
	v_mfma_f32_16x16x32_bf16 v[18:21], v[158:161], v[194:197], v[18:21]
	v_mfma_f32_16x16x32_bf16 v[10:13], v[166:169], v[194:197], v[10:13]
	v_mfma_f32_16x16x32_bf16 v[6:9], v[158:161], v[210:213], v[6:9]
	v_mfma_f32_16x16x32_bf16 v[2:5], v[166:169], v[210:213], v[2:5]
	v_mfma_f32_16x16x32_bf16 v[50:53], v[162:165], v[178:181], v[50:53]
	v_mfma_f32_16x16x32_bf16 v[42:45], v[170:173], v[178:181], v[42:45]
	v_mfma_f32_16x16x32_bf16 v[34:37], v[162:165], v[186:189], v[34:37]
	v_mfma_f32_16x16x32_bf16 v[26:29], v[170:173], v[186:189], v[26:29]
	v_mfma_f32_16x16x32_bf16 v[18:21], v[162:165], v[206:209], v[18:21]
	v_mfma_f32_16x16x32_bf16 v[10:13], v[170:173], v[206:209], v[10:13]
	v_mfma_f32_16x16x32_bf16 v[6:9], v[162:165], v[214:217], v[6:9]
	s_nop 1
	s_barrier
	v_mfma_f32_16x16x32_bf16 v[2:5], v[170:173], v[214:217], v[2:5]
	s_setprio 0
	s_add_i32 s33, 0, 0x18000
	v_add_u32_e32 v141, s33, v135
	s_add_i32 s64, 0, 0x1c000
	ds_read_b128 v[142:145], v141
	ds_read_b128 v[146:149], v141 offset:1024
	ds_read_b128 v[150:153], v141 offset:2048
	ds_read_b128 v[154:157], v141 offset:3072
	v_add_u32_e32 v141, s64, v135
	ds_read_b128 v[158:161], v141
	ds_read_b128 v[162:165], v141 offset:1024
	ds_read_b128 v[166:169], v141 offset:2048
	ds_read_b128 v[170:173], v141 offset:3072
	s_add_u32 s0, s34, 0x200000
	s_addc_u32 s1, s35, 0
	s_mov_b32 m0, s65
	v_lshl_add_u64 v[190:191], s[0:1], 0, v[130:131]
	ds_read_b128 v[174:177], v140 offset:32768
	ds_read_b128 v[178:181], v140 offset:33792
	ds_read_b128 v[182:185], v140 offset:34816
	ds_read_b128 v[186:189], v140 offset:35840
	ds_read_b128 v[194:197], v140 offset:36864
	ds_read_b128 v[206:209], v140 offset:37888
	ds_read_b128 v[210:213], v140 offset:38912
	ds_read_b128 v[214:217], v140 offset:39936
	global_load_lds_dwordx4 v[190:191], off
	v_lshl_add_u64 v[190:191], s[0:1], 0, v[126:127]
	s_mov_b32 m0, s71
	s_nop 0
	global_load_lds_dwordx4 v[190:191], off
	s_waitcnt vmcnt(8)
	s_waitcnt lgkmcnt(0)
	s_barrier
	s_setprio 1
	s_waitcnt lgkmcnt(0)
	v_mfma_f32_16x16x32_bf16 v[118:121], v[142:145], v[174:177], v[118:121]
	v_mfma_f32_16x16x32_bf16 v[114:117], v[150:153], v[174:177], v[114:117]
	v_mfma_f32_16x16x32_bf16 v[136:139], v[142:145], v[182:185], v[136:139]
	v_mfma_f32_16x16x32_bf16 v[86:89], v[150:153], v[182:185], v[86:89]
	v_mfma_f32_16x16x32_bf16 v[110:113], v[142:145], v[194:197], v[110:113]
	v_mfma_f32_16x16x32_bf16 v[102:105], v[150:153], v[194:197], v[102:105]
	v_mfma_f32_16x16x32_bf16 v[122:125], v[142:145], v[210:213], v[122:125]
	v_mfma_f32_16x16x32_bf16 v[78:81], v[150:153], v[210:213], v[78:81]
	v_mfma_f32_16x16x32_bf16 v[118:121], v[146:149], v[178:181], v[118:121]
	v_mfma_f32_16x16x32_bf16 v[114:117], v[154:157], v[178:181], v[114:117]
	v_mfma_f32_16x16x32_bf16 v[136:139], v[146:149], v[186:189], v[136:139]
	v_mfma_f32_16x16x32_bf16 v[86:89], v[154:157], v[186:189], v[86:89]
	v_mfma_f32_16x16x32_bf16 v[110:113], v[146:149], v[206:209], v[110:113]
	v_mfma_f32_16x16x32_bf16 v[102:105], v[154:157], v[206:209], v[102:105]
	v_mfma_f32_16x16x32_bf16 v[122:125], v[146:149], v[214:217], v[122:125]
	v_mfma_f32_16x16x32_bf16 v[78:81], v[154:157], v[214:217], v[78:81]
	s_setprio 0
	s_setprio 1
	v_mfma_f32_16x16x32_bf16 v[98:101], v[158:161], v[174:177], v[98:101]
	v_mfma_f32_16x16x32_bf16 v[82:85], v[166:169], v[174:177], v[82:85]
	v_mfma_f32_16x16x32_bf16 v[90:93], v[158:161], v[182:185], v[90:93]
	v_mfma_f32_16x16x32_bf16 v[94:97], v[166:169], v[182:185], v[94:97]
	v_mfma_f32_16x16x32_bf16 v[106:109], v[158:161], v[194:197], v[106:109]
	v_mfma_f32_16x16x32_bf16 v[74:77], v[166:169], v[194:197], v[74:77]
	v_mfma_f32_16x16x32_bf16 v[70:73], v[158:161], v[210:213], v[70:73]
	v_mfma_f32_16x16x32_bf16 v[66:69], v[166:169], v[210:213], v[66:69]
	v_mfma_f32_16x16x32_bf16 v[98:101], v[162:165], v[178:181], v[98:101]
	v_mfma_f32_16x16x32_bf16 v[82:85], v[170:173], v[178:181], v[82:85]
	v_mfma_f32_16x16x32_bf16 v[90:93], v[162:165], v[186:189], v[90:93]
	v_mfma_f32_16x16x32_bf16 v[94:97], v[170:173], v[186:189], v[94:97]
	v_mfma_f32_16x16x32_bf16 v[106:109], v[162:165], v[206:209], v[106:109]
	v_mfma_f32_16x16x32_bf16 v[74:77], v[170:173], v[206:209], v[74:77]
	v_mfma_f32_16x16x32_bf16 v[70:73], v[162:165], v[214:217], v[70:73]
	s_nop 1
	s_barrier
; #define PG8_STAGE(bufoff, gbase, voff) do { _Pragma("unroll") for (int _i = 0; _i < 2; ++_i) \
;         __builtin_amdgcn_global_load_lds((const unsigned*)((const char*)(gbase) + (voff)[_i]), (LAS unsigned*)(lds + (bufoff) + ldsw + _i * 8192), 16, 0, 0); } while (0)
; #define PG8_LDA(dst, b, h) do { _Pragma("unroll") for (int m = 0; m < 4; ++m) _Pragma("unroll") for (int k = 0; k < 2; ++k) dst[m][k] = *(const LAS bf16x8*)(lds + PG8_SA(b, h) + aoff + m * 2048 + k * 1024); } while (0)
; #define PG8_MMA(ai, bj, At, Bt) do { __builtin_amdgcn_s_setprio(1); _Pragma("unroll") for (int m = 0; m < 4; ++m) _Pragma("unroll") for (int n = 0; n < 2; ++n) _Pragma("unroll") for (int k = 0; k < 2; ++k) \
;         acc[ai][bj][m][n] = __builtin_amdgcn_mfma_f32_16x16x32_bf16(Bt[n][k], At[m][k], acc[ai][bj][m][n], 0, 0, 0); __builtin_amdgcn_s_setprio(0); } while (0)
; #define PG8_WAIT_V(n) asm volatile("s_waitcnt vmcnt(" #n ")" ::: "memory")
; #define PG8_WAIT_L(n) asm volatile("s_waitcnt lgkmcnt(" #n ")" ::: "memory")
; #define PG8_BAR __builtin_amdgcn_s_barrier()
; #define PG8_SCHED __builtin_amdgcn_sched_barrier(0)
; template <class Epi, bool ALIGN_EPI = true, bool SP2 = true>
; __device__ __forceinline__ void gemm_phase(LAS unsigned char* lds, const Gemm g, const StaticOrder& S, const Epi& E, unsigned long long& tacc, const int tmode) {
;     ...
;             PG8_WAIT_V(8); PG8_WAIT_L(0); PG8_BAR; PG8_MMA(0, 0, At, B0); PG8_MMA(0, 1, At, B1); PG8_BAR; PG8_SCHED;
;             PG8_LDA(At, 1, 1); PG8_STAGE(PG8_SB(1, 0), b3, voffB); PG8_STAGE(PG8_SB(1, 1), b3 + hstepB, voffB); PG8_STAGE(PG8_SA(1, 0), a3, voffA);
;             PG8_WAIT_V(8); PG8_WAIT_L(0); PG8_BAR; PG8_MMA(1, 0, At, B0); PG8_MMA(1, 1, At, B1); PG8_BAR; PG8_SCHED;
	v_mfma_f32_16x16x32_bf16 v[66:69], v[170:173], v[214:217], v[66:69]
	s_setprio 0
	s_add_u32 s0, s48, 0x4000
	s_addc_u32 s1, s49, 0
	s_add_i32 s33, s33, s57
	v_lshl_add_u64 v[190:191], s[0:1], 0, v[130:131]
	s_mov_b32 m0, s33
	ds_read_b128 v[174:177], v140 offset:49152
	ds_read_b128 v[178:181], v140 offset:50176
	ds_read_b128 v[182:185], v140 offset:51200
	ds_read_b128 v[186:189], v140 offset:52224
	ds_read_b128 v[194:197], v140 offset:53248
	ds_read_b128 v[206:209], v140 offset:54272
	ds_read_b128 v[210:213], v140 offset:55296
	ds_read_b128 v[214:217], v140 offset:56320
	global_load_lds_dwordx4 v[190:191], off
	s_add_i32 m0, s33, 0x2000
	v_lshl_add_u64 v[190:191], s[0:1], 0, v[126:127]
	s_add_u32 s0, s48, 0x204000
	s_addc_u32 s1, s49, 0
	s_add_i32 s33, s64, s57
	global_load_lds_dwordx4 v[190:191], off
	v_lshl_add_u64 v[190:191], s[0:1], 0, v[130:131]
	s_mov_b32 m0, s33
	s_nop 0
	global_load_lds_dwordx4 v[190:191], off
	v_lshl_add_u64 v[190:191], s[0:1], 0, v[126:127]
	s_add_i32 m0, s33, 0x2000
	s_nop 0
	global_load_lds_dwordx4 v[190:191], off
	v_lshl_add_u64 v[190:191], s[46:47], 0, v[130:131]
	s_mov_b32 m0, s73
	s_nop 0
	global_load_lds_dwordx4 v[190:191], off
	v_lshl_add_u64 v[190:191], s[46:47], 0, v[126:127]
	s_mov_b32 m0, s81
	s_nop 0
	global_load_lds_dwordx4 v[190:191], off
	s_waitcnt vmcnt(8)
	s_waitcnt lgkmcnt(0)
	s_barrier
	s_setprio 1
	s_waitcnt lgkmcnt(0)
	v_mfma_f32_16x16x32_bf16 v[62:65], v[142:145], v[174:177], v[62:65]
	v_mfma_f32_16x16x32_bf16 v[58:61], v[150:153], v[174:177], v[58:61]
	v_mfma_f32_16x16x32_bf16 v[54:57], v[142:145], v[182:185], v[54:57]
	v_mfma_f32_16x16x32_bf16 v[46:49], v[150:153], v[182:185], v[46:49]
	v_mfma_f32_16x16x32_bf16 v[38:41], v[142:145], v[194:197], v[38:41]
	v_mfma_f32_16x16x32_bf16 v[30:33], v[150:153], v[194:197], v[30:33]
	v_mfma_f32_16x16x32_bf16 v[22:25], v[142:145], v[210:213], v[22:25]
	v_mfma_f32_16x16x32_bf16 v[14:17], v[150:153], v[210:213], v[14:17]
	v_mfma_f32_16x16x32_bf16 v[62:65], v[146:149], v[178:181], v[62:65]
	v_mfma_f32_16x16x32_bf16 v[58:61], v[154:157], v[178:181], v[58:61]
	v_mfma_f32_16x16x32_bf16 v[54:57], v[146:149], v[186:189], v[54:57]
	v_mfma_f32_16x16x32_bf16 v[46:49], v[154:157], v[186:189], v[46:49]
	v_mfma_f32_16x16x32_bf16 v[38:41], v[146:149], v[206:209], v[38:41]
	v_mfma_f32_16x16x32_bf16 v[30:33], v[154:157], v[206:209], v[30:33]
	v_mfma_f32_16x16x32_bf16 v[22:25], v[146:149], v[214:217], v[22:25]
	v_mfma_f32_16x16x32_bf16 v[14:17], v[154:157], v[214:217], v[14:17]
	s_setprio 0
	s_setprio 1
	v_mfma_f32_16x16x32_bf16 v[50:53], v[158:161], v[174:177], v[50:53]
	v_mfma_f32_16x16x32_bf16 v[42:45], v[166:169], v[174:177], v[42:45]
	v_mfma_f32_16x16x32_bf16 v[34:37], v[158:161], v[182:185], v[34:37]
	v_mfma_f32_16x16x32_bf16 v[26:29], v[166:169], v[182:185], v[26:29]
	v_mfma_f32_16x16x32_bf16 v[18:21], v[158:161], v[194:197], v[18:21]
	v_mfma_f32_16x16x32_bf16 v[10:13], v[166:169], v[194:197], v[10:13]
	v_mfma_f32_16x16x32_bf16 v[6:9], v[158:161], v[210:213], v[6:9]
	v_mfma_f32_16x16x32_bf16 v[2:5], v[166:169], v[210:213], v[2:5]
	v_mfma_f32_16x16x32_bf16 v[50:53], v[162:165], v[178:181], v[50:53]
	v_mfma_f32_16x16x32_bf16 v[42:45], v[170:173], v[178:181], v[42:45]
	v_mfma_f32_16x16x32_bf16 v[34:37], v[162:165], v[186:189], v[34:37]
	v_mfma_f32_16x16x32_bf16 v[26:29], v[170:173], v[186:189], v[26:29]
	v_mfma_f32_16x16x32_bf16 v[18:21], v[162:165], v[206:209], v[18:21]
	v_mfma_f32_16x16x32_bf16 v[10:13], v[170:173], v[206:209], v[10:13]
	v_mfma_f32_16x16x32_bf16 v[6:9], v[162:165], v[214:217], v[6:9]
	s_nop 1
	s_barrier
	v_mfma_f32_16x16x32_bf16 v[2:5], v[170:173], v[214:217], v[2:5]
	s_setprio 0
	s_add_i32 s72, s72, 2
	s_add_u32 s40, s40, 0x8000
	s_addc_u32 s41, s41, 0
	s_cmpk_lt_u32 s72, 0x7e
	s_cbranch_scc1 .LBB0_1285
	s_andn2_b64 vcc, exec, s[20:21]
	s_cbranch_vccnz .LBB0_1288
	s_barrier
